# v13 + all flat_load/flat_store converted to global_load/global_store (decouples LDS lgkmcnt waits from global-memory latency in epilogues)
# speedup vs baseline: 1.0031x; 1.0031x over previous
.LBB0_261:
	v_mov_b32_e32 v128, v182
	s_ashr_i32 s0, s1, 2
	v_and_b32_e32 v128, 63, v128
	s_andn2_b32 s0, s0, 63
	v_and_or_b32 v132, v128, 15, s0
	s_lshr_b32 s0, s1, 1
	v_ashrrev_i32_e32 v128, 1, v128
	v_ashrrev_i32_e32 v133, 31, v132
	s_and_b32 s0, s0, 0x60
	v_and_b32_e32 v128, -8, v128
	v_lshlrev_b64 v[132:133], 9, v[132:133]
	v_add_u32_e32 v134, s0, v128
	v_lshl_add_u64 v[132:133], s[4:5], 0, v[132:133]
	v_ashrrev_i32_e32 v135, 31, v134
	v_lshl_add_u64 v[132:133], v[134:135], 1, v[132:133]
	v_mov_b64_e32 v[134:135], v[132:133]
	v_cvt_pk_bf16_f32 v104, v104, v105
	v_cvt_pk_bf16_f32 v105, v106, v107
	v_cvt_pk_bf16_f32 v106, v108, v109
	v_cvt_pk_bf16_f32 v107, v110, v111
	global_store_dwordx4 v[134:135], v[104:107], off
	v_cvt_pk_bf16_f32 v88, v88, v89
	v_cvt_pk_bf16_f32 v89, v90, v91
	v_cvt_pk_bf16_f32 v104, v120, v121
	v_cvt_pk_bf16_f32 v105, v122, v123
	v_cvt_pk_bf16_f32 v106, v124, v125
	v_cvt_pk_bf16_f32 v107, v126, v127
	global_store_dwordx4 v[134:135], v[104:107], off offset:256
	v_cvt_pk_bf16_f32 v90, v92, v93
	v_cvt_pk_bf16_f32 v91, v94, v95
	v_lshl_add_u64 v[104:105], v[132:133], 0, s[38:39]
	global_store_dwordx4 v[104:105], v[88:91], off
	v_cvt_pk_bf16_f32 v56, v56, v57
	v_cvt_pk_bf16_f32 v57, v58, v59
	v_cvt_pk_bf16_f32 v88, v112, v113
	v_cvt_pk_bf16_f32 v89, v114, v115
	v_cvt_pk_bf16_f32 v90, v116, v117
	v_cvt_pk_bf16_f32 v91, v118, v119
	global_store_dwordx4 v[104:105], v[88:91], off offset:256
	v_cvt_pk_bf16_f32 v58, v60, v61
	v_cvt_pk_bf16_f32 v59, v62, v63
	v_lshl_add_u64 v[88:89], v[132:133], 0, s[64:65]
	global_store_dwordx4 v[88:89], v[56:59], off
	v_cvt_pk_bf16_f32 v32, v32, v33
	v_cvt_pk_bf16_f32 v33, v34, v35
	v_cvt_pk_bf16_f32 v56, v96, v97
	v_cvt_pk_bf16_f32 v57, v98, v99
	v_cvt_pk_bf16_f32 v58, v100, v101
	v_cvt_pk_bf16_f32 v59, v102, v103
	global_store_dwordx4 v[88:89], v[56:59], off offset:256
	v_cvt_pk_bf16_f32 v34, v36, v37
	v_cvt_pk_bf16_f32 v35, v38, v39
	v_lshl_add_u64 v[56:57], v[132:133], 0, s[66:67]
	global_store_dwordx4 v[56:57], v[32:35], off
	s_mov_b64 s[0:1], 0x10000
	v_lshl_add_u64 v[36:37], v[132:133], 0, s[0:1]
	v_cvt_pk_bf16_f32 v32, v64, v65
	v_cvt_pk_bf16_f32 v33, v66, v67
	v_cvt_pk_bf16_f32 v34, v68, v69
	v_cvt_pk_bf16_f32 v35, v70, v71
	global_store_dwordx4 v[56:57], v[32:35], off offset:256
	s_mov_b64 s[0:1], 0x12000
	v_cvt_pk_bf16_f32 v16, v16, v17
	v_cvt_pk_bf16_f32 v32, v72, v73
	v_cvt_pk_bf16_f32 v33, v74, v75
	v_cvt_pk_bf16_f32 v34, v76, v77
	v_cvt_pk_bf16_f32 v35, v78, v79
	global_store_dwordx4 v[36:37], v[32:35], off
	v_cvt_pk_bf16_f32 v17, v18, v19
	v_cvt_pk_bf16_f32 v18, v20, v21
	v_cvt_pk_bf16_f32 v32, v80, v81
	v_cvt_pk_bf16_f32 v33, v82, v83
	v_cvt_pk_bf16_f32 v34, v84, v85
	v_cvt_pk_bf16_f32 v35, v86, v87
	global_store_dwordx4 v[36:37], v[32:35], off offset:256
	v_lshl_add_u64 v[36:37], v[132:133], 0, s[0:1]
	s_mov_b64 s[0:1], 0x14000
	v_cvt_pk_bf16_f32 v32, v40, v41
	v_cvt_pk_bf16_f32 v33, v42, v43
	v_cvt_pk_bf16_f32 v34, v44, v45
	v_cvt_pk_bf16_f32 v35, v46, v47
	global_store_dwordx4 v[36:37], v[32:35], off
	v_cvt_pk_bf16_f32 v19, v22, v23
	v_cvt_pk_bf16_f32 v0, v0, v1
	v_cvt_pk_bf16_f32 v32, v48, v49
	v_cvt_pk_bf16_f32 v33, v50, v51
	v_cvt_pk_bf16_f32 v34, v52, v53
	v_cvt_pk_bf16_f32 v35, v54, v55
	global_store_dwordx4 v[36:37], v[32:35], off offset:256
	v_cvt_pk_bf16_f32 v1, v2, v3
	v_cvt_pk_bf16_f32 v2, v4, v5
	v_lshl_add_u64 v[32:33], v[132:133], 0, s[0:1]
	global_store_dwordx4 v[32:33], v[16:19], off
	s_mov_b64 s[0:1], 0x16000
	v_cvt_pk_bf16_f32 v3, v6, v7
	v_cvt_pk_bf16_f32 v16, v24, v25
	v_cvt_pk_bf16_f32 v17, v26, v27
	v_cvt_pk_bf16_f32 v18, v28, v29
	v_cvt_pk_bf16_f32 v19, v30, v31
	global_store_dwordx4 v[32:33], v[16:19], off offset:256
	s_add_i32 s78, s78, s96
	s_cmpk_gt_i32 s78, 0xff
	v_lshl_add_u64 v[16:17], v[132:133], 0, s[0:1]
	global_store_dwordx4 v[16:17], v[0:3], off
	s_nop 1
	v_cvt_pk_bf16_f32 v0, v8, v9
	v_cvt_pk_bf16_f32 v1, v10, v11
	v_cvt_pk_bf16_f32 v2, v12, v13
	v_cvt_pk_bf16_f32 v3, v14, v15
	global_store_dwordx4 v[16:17], v[0:3], off offset:256
	s_cbranch_scc1 .LBB0_404

.LBB0_614:
	s_or_b64 exec, exec, s[20:21]
	s_add_u32 s3, s24, s19
	s_addc_u32 s21, s25, 0
	v_mov_b32_e32 v32, v182
	s_add_u32 s20, s3, 0x8801000
	s_waitcnt lgkmcnt(0)
	s_barrier
	s_addc_u32 s21, s21, 0
	v_and_b32_e32 v34, 63, v32
	s_lshl_b64 s[0:1], s[0:1], 1
	s_add_u32 s0, s63, s0
	v_ashrrev_i32_e32 v32, 1, v34
	s_addc_u32 s1, s64, s1
	v_and_b32_e32 v32, -8, v32
	s_add_u32 s0, s0, s19
	v_add_u32_e32 v32, s80, v32
	s_addc_u32 s1, s1, 0
	s_lshl_b32 s2, s2, 2
	v_ashrrev_i32_e32 v33, 31, v32
	v_and_or_b32 v174, v34, 15, s79
	v_mov_b64_e32 v[172:173], s[20:21]
	s_add_u32 s2, s46, s2
	v_mad_i64_i32 v[34:35], s[20:21], v174, s77, v[172:173]
	v_lshlrev_b64 v[86:87], 1, v[32:33]
	s_addc_u32 s3, s47, 0
	v_lshl_add_u64 v[34:35], v[34:35], 0, v[86:87]
	global_load_dwordx4 v[186:189], v[34:35], off nt
	v_lshl_add_u64 v[32:33], v[32:33], 2, s[2:3]
	global_load_dwordx4 v[44:47], v[32:33], off
	global_load_dwordx4 v[36:39], v[32:33], off offset:16
	v_or_b32_e32 v180, 16, v174
	v_or_b32_e32 v178, 32, v174
	v_mad_i64_i32 v[40:41], s[2:3], v180, s77, v[172:173]
	v_mad_i64_i32 v[42:43], s[2:3], v178, s77, v[172:173]
	v_lshl_add_u32 v152, v174, 2, 0
	v_lshl_add_u64 v[40:41], v[40:41], 0, v[86:87]
	v_lshl_add_u64 v[42:43], v[42:43], 0, v[86:87]
	global_load_dwordx4 v[190:193], v[34:35], off offset:256 nt
	global_load_dwordx4 v[68:71], v[40:41], off nt
	global_load_dwordx4 v[64:67], v[40:41], off offset:256 nt
	global_load_dwordx4 v[60:63], v[42:43], off nt
	global_load_dwordx4 v[56:59], v[42:43], off offset:256 nt
	ds_read_b32 v35, v152
	ds_read_b32 v41, v152 offset:1024
	ds_read_b32 v43, v152 offset:2048
	ds_read_b32 v197, v152 offset:3072
	ds_read_b32 v34, v152 offset:4096
	ds_read_b32 v40, v152 offset:5120
	ds_read_b32 v42, v152 offset:6144
	ds_read_b32 v196, v152 offset:7168
	v_or_b32_e32 v176, 48, v174
	v_ashrrev_i32_e32 v175, 31, v174
	s_waitcnt lgkmcnt(0)
	v_pk_add_f32 v[34:35], v[34:35], v[40:41]
	v_mad_i64_i32 v[48:49], s[2:3], v176, s77, v[172:173]
	v_pk_add_f32 v[34:35], v[34:35], v[42:43]
	v_lshlrev_b64 v[50:51], 11, v[174:175]
	v_pk_add_f32 v[34:35], v[34:35], v[196:197]
	v_lshl_add_u64 v[48:49], v[48:49], 0, v[86:87]
	v_pk_mul_f32 v[196:197], v[34:35], s[16:17] op_sel_hi:[1,0]
	v_lshl_add_u64 v[194:195], s[0:1], 0, v[50:51]
	v_fma_f32 v34, -v197, v197, v196
	v_max_f32_e32 v34, 0, v34
	v_add_f32_e32 v34, 0x358637bd, v34
	v_mul_f32_e32 v35, 0x4b800000, v34
	v_cmp_gt_f32_e32 vcc, s78, v34
	global_load_dwordx4 v[52:55], v[48:49], off nt
	s_nop 0
	global_load_dwordx4 v[48:51], v[48:49], off offset:256 nt
	v_cndmask_b32_e32 v34, v34, v35, vcc
	v_rsq_f32_e32 v175, v34
	global_load_dwordx4 v[40:43], v[32:33], off offset:512
	s_nop 0
	global_load_dwordx4 v[32:35], v[32:33], off offset:528
	v_pk_add_f32 v[28:29], v[28:29], v[196:197] op_sel:[0,1] neg_lo:[0,1] neg_hi:[0,1]
	v_pk_add_f32 v[30:31], v[30:31], v[196:197] op_sel:[0,1] neg_lo:[0,1] neg_hi:[0,1]
	v_mul_f32_e32 v177, 0x45800000, v175
	v_cndmask_b32_e32 v198, v175, v177, vcc
	v_pk_mul_f32 v[28:29], v[28:29], v[198:199] op_sel_hi:[1,0]
	v_pk_mul_f32 v[30:31], v[30:31], v[198:199] op_sel_hi:[1,0]
	v_pk_add_f32 v[166:167], v[166:167], v[196:197] op_sel:[0,1] neg_lo:[0,1] neg_hi:[0,1]
	v_pk_add_f32 v[150:151], v[150:151], v[196:197] op_sel:[0,1] neg_lo:[0,1] neg_hi:[0,1]
	v_pk_mul_f32 v[166:167], v[166:167], v[198:199] op_sel_hi:[1,0]
	v_pk_mul_f32 v[150:151], v[150:151], v[198:199] op_sel_hi:[1,0]
	v_pk_add_f32 v[164:165], v[164:165], v[196:197] op_sel:[0,1] neg_lo:[0,1] neg_hi:[0,1]
	v_pk_add_f32 v[148:149], v[148:149], v[196:197] op_sel:[0,1] neg_lo:[0,1] neg_hi:[0,1]
	v_pk_mul_f32 v[164:165], v[164:165], v[198:199] op_sel_hi:[1,0]
	v_pk_mul_f32 v[148:149], v[148:149], v[198:199] op_sel_hi:[1,0]
	v_pk_add_f32 v[140:141], v[140:141], v[196:197] op_sel:[0,1] neg_lo:[0,1] neg_hi:[0,1]
	v_ashrrev_i32_e32 v181, 31, v180
	v_pk_mul_f32 v[140:141], v[140:141], v[198:199] op_sel_hi:[1,0]
	s_add_i32 s18, s18, s96
	s_add_i32 s69, s69, s70
	s_add_i32 s71, s71, s72
	s_cmpk_gt_i32 s18, 0xff
	s_waitcnt vmcnt(0)
	v_lshlrev_b32_e32 v200, 16, v186
	v_and_b32_e32 v201, 0xffff0000, v186
	v_mul_f32_e32 v175, 0xbfb8aa3b, v200
	v_mul_f32_e32 v177, 0xbfb8aa3b, v201
	v_exp_f32_e32 v175, v175
	v_exp_f32_e32 v177, v177
	v_lshlrev_b32_e32 v186, 16, v187
	v_and_b32_e32 v187, 0xffff0000, v187
	v_add_f32_e32 v175, 1.0, v175
	v_mul_f32_e32 v179, 0xbfb8aa3b, v186
	v_add_f32_e32 v177, 1.0, v177
	v_rcp_f32_e32 v202, v175
	v_mul_f32_e32 v175, 0xbfb8aa3b, v187
	v_rcp_f32_e32 v203, v177
	v_exp_f32_e32 v177, v179
	v_exp_f32_e32 v175, v175
	v_pk_mul_f32 v[28:29], v[44:45], v[28:29]
	v_pk_mul_f32 v[200:201], v[202:203], v[200:201]
	v_add_f32_e32 v177, 1.0, v177
	v_add_f32_e32 v175, 1.0, v175
	v_pk_mul_f32 v[28:29], v[200:201], v[28:29]
	v_rcp_f32_e32 v200, v177
	v_rcp_f32_e32 v201, v175
	v_pk_mul_f32 v[30:31], v[46:47], v[30:31]
	v_pk_mul_f32 v[166:167], v[36:37], v[166:167]
	v_cvt_pk_bf16_f32 v28, v28, v29
	v_pk_mul_f32 v[186:187], v[200:201], v[186:187]
	v_lshlrev_b32_e32 v200, 16, v188
	v_and_b32_e32 v201, 0xffff0000, v188
	v_mul_f32_e32 v175, 0xbfb8aa3b, v200
	v_exp_f32_e32 v175, v175
	v_mul_f32_e32 v177, 0xbfb8aa3b, v201
	v_exp_f32_e32 v177, v177
	v_pk_mul_f32 v[30:31], v[186:187], v[30:31]
	v_add_f32_e32 v175, 1.0, v175
	v_rcp_f32_e32 v186, v175
	v_add_f32_e32 v175, 1.0, v177
	v_lshlrev_b32_e32 v188, 16, v189
	v_rcp_f32_e32 v187, v175
	v_and_b32_e32 v189, 0xffff0000, v189
	v_mul_f32_e32 v175, 0xbfb8aa3b, v188
	v_exp_f32_e32 v175, v175
	v_mul_f32_e32 v177, 0xbfb8aa3b, v189
	v_exp_f32_e32 v177, v177
	v_pk_mul_f32 v[186:187], v[186:187], v[200:201]
	v_add_f32_e32 v175, 1.0, v175
	v_pk_mul_f32 v[166:167], v[186:187], v[166:167]
	v_rcp_f32_e32 v186, v175
	v_add_f32_e32 v175, 1.0, v177
	v_rcp_f32_e32 v187, v175
	v_cvt_pk_bf16_f32 v29, v30, v31
	v_cvt_pk_bf16_f32 v30, v166, v167
	v_lshlrev_b32_e32 v166, 16, v190
	v_and_b32_e32 v167, 0xffff0000, v190
	v_mul_f32_e32 v175, 0xbfb8aa3b, v166
	v_mul_f32_e32 v177, 0xbfb8aa3b, v167
	v_exp_f32_e32 v175, v175
	v_exp_f32_e32 v177, v177
	v_pk_mul_f32 v[150:151], v[38:39], v[150:151]
	v_pk_mul_f32 v[186:187], v[186:187], v[188:189]
	s_waitcnt lgkmcnt(0)
	v_pk_mul_f32 v[164:165], v[42:43], v[164:165]
	v_pk_mul_f32 v[150:151], v[186:187], v[150:151]
	v_pk_mul_f32 v[148:149], v[32:33], v[148:149]
	v_cvt_pk_bf16_f32 v31, v150, v151
	v_lshl_add_u64 v[150:151], v[194:195], 0, v[86:87]
	global_store_dwordx4 v[150:151], v[28:31], off
	v_pk_mul_f32 v[140:141], v[34:35], v[140:141]
	v_ashrrev_i32_e32 v179, 31, v178
	v_add_f32_e32 v28, 1.0, v175
	v_add_f32_e32 v29, 1.0, v177
	v_rcp_f32_e32 v28, v28
	v_rcp_f32_e32 v29, v29
	v_pk_add_f32 v[30:31], v[170:171], v[196:197] op_sel:[0,1] neg_lo:[0,1] neg_hi:[0,1]
	v_ashrrev_i32_e32 v177, 31, v176
	v_pk_mul_f32 v[30:31], v[30:31], v[198:199] op_sel_hi:[1,0]
	v_pk_mul_f32 v[28:29], v[28:29], v[166:167]
	v_lshlrev_b32_e32 v166, 16, v191
	v_and_b32_e32 v167, 0xffff0000, v191
	v_mul_f32_e32 v170, 0xbfb8aa3b, v166
	v_mul_f32_e32 v171, 0xbfb8aa3b, v167
	v_exp_f32_e32 v170, v170
	v_exp_f32_e32 v171, v171
	v_pk_mul_f32 v[30:31], v[40:41], v[30:31]
	s_nop 0
	v_pk_mul_f32 v[28:29], v[28:29], v[30:31]
	v_add_f32_e32 v30, 1.0, v170
	v_add_f32_e32 v31, 1.0, v171
	v_rcp_f32_e32 v30, v30
	v_rcp_f32_e32 v31, v31
	v_cvt_pk_bf16_f32 v28, v28, v29
	v_pk_mul_f32 v[30:31], v[30:31], v[166:167]
	v_lshlrev_b32_e32 v166, 16, v192
	v_and_b32_e32 v167, 0xffff0000, v192
	v_mul_f32_e32 v170, 0xbfb8aa3b, v166
	v_mul_f32_e32 v171, 0xbfb8aa3b, v167
	v_exp_f32_e32 v170, v170
	v_exp_f32_e32 v171, v171
	v_pk_mul_f32 v[30:31], v[30:31], v[164:165]
	v_add_f32_e32 v164, 1.0, v170
	v_add_f32_e32 v165, 1.0, v171
	v_rcp_f32_e32 v164, v164
	v_rcp_f32_e32 v165, v165
	v_cvt_pk_bf16_f32 v29, v30, v31
	v_pk_mul_f32 v[164:165], v[164:165], v[166:167]
	v_lshlrev_b32_e32 v166, 16, v193
	v_and_b32_e32 v167, 0xffff0000, v193
	v_mul_f32_e32 v170, 0xbfb8aa3b, v166
	v_mul_f32_e32 v171, 0xbfb8aa3b, v167
	v_exp_f32_e32 v170, v170
	v_exp_f32_e32 v171, v171
	v_pk_mul_f32 v[148:149], v[164:165], v[148:149]
	v_add_f32_e32 v164, 1.0, v170
	v_add_f32_e32 v165, 1.0, v171
	v_rcp_f32_e32 v164, v164
	v_rcp_f32_e32 v165, v165
	v_cvt_pk_bf16_f32 v30, v148, v149
	v_pk_mul_f32 v[164:165], v[164:165], v[166:167]
	s_nop 0
	v_pk_mul_f32 v[140:141], v[164:165], v[140:141]
	s_nop 0
	v_cvt_pk_bf16_f32 v31, v140, v141
	global_store_dwordx4 v[150:151], v[28:31], off offset:256
	ds_read_b32 v29, v152 offset:64
	ds_read_b32 v31, v152 offset:1088
	ds_read_b32 v141, v152 offset:2112
	ds_read_b32 v149, v152 offset:3136
	ds_read_b32 v28, v152 offset:4160
	ds_read_b32 v30, v152 offset:5184
	ds_read_b32 v140, v152 offset:6208
	ds_read_b32 v148, v152 offset:7232
	s_waitcnt lgkmcnt(0)
	v_pk_add_f32 v[28:29], v[28:29], v[30:31]
	s_nop 0
	v_pk_add_f32 v[28:29], v[28:29], v[140:141]
	v_lshlrev_b64 v[140:141], 11, v[180:181]
	v_pk_add_f32 v[28:29], v[28:29], v[148:149]
	v_lshlrev_b32_e32 v148, 16, v68
	v_pk_mul_f32 v[28:29], v[28:29], s[16:17] op_sel_hi:[1,0]
	v_and_b32_e32 v149, 0xffff0000, v68
	v_fma_f32 v30, -v29, v29, v28
	v_max_f32_e32 v30, 0, v30
	v_add_f32_e32 v30, 0x358637bd, v30
	v_mul_f32_e32 v31, 0x4b800000, v30
	v_cmp_gt_f32_e32 vcc, s78, v30
	v_mul_f32_e32 v68, 0xbfb8aa3b, v149
	v_exp_f32_e32 v68, v68
	v_cndmask_b32_e32 v30, v30, v31, vcc
	v_rsq_f32_e32 v30, v30
	v_pk_add_f32 v[20:21], v[20:21], v[28:29] op_sel:[0,1] neg_lo:[0,1] neg_hi:[0,1]
	v_pk_add_f32 v[22:23], v[22:23], v[28:29] op_sel:[0,1] neg_lo:[0,1] neg_hi:[0,1]
	v_pk_add_f32 v[136:137], v[136:137], v[28:29] op_sel:[0,1] neg_lo:[0,1] neg_hi:[0,1]
	v_mul_f32_e32 v31, 0x45800000, v30
	v_cndmask_b32_e32 v30, v30, v31, vcc
	v_mul_f32_e32 v31, 0xbfb8aa3b, v148
	v_exp_f32_e32 v31, v31
	v_lshl_add_u64 v[140:141], s[0:1], 0, v[140:141]
	v_pk_add_f32 v[130:131], v[130:131], v[28:29] op_sel:[0,1] neg_lo:[0,1] neg_hi:[0,1]
	v_add_f32_e32 v31, 1.0, v31
	v_rcp_f32_e32 v150, v31
	v_add_f32_e32 v31, 1.0, v68
	v_rcp_f32_e32 v151, v31
	v_lshlrev_b32_e32 v68, 16, v69
	v_pk_mul_f32 v[20:21], v[20:21], v[30:31] op_sel_hi:[1,0]
	v_and_b32_e32 v69, 0xffff0000, v69
	v_mul_f32_e32 v31, 0xbfb8aa3b, v68
	v_pk_mul_f32 v[148:149], v[150:151], v[148:149]
	v_exp_f32_e32 v31, v31
	v_mul_f32_e32 v150, 0xbfb8aa3b, v69
	v_exp_f32_e32 v150, v150
	v_pk_mul_f32 v[20:21], v[44:45], v[20:21]
	v_add_f32_e32 v31, 1.0, v31
	v_pk_mul_f32 v[20:21], v[148:149], v[20:21]
	v_rcp_f32_e32 v148, v31
	v_add_f32_e32 v31, 1.0, v150
	v_rcp_f32_e32 v149, v31
	v_pk_mul_f32 v[22:23], v[22:23], v[30:31] op_sel_hi:[1,0]
	v_pk_add_f32 v[150:151], v[154:155], v[28:29] op_sel:[0,1] neg_lo:[0,1] neg_hi:[0,1]
	v_pk_mul_f32 v[22:23], v[46:47], v[22:23]
	v_pk_mul_f32 v[68:69], v[148:149], v[68:69]
	v_lshlrev_b32_e32 v148, 16, v70
	v_and_b32_e32 v149, 0xffff0000, v70
	v_mul_f32_e32 v31, 0xbfb8aa3b, v148
	v_exp_f32_e32 v31, v31
	v_mul_f32_e32 v70, 0xbfb8aa3b, v149
	v_exp_f32_e32 v70, v70
	v_pk_mul_f32 v[22:23], v[68:69], v[22:23]
	v_add_f32_e32 v31, 1.0, v31
	v_rcp_f32_e32 v68, v31
	v_add_f32_e32 v31, 1.0, v70
	v_rcp_f32_e32 v69, v31
	v_lshlrev_b32_e32 v70, 16, v71
	v_pk_mul_f32 v[150:151], v[150:151], v[30:31] op_sel_hi:[1,0]
	v_and_b32_e32 v71, 0xffff0000, v71
	v_mul_f32_e32 v31, 0xbfb8aa3b, v70
	v_pk_mul_f32 v[68:69], v[68:69], v[148:149]
	v_exp_f32_e32 v31, v31
	v_mul_f32_e32 v148, 0xbfb8aa3b, v71
	v_exp_f32_e32 v149, v148
	v_cvt_pk_bf16_f32 v20, v20, v21
	v_add_f32_e32 v31, 1.0, v31
	v_rcp_f32_e32 v148, v31
	v_add_f32_e32 v31, 1.0, v149
	v_rcp_f32_e32 v149, v31
	v_pk_mul_f32 v[136:137], v[136:137], v[30:31] op_sel_hi:[1,0]
	v_cvt_pk_bf16_f32 v21, v22, v23
	v_pk_mul_f32 v[136:137], v[38:39], v[136:137]
	v_pk_mul_f32 v[70:71], v[148:149], v[70:71]
	v_pk_mul_f32 v[150:151], v[36:37], v[150:151]
	v_pk_mul_f32 v[70:71], v[70:71], v[136:137]
	v_pk_mul_f32 v[68:69], v[68:69], v[150:151]
	v_cvt_pk_bf16_f32 v23, v70, v71
	v_lshlrev_b32_e32 v70, 16, v64
	v_and_b32_e32 v71, 0xffff0000, v64
	v_mul_f32_e32 v31, 0xbfb8aa3b, v70
	v_mul_f32_e32 v64, 0xbfb8aa3b, v71
	v_exp_f32_e32 v31, v31
	v_exp_f32_e32 v64, v64
	v_cvt_pk_bf16_f32 v22, v68, v69
	v_lshl_add_u64 v[68:69], v[140:141], 0, v[86:87]
	global_store_dwordx4 v[68:69], v[20:23], off
	s_nop 1
	v_add_f32_e32 v20, 1.0, v31
	v_add_f32_e32 v21, 1.0, v64
	v_rcp_f32_e32 v20, v20
	v_rcp_f32_e32 v21, v21
	v_pk_add_f32 v[22:23], v[168:169], v[28:29] op_sel:[0,1] neg_lo:[0,1] neg_hi:[0,1]
	v_lshlrev_b32_e32 v64, 16, v65
	v_and_b32_e32 v65, 0xffff0000, v65
	v_pk_mul_f32 v[22:23], v[22:23], v[30:31] op_sel_hi:[1,0]
	v_pk_mul_f32 v[20:21], v[20:21], v[70:71]
	v_mul_f32_e32 v31, 0xbfb8aa3b, v64
	v_mul_f32_e32 v70, 0xbfb8aa3b, v65
	v_exp_f32_e32 v31, v31
	v_exp_f32_e32 v70, v70
	v_pk_mul_f32 v[22:23], v[40:41], v[22:23]
	s_nop 0
	v_pk_mul_f32 v[20:21], v[20:21], v[22:23]
	v_add_f32_e32 v22, 1.0, v31
	v_add_f32_e32 v23, 1.0, v70
	v_rcp_f32_e32 v22, v22
	v_rcp_f32_e32 v23, v23
	v_pk_add_f32 v[70:71], v[156:157], v[28:29] op_sel:[0,1] neg_lo:[0,1] neg_hi:[0,1]
	v_pk_add_f32 v[28:29], v[120:121], v[28:29] op_sel:[0,1] neg_lo:[0,1] neg_hi:[0,1]
	v_pk_mul_f32 v[70:71], v[70:71], v[30:31] op_sel_hi:[1,0]
	v_pk_mul_f32 v[22:23], v[22:23], v[64:65]
	v_lshlrev_b32_e32 v64, 16, v66
	v_and_b32_e32 v65, 0xffff0000, v66
	v_mul_f32_e32 v31, 0xbfb8aa3b, v64
	v_exp_f32_e32 v31, v31
	v_mul_f32_e32 v66, 0xbfb8aa3b, v65
	v_exp_f32_e32 v66, v66
	v_pk_mul_f32 v[70:71], v[42:43], v[70:71]
	v_add_f32_e32 v31, 1.0, v31
	v_pk_mul_f32 v[22:23], v[22:23], v[70:71]
	v_rcp_f32_e32 v70, v31
	v_add_f32_e32 v31, 1.0, v66
	v_rcp_f32_e32 v71, v31
	v_lshlrev_b32_e32 v66, 16, v67
	v_pk_mul_f32 v[130:131], v[130:131], v[30:31] op_sel_hi:[1,0]
	v_and_b32_e32 v67, 0xffff0000, v67
	v_mul_f32_e32 v31, 0xbfb8aa3b, v66
	v_pk_mul_f32 v[64:65], v[70:71], v[64:65]
	v_exp_f32_e32 v31, v31
	v_mul_f32_e32 v70, 0xbfb8aa3b, v67
	v_exp_f32_e32 v71, v70
	v_pk_mul_f32 v[130:131], v[32:33], v[130:131]
	v_add_f32_e32 v31, 1.0, v31
	v_rcp_f32_e32 v70, v31
	v_add_f32_e32 v31, 1.0, v71
	v_rcp_f32_e32 v71, v31
	v_pk_mul_f32 v[28:29], v[28:29], v[30:31] op_sel_hi:[1,0]
	v_pk_mul_f32 v[64:65], v[64:65], v[130:131]
	v_pk_mul_f32 v[28:29], v[34:35], v[28:29]
	v_pk_mul_f32 v[30:31], v[70:71], v[66:67]
	v_cvt_pk_bf16_f32 v20, v20, v21
	v_pk_mul_f32 v[28:29], v[30:31], v[28:29]
	v_cvt_pk_bf16_f32 v21, v22, v23
	v_cvt_pk_bf16_f32 v22, v64, v65
	v_cvt_pk_bf16_f32 v23, v28, v29
	global_store_dwordx4 v[68:69], v[20:23], off offset:256
	ds_read_b32 v21, v152 offset:128
	ds_read_b32 v23, v152 offset:1152
	ds_read_b32 v29, v152 offset:2176
	ds_read_b32 v31, v152 offset:3200
	ds_read_b32 v20, v152 offset:4224
	ds_read_b32 v22, v152 offset:5248
	ds_read_b32 v28, v152 offset:6272
	ds_read_b32 v30, v152 offset:7296
	v_add_u32_e32 v70, 0x80, v174
	v_ashrrev_i32_e32 v71, 31, v70
	s_waitcnt lgkmcnt(0)
	v_pk_add_f32 v[20:21], v[20:21], v[22:23]
	s_nop 0
	v_pk_add_f32 v[20:21], v[20:21], v[28:29]
	v_lshlrev_b64 v[28:29], 11, v[178:179]
	v_pk_add_f32 v[20:21], v[20:21], v[30:31]
	v_lshlrev_b32_e32 v30, 16, v60
	v_pk_mul_f32 v[20:21], v[20:21], s[16:17] op_sel_hi:[1,0]
	v_and_b32_e32 v31, 0xffff0000, v60
	v_fma_f32 v22, -v21, v21, v20
	v_max_f32_e32 v22, 0, v22
	v_add_f32_e32 v22, 0x358637bd, v22
	v_mul_f32_e32 v23, 0x4b800000, v22
	v_cmp_gt_f32_e32 vcc, s78, v22
	v_mul_f32_e32 v60, 0xbfb8aa3b, v31
	v_exp_f32_e32 v60, v60
	v_cndmask_b32_e32 v22, v22, v23, vcc
	v_rsq_f32_e32 v22, v22
	v_pk_add_f32 v[16:17], v[16:17], v[20:21] op_sel:[0,1] neg_lo:[0,1] neg_hi:[0,1]
	v_pk_add_f32 v[18:19], v[18:19], v[20:21] op_sel:[0,1] neg_lo:[0,1] neg_hi:[0,1]
	v_lshl_add_u64 v[28:29], s[0:1], 0, v[28:29]
	v_mul_f32_e32 v23, 0x45800000, v22
	v_cndmask_b32_e32 v22, v22, v23, vcc
	v_mul_f32_e32 v23, 0xbfb8aa3b, v30
	v_exp_f32_e32 v23, v23
	v_lshl_add_u64 v[28:29], v[28:29], 0, v[86:87]
	v_add_f32_e32 v23, 1.0, v23
	v_rcp_f32_e32 v64, v23
	v_add_f32_e32 v23, 1.0, v60
	v_rcp_f32_e32 v65, v23
	v_lshlrev_b32_e32 v60, 16, v61
	v_pk_mul_f32 v[16:17], v[16:17], v[22:23] op_sel_hi:[1,0]
	v_and_b32_e32 v61, 0xffff0000, v61
	v_mul_f32_e32 v23, 0xbfb8aa3b, v60
	v_pk_mul_f32 v[30:31], v[64:65], v[30:31]
	v_exp_f32_e32 v23, v23
	v_mul_f32_e32 v64, 0xbfb8aa3b, v61
	v_exp_f32_e32 v64, v64
	v_pk_mul_f32 v[16:17], v[44:45], v[16:17]
	v_add_f32_e32 v23, 1.0, v23
	v_pk_mul_f32 v[16:17], v[30:31], v[16:17]
	v_rcp_f32_e32 v30, v23
	v_add_f32_e32 v23, 1.0, v64
	v_rcp_f32_e32 v31, v23
	v_pk_mul_f32 v[18:19], v[18:19], v[22:23] op_sel_hi:[1,0]
	v_pk_add_f32 v[64:65], v[134:135], v[20:21] op_sel:[0,1] neg_lo:[0,1] neg_hi:[0,1]
	v_pk_mul_f32 v[18:19], v[46:47], v[18:19]
	v_pk_mul_f32 v[30:31], v[30:31], v[60:61]
	v_lshlrev_b32_e32 v60, 16, v62
	v_and_b32_e32 v61, 0xffff0000, v62
	v_mul_f32_e32 v23, 0xbfb8aa3b, v60
	v_exp_f32_e32 v23, v23
	v_mul_f32_e32 v62, 0xbfb8aa3b, v61
	v_exp_f32_e32 v62, v62
	v_pk_mul_f32 v[18:19], v[30:31], v[18:19]
	v_add_f32_e32 v23, 1.0, v23
	v_rcp_f32_e32 v30, v23
	v_add_f32_e32 v23, 1.0, v62
	v_rcp_f32_e32 v31, v23
	v_pk_mul_f32 v[64:65], v[64:65], v[22:23] op_sel_hi:[1,0]
	v_cvt_pk_bf16_f32 v16, v16, v17
	v_pk_mul_f32 v[64:65], v[36:37], v[64:65]
	v_pk_mul_f32 v[30:31], v[30:31], v[60:61]
	v_lshlrev_b32_e32 v60, 16, v63
	v_and_b32_e32 v61, 0xffff0000, v63
	v_mul_f32_e32 v23, 0xbfb8aa3b, v60
	v_exp_f32_e32 v23, v23
	v_mul_f32_e32 v62, 0xbfb8aa3b, v61
	v_exp_f32_e32 v63, v62
	v_pk_mul_f32 v[30:31], v[30:31], v[64:65]
	v_add_f32_e32 v23, 1.0, v23
	v_rcp_f32_e32 v62, v23
	v_add_f32_e32 v23, 1.0, v63
	v_rcp_f32_e32 v63, v23
	v_pk_add_f32 v[64:65], v[116:117], v[20:21] op_sel:[0,1] neg_lo:[0,1] neg_hi:[0,1]
	v_cvt_pk_bf16_f32 v17, v18, v19
	v_cvt_pk_bf16_f32 v18, v30, v31
	v_lshlrev_b32_e32 v30, 16, v56
	v_and_b32_e32 v31, 0xffff0000, v56
	v_pk_mul_f32 v[64:65], v[64:65], v[22:23] op_sel_hi:[1,0]
	v_mul_f32_e32 v23, 0xbfb8aa3b, v30
	v_mul_f32_e32 v56, 0xbfb8aa3b, v31
	v_exp_f32_e32 v23, v23
	v_exp_f32_e32 v56, v56
	v_pk_mul_f32 v[64:65], v[38:39], v[64:65]
	v_pk_mul_f32 v[60:61], v[62:63], v[60:61]
	s_nop 0
	v_pk_mul_f32 v[60:61], v[60:61], v[64:65]
	s_nop 0
	v_cvt_pk_bf16_f32 v19, v60, v61
	global_store_dwordx4 v[28:29], v[16:19], off
	v_pk_add_f32 v[60:61], v[114:115], v[20:21] op_sel:[0,1] neg_lo:[0,1] neg_hi:[0,1]
	s_nop 0
	v_add_f32_e32 v16, 1.0, v23
	v_add_f32_e32 v17, 1.0, v56
	v_rcp_f32_e32 v16, v16
	v_rcp_f32_e32 v17, v17
	v_pk_add_f32 v[18:19], v[160:161], v[20:21] op_sel:[0,1] neg_lo:[0,1] neg_hi:[0,1]
	v_pk_mul_f32 v[16:17], v[16:17], v[30:31]
	v_lshlrev_b32_e32 v30, 16, v57
	v_and_b32_e32 v31, 0xffff0000, v57
	v_pk_mul_f32 v[18:19], v[18:19], v[22:23] op_sel_hi:[1,0]
	v_mul_f32_e32 v23, 0xbfb8aa3b, v30
	v_mul_f32_e32 v56, 0xbfb8aa3b, v31
	v_exp_f32_e32 v23, v23
	v_exp_f32_e32 v56, v56
	v_pk_mul_f32 v[18:19], v[40:41], v[18:19]
	s_nop 0
	v_pk_mul_f32 v[16:17], v[16:17], v[18:19]
	v_add_f32_e32 v18, 1.0, v23
	v_add_f32_e32 v19, 1.0, v56
	v_rcp_f32_e32 v18, v18
	v_rcp_f32_e32 v19, v19
	v_pk_add_f32 v[56:57], v[138:139], v[20:21] op_sel:[0,1] neg_lo:[0,1] neg_hi:[0,1]
	v_pk_add_f32 v[20:21], v[106:107], v[20:21] op_sel:[0,1] neg_lo:[0,1] neg_hi:[0,1]
	v_pk_mul_f32 v[56:57], v[56:57], v[22:23] op_sel_hi:[1,0]
	v_pk_mul_f32 v[18:19], v[18:19], v[30:31]
	v_lshlrev_b32_e32 v30, 16, v58
	v_and_b32_e32 v31, 0xffff0000, v58
	v_mul_f32_e32 v23, 0xbfb8aa3b, v30
	v_exp_f32_e32 v23, v23
	v_mul_f32_e32 v58, 0xbfb8aa3b, v31
	v_exp_f32_e32 v58, v58
	v_pk_mul_f32 v[56:57], v[42:43], v[56:57]
	v_add_f32_e32 v23, 1.0, v23
	v_pk_mul_f32 v[18:19], v[18:19], v[56:57]
	v_rcp_f32_e32 v56, v23
	v_add_f32_e32 v23, 1.0, v58
	v_rcp_f32_e32 v57, v23
	v_pk_mul_f32 v[60:61], v[60:61], v[22:23] op_sel_hi:[1,0]
	v_cvt_pk_bf16_f32 v16, v16, v17
	v_pk_mul_f32 v[60:61], v[32:33], v[60:61]
	v_pk_mul_f32 v[30:31], v[56:57], v[30:31]
	v_lshlrev_b32_e32 v56, 16, v59
	v_and_b32_e32 v57, 0xffff0000, v59
	v_mul_f32_e32 v23, 0xbfb8aa3b, v56
	v_exp_f32_e32 v23, v23
	v_mul_f32_e32 v58, 0xbfb8aa3b, v57
	v_exp_f32_e32 v59, v58
	v_pk_mul_f32 v[30:31], v[30:31], v[60:61]
	v_add_f32_e32 v23, 1.0, v23
	v_rcp_f32_e32 v58, v23
	v_add_f32_e32 v23, 1.0, v59
	v_rcp_f32_e32 v59, v23
	v_pk_mul_f32 v[20:21], v[20:21], v[22:23] op_sel_hi:[1,0]
	v_cvt_pk_bf16_f32 v17, v18, v19
	v_pk_mul_f32 v[20:21], v[34:35], v[20:21]
	v_pk_mul_f32 v[22:23], v[58:59], v[56:57]
	v_cvt_pk_bf16_f32 v18, v30, v31
	v_pk_mul_f32 v[20:21], v[22:23], v[20:21]
	v_add_u32_e32 v60, 0x90, v174
	v_cvt_pk_bf16_f32 v19, v20, v21
	global_store_dwordx4 v[28:29], v[16:19], off offset:256
	ds_read_b32 v17, v152 offset:192
	ds_read_b32 v19, v152 offset:1216
	ds_read_b32 v21, v152 offset:2240
	ds_read_b32 v23, v152 offset:3264
	ds_read_b32 v16, v152 offset:4288
	ds_read_b32 v18, v152 offset:5312
	ds_read_b32 v20, v152 offset:6336
	ds_read_b32 v22, v152 offset:7360
	v_add_u32_e32 v58, 0xa0, v174
	v_add_u32_e32 v56, 0xb0, v174
	s_waitcnt lgkmcnt(0)
	v_pk_add_f32 v[16:17], v[16:17], v[18:19]
	v_ashrrev_i32_e32 v61, 31, v60
	v_pk_add_f32 v[16:17], v[16:17], v[20:21]
	v_lshlrev_b64 v[20:21], 11, v[176:177]
	v_pk_add_f32 v[16:17], v[16:17], v[22:23]
	v_lshlrev_b32_e32 v22, 16, v52
	v_pk_mul_f32 v[16:17], v[16:17], s[16:17] op_sel_hi:[1,0]
	v_and_b32_e32 v23, 0xffff0000, v52
	v_fma_f32 v18, -v17, v17, v16
	v_max_f32_e32 v18, 0, v18
	v_add_f32_e32 v18, 0x358637bd, v18
	v_mul_f32_e32 v19, 0x4b800000, v18
	v_cmp_gt_f32_e32 vcc, s78, v18
	v_mul_f32_e32 v28, 0xbfb8aa3b, v23
	v_exp_f32_e32 v29, v28
	v_cndmask_b32_e32 v18, v18, v19, vcc
	v_rsq_f32_e32 v18, v18
	v_pk_add_f32 v[8:9], v[8:9], v[16:17] op_sel:[0,1] neg_lo:[0,1] neg_hi:[0,1]
	v_pk_add_f32 v[10:11], v[10:11], v[16:17] op_sel:[0,1] neg_lo:[0,1] neg_hi:[0,1]
	v_lshl_add_u64 v[20:21], s[0:1], 0, v[20:21]
	v_mul_f32_e32 v19, 0x45800000, v18
	v_cndmask_b32_e32 v18, v18, v19, vcc
	v_mul_f32_e32 v19, 0xbfb8aa3b, v22
	v_exp_f32_e32 v19, v19
	v_lshl_add_u64 v[20:21], v[20:21], 0, v[86:87]
	v_add_f32_e32 v19, 1.0, v19
	v_rcp_f32_e32 v28, v19
	v_add_f32_e32 v19, 1.0, v29
	v_rcp_f32_e32 v29, v19
	v_pk_mul_f32 v[8:9], v[8:9], v[18:19] op_sel_hi:[1,0]
	v_pk_mul_f32 v[22:23], v[28:29], v[22:23]
	v_lshlrev_b32_e32 v28, 16, v53
	v_and_b32_e32 v29, 0xffff0000, v53
	v_mul_f32_e32 v19, 0xbfb8aa3b, v28
	v_exp_f32_e32 v19, v19
	v_mul_f32_e32 v30, 0xbfb8aa3b, v29
	v_exp_f32_e32 v30, v30
	v_pk_mul_f32 v[8:9], v[44:45], v[8:9]
	v_add_f32_e32 v19, 1.0, v19
	v_pk_mul_f32 v[8:9], v[22:23], v[8:9]
	v_rcp_f32_e32 v22, v19
	v_add_f32_e32 v19, 1.0, v30
	v_rcp_f32_e32 v23, v19
	v_pk_mul_f32 v[10:11], v[10:11], v[18:19] op_sel_hi:[1,0]
	v_cvt_pk_bf16_f32 v8, v8, v9
	v_pk_mul_f32 v[10:11], v[46:47], v[10:11]
	v_pk_mul_f32 v[22:23], v[22:23], v[28:29]
	v_lshlrev_b32_e32 v28, 16, v54
	v_and_b32_e32 v29, 0xffff0000, v54
	v_mul_f32_e32 v19, 0xbfb8aa3b, v28
	v_exp_f32_e32 v19, v19
	v_mul_f32_e32 v30, 0xbfb8aa3b, v29
	v_exp_f32_e32 v30, v30
	v_pk_mul_f32 v[10:11], v[22:23], v[10:11]
	v_add_f32_e32 v19, 1.0, v19
	v_rcp_f32_e32 v22, v19
	v_add_f32_e32 v19, 1.0, v30
	v_rcp_f32_e32 v23, v19
	v_pk_add_f32 v[30:31], v[118:119], v[16:17] op_sel:[0,1] neg_lo:[0,1] neg_hi:[0,1]
	v_cvt_pk_bf16_f32 v9, v10, v11
	v_pk_mul_f32 v[30:31], v[30:31], v[18:19] op_sel_hi:[1,0]
	v_pk_mul_f32 v[22:23], v[22:23], v[28:29]
	v_lshlrev_b32_e32 v28, 16, v55
	v_and_b32_e32 v29, 0xffff0000, v55
	v_mul_f32_e32 v19, 0xbfb8aa3b, v28
	v_exp_f32_e32 v19, v19
	v_mul_f32_e32 v52, 0xbfb8aa3b, v29
	v_exp_f32_e32 v52, v52
	v_pk_mul_f32 v[30:31], v[36:37], v[30:31]
	v_add_f32_e32 v19, 1.0, v19
	v_pk_mul_f32 v[22:23], v[22:23], v[30:31]
	v_rcp_f32_e32 v30, v19
	v_add_f32_e32 v19, 1.0, v52
	v_rcp_f32_e32 v31, v19
	v_pk_add_f32 v[52:53], v[110:111], v[16:17] op_sel:[0,1] neg_lo:[0,1] neg_hi:[0,1]
	v_cvt_pk_bf16_f32 v10, v22, v23
	v_pk_mul_f32 v[52:53], v[52:53], v[18:19] op_sel_hi:[1,0]
	v_pk_mul_f32 v[28:29], v[30:31], v[28:29]
	v_pk_mul_f32 v[52:53], v[38:39], v[52:53]
	v_lshlrev_b32_e32 v22, 16, v48
	v_pk_mul_f32 v[28:29], v[28:29], v[52:53]
	v_and_b32_e32 v23, 0xffff0000, v48
	v_cvt_pk_bf16_f32 v11, v28, v29
	v_mul_f32_e32 v19, 0xbfb8aa3b, v22
	v_mul_f32_e32 v28, 0xbfb8aa3b, v23
	v_exp_f32_e32 v19, v19
	v_exp_f32_e32 v28, v28
	global_store_dwordx4 v[20:21], v[8:11], off
	s_nop 1
	v_add_f32_e32 v8, 1.0, v19
	v_add_f32_e32 v9, 1.0, v28
	v_rcp_f32_e32 v8, v8
	v_rcp_f32_e32 v9, v9
	v_pk_add_f32 v[10:11], v[142:143], v[16:17] op_sel:[0,1] neg_lo:[0,1] neg_hi:[0,1]
	v_pk_mul_f32 v[8:9], v[8:9], v[22:23]
	v_lshlrev_b32_e32 v22, 16, v49
	v_and_b32_e32 v23, 0xffff0000, v49
	v_pk_mul_f32 v[10:11], v[10:11], v[18:19] op_sel_hi:[1,0]
	v_mul_f32_e32 v19, 0xbfb8aa3b, v22
	v_mul_f32_e32 v28, 0xbfb8aa3b, v23
	v_exp_f32_e32 v19, v19
	v_exp_f32_e32 v28, v28
	v_pk_mul_f32 v[10:11], v[40:41], v[10:11]
	s_nop 0
	v_pk_mul_f32 v[8:9], v[8:9], v[10:11]
	v_add_f32_e32 v10, 1.0, v19
	v_add_f32_e32 v11, 1.0, v28
	v_rcp_f32_e32 v10, v10
	v_rcp_f32_e32 v11, v11
	v_pk_add_f32 v[28:29], v[122:123], v[16:17] op_sel:[0,1] neg_lo:[0,1] neg_hi:[0,1]
	v_cvt_pk_bf16_f32 v8, v8, v9
	v_pk_mul_f32 v[28:29], v[28:29], v[18:19] op_sel_hi:[1,0]
	v_pk_mul_f32 v[10:11], v[10:11], v[22:23]
	v_lshlrev_b32_e32 v22, 16, v50
	v_and_b32_e32 v23, 0xffff0000, v50
	v_mul_f32_e32 v19, 0xbfb8aa3b, v22
	v_exp_f32_e32 v19, v19
	v_mul_f32_e32 v30, 0xbfb8aa3b, v23
	v_exp_f32_e32 v30, v30
	v_pk_mul_f32 v[28:29], v[42:43], v[28:29]
	v_add_f32_e32 v19, 1.0, v19
	v_pk_mul_f32 v[10:11], v[10:11], v[28:29]
	v_rcp_f32_e32 v28, v19
	v_add_f32_e32 v19, 1.0, v30
	v_rcp_f32_e32 v29, v19
	v_pk_add_f32 v[30:31], v[108:109], v[16:17] op_sel:[0,1] neg_lo:[0,1] neg_hi:[0,1]
	v_pk_add_f32 v[16:17], v[104:105], v[16:17] op_sel:[0,1] neg_lo:[0,1] neg_hi:[0,1]
	v_pk_mul_f32 v[30:31], v[30:31], v[18:19] op_sel_hi:[1,0]
	v_pk_mul_f32 v[22:23], v[28:29], v[22:23]
	v_lshlrev_b32_e32 v28, 16, v51
	v_and_b32_e32 v29, 0xffff0000, v51
	v_mul_f32_e32 v19, 0xbfb8aa3b, v28
	v_exp_f32_e32 v19, v19
	v_mul_f32_e32 v48, 0xbfb8aa3b, v29
	v_exp_f32_e32 v48, v48
	v_pk_mul_f32 v[30:31], v[32:33], v[30:31]
	v_add_f32_e32 v19, 1.0, v19
	v_pk_mul_f32 v[22:23], v[22:23], v[30:31]
	v_rcp_f32_e32 v30, v19
	v_add_f32_e32 v19, 1.0, v48
	v_rcp_f32_e32 v31, v19
	v_pk_mul_f32 v[16:17], v[16:17], v[18:19] op_sel_hi:[1,0]
	v_cvt_pk_bf16_f32 v9, v10, v11
	v_pk_mul_f32 v[16:17], v[34:35], v[16:17]
	v_pk_mul_f32 v[18:19], v[30:31], v[28:29]
	v_cvt_pk_bf16_f32 v10, v22, v23
	v_pk_mul_f32 v[16:17], v[18:19], v[16:17]
	v_mad_i64_i32 v[104:105], s[2:3], v56, s77, v[172:173]
	v_cvt_pk_bf16_f32 v11, v16, v17
	global_store_dwordx4 v[20:21], v[8:11], off offset:256
	s_nop 1
	v_mad_i64_i32 v[8:9], s[2:3], v70, s77, v[172:173]
	v_lshl_add_u64 v[8:9], v[8:9], 0, v[86:87]
	global_load_dwordx4 v[62:65], v[8:9], off nt
	global_load_dwordx4 v[66:69], v[8:9], off offset:256 nt
	v_mad_i64_i32 v[8:9], s[2:3], v60, s77, v[172:173]
	v_lshl_add_u64 v[8:9], v[8:9], 0, v[86:87]
	global_load_dwordx4 v[52:55], v[8:9], off nt
	global_load_dwordx4 v[48:51], v[8:9], off offset:256 nt
	v_mad_i64_i32 v[8:9], s[2:3], v58, s77, v[172:173]
	v_lshl_add_u64 v[8:9], v[8:9], 0, v[86:87]
	global_load_dwordx4 v[28:31], v[8:9], off nt
	global_load_dwordx4 v[20:23], v[8:9], off offset:256 nt
	ds_read_b32 v9, v152 offset:512
	ds_read_b32 v11, v152 offset:1536
	ds_read_b32 v17, v152 offset:2560
	ds_read_b32 v19, v152 offset:3584
	ds_read_b32 v8, v152 offset:4608
	ds_read_b32 v10, v152 offset:5632
	ds_read_b32 v16, v152 offset:6656
	ds_read_b32 v18, v152 offset:7680
	v_lshlrev_b64 v[70:71], 11, v[70:71]
	v_lshl_add_u64 v[70:71], s[0:1], 0, v[70:71]
	s_waitcnt lgkmcnt(0)
	v_pk_add_f32 v[8:9], v[8:9], v[10:11]
	v_lshlrev_b64 v[60:61], 11, v[60:61]
	v_pk_add_f32 v[8:9], v[8:9], v[16:17]
	v_lshl_add_u64 v[60:61], s[0:1], 0, v[60:61]
	v_pk_add_f32 v[8:9], v[8:9], v[18:19]
	s_waitcnt vmcnt(0)
	v_lshlrev_b32_e32 v108, 16, v62
	v_pk_mul_f32 v[106:107], v[8:9], s[16:17] op_sel_hi:[1,0]
	v_and_b32_e32 v109, 0xffff0000, v62
	v_fma_f32 v8, -v107, v107, v106
	v_max_f32_e32 v8, 0, v8
	v_add_f32_e32 v8, 0x358637bd, v8
	v_mul_f32_e32 v9, 0x4b800000, v8
	v_cmp_gt_f32_e32 vcc, s78, v8
	v_lshlrev_b32_e32 v62, 16, v63
	v_and_b32_e32 v63, 0xffff0000, v63
	v_cndmask_b32_e32 v8, v8, v9, vcc
	v_rsq_f32_e32 v57, v8
	v_lshl_add_u64 v[8:9], v[104:105], 0, v[86:87]
	v_pk_add_f32 v[24:25], v[24:25], v[106:107] op_sel:[0,1] neg_lo:[0,1] neg_hi:[0,1]
	v_pk_add_f32 v[26:27], v[26:27], v[106:107] op_sel:[0,1] neg_lo:[0,1] neg_hi:[0,1]
	v_mul_f32_e32 v59, 0x45800000, v57
	v_cndmask_b32_e32 v104, v57, v59, vcc
	v_mul_f32_e32 v57, 0xbfb8aa3b, v108
	v_exp_f32_e32 v57, v57
	v_mul_f32_e32 v59, 0xbfb8aa3b, v109
	v_exp_f32_e32 v59, v59
	v_pk_mul_f32 v[24:25], v[24:25], v[104:105] op_sel_hi:[1,0]
	v_add_f32_e32 v57, 1.0, v57
	v_rcp_f32_e32 v110, v57
	v_add_f32_e32 v57, 1.0, v59
	v_rcp_f32_e32 v111, v57
	v_mul_f32_e32 v57, 0xbfb8aa3b, v62
	v_exp_f32_e32 v57, v57
	v_mul_f32_e32 v59, 0xbfb8aa3b, v63
	v_exp_f32_e32 v59, v59
	v_pk_mul_f32 v[24:25], v[44:45], v[24:25]
	v_pk_mul_f32 v[108:109], v[110:111], v[108:109]
	v_add_f32_e32 v57, 1.0, v57
	v_pk_mul_f32 v[24:25], v[108:109], v[24:25]
	v_rcp_f32_e32 v108, v57
	v_add_f32_e32 v57, 1.0, v59
	v_rcp_f32_e32 v109, v57
	v_pk_mul_f32 v[26:27], v[26:27], v[104:105] op_sel_hi:[1,0]
	v_pk_add_f32 v[110:111], v[158:159], v[106:107] op_sel:[0,1] neg_lo:[0,1] neg_hi:[0,1]
	v_pk_mul_f32 v[26:27], v[46:47], v[26:27]
	v_pk_mul_f32 v[62:63], v[108:109], v[62:63]
	v_lshlrev_b32_e32 v108, 16, v64
	v_and_b32_e32 v109, 0xffff0000, v64
	v_mul_f32_e32 v57, 0xbfb8aa3b, v108
	v_exp_f32_e32 v57, v57
	v_mul_f32_e32 v59, 0xbfb8aa3b, v109
	v_exp_f32_e32 v59, v59
	v_pk_mul_f32 v[26:27], v[62:63], v[26:27]
	v_add_f32_e32 v57, 1.0, v57
	v_rcp_f32_e32 v62, v57
	v_add_f32_e32 v57, 1.0, v59
	v_lshlrev_b32_e32 v64, 16, v65
	v_rcp_f32_e32 v63, v57
	v_and_b32_e32 v65, 0xffff0000, v65
	v_mul_f32_e32 v57, 0xbfb8aa3b, v64
	v_exp_f32_e32 v57, v57
	v_mul_f32_e32 v59, 0xbfb8aa3b, v65
	v_exp_f32_e32 v59, v59
	v_pk_mul_f32 v[62:63], v[62:63], v[108:109]
	v_add_f32_e32 v57, 1.0, v57
	v_rcp_f32_e32 v108, v57
	v_add_f32_e32 v57, 1.0, v59
	v_pk_mul_f32 v[110:111], v[110:111], v[104:105] op_sel_hi:[1,0]
	v_rcp_f32_e32 v109, v57
	v_pk_mul_f32 v[110:111], v[36:37], v[110:111]
	v_cvt_pk_bf16_f32 v24, v24, v25
	v_pk_mul_f32 v[62:63], v[62:63], v[110:111]
	v_pk_add_f32 v[110:111], v[132:133], v[106:107] op_sel:[0,1] neg_lo:[0,1] neg_hi:[0,1]
	v_pk_mul_f32 v[64:65], v[108:109], v[64:65]
	v_pk_mul_f32 v[110:111], v[110:111], v[104:105] op_sel_hi:[1,0]
	v_cvt_pk_bf16_f32 v25, v26, v27
	v_pk_mul_f32 v[110:111], v[38:39], v[110:111]
	v_cvt_pk_bf16_f32 v26, v62, v63
	v_pk_mul_f32 v[64:65], v[64:65], v[110:111]
	v_lshl_add_u64 v[62:63], v[70:71], 0, v[86:87]
	v_cvt_pk_bf16_f32 v27, v64, v65
	v_lshlrev_b32_e32 v64, 16, v66
	v_and_b32_e32 v65, 0xffff0000, v66
	v_mul_f32_e32 v57, 0xbfb8aa3b, v64
	v_mul_f32_e32 v59, 0xbfb8aa3b, v65
	v_exp_f32_e32 v57, v57
	v_exp_f32_e32 v59, v59
	global_load_dwordx4 v[16:19], v[8:9], off nt
	s_nop 0
	global_load_dwordx4 v[8:11], v[8:9], off offset:256 nt
	v_pk_add_f32 v[70:71], v[128:129], v[106:107] op_sel:[0,1] neg_lo:[0,1] neg_hi:[0,1]
	global_store_dwordx4 v[62:63], v[24:27], off
	v_pk_mul_f32 v[70:71], v[70:71], v[104:105] op_sel_hi:[1,0]
	s_nop 0
	v_add_f32_e32 v24, 1.0, v57
	v_add_f32_e32 v25, 1.0, v59
	v_rcp_f32_e32 v24, v24
	v_rcp_f32_e32 v25, v25
	v_pk_add_f32 v[26:27], v[162:163], v[106:107] op_sel:[0,1] neg_lo:[0,1] neg_hi:[0,1]
	v_pk_mul_f32 v[70:71], v[32:33], v[70:71]
	v_pk_mul_f32 v[26:27], v[26:27], v[104:105] op_sel_hi:[1,0]
	v_pk_mul_f32 v[24:25], v[24:25], v[64:65]
	v_lshlrev_b32_e32 v64, 16, v67
	v_and_b32_e32 v65, 0xffff0000, v67
	v_mul_f32_e32 v57, 0xbfb8aa3b, v64
	v_mul_f32_e32 v59, 0xbfb8aa3b, v65
	v_exp_f32_e32 v57, v57
	v_exp_f32_e32 v59, v59
	v_pk_mul_f32 v[26:27], v[40:41], v[26:27]
	v_pk_add_f32 v[66:67], v[146:147], v[106:107] op_sel:[0,1] neg_lo:[0,1] neg_hi:[0,1]
	v_pk_mul_f32 v[24:25], v[24:25], v[26:27]
	v_add_f32_e32 v26, 1.0, v57
	v_add_f32_e32 v27, 1.0, v59
	v_rcp_f32_e32 v26, v26
	v_rcp_f32_e32 v27, v27
	v_pk_mul_f32 v[66:67], v[66:67], v[104:105] op_sel_hi:[1,0]
	v_cvt_pk_bf16_f32 v24, v24, v25
	v_pk_mul_f32 v[66:67], v[42:43], v[66:67]
	v_pk_mul_f32 v[26:27], v[26:27], v[64:65]
	v_lshlrev_b32_e32 v64, 16, v68
	v_and_b32_e32 v65, 0xffff0000, v68
	v_mul_f32_e32 v57, 0xbfb8aa3b, v64
	v_exp_f32_e32 v57, v57
	v_mul_f32_e32 v59, 0xbfb8aa3b, v65
	v_exp_f32_e32 v59, v59
	v_pk_mul_f32 v[26:27], v[26:27], v[66:67]
	v_add_f32_e32 v57, 1.0, v57
	v_rcp_f32_e32 v66, v57
	v_add_f32_e32 v57, 1.0, v59
	v_rcp_f32_e32 v67, v57
	v_cvt_pk_bf16_f32 v25, v26, v27
	v_pk_mul_f32 v[64:65], v[66:67], v[64:65]
	v_lshlrev_b32_e32 v66, 16, v69
	v_and_b32_e32 v67, 0xffff0000, v69
	v_mul_f32_e32 v57, 0xbfb8aa3b, v66
	v_exp_f32_e32 v57, v57
	v_mul_f32_e32 v59, 0xbfb8aa3b, v67
	v_exp_f32_e32 v59, v59
	v_pk_mul_f32 v[64:65], v[64:65], v[70:71]
	v_add_f32_e32 v57, 1.0, v57
	v_rcp_f32_e32 v68, v57
	v_add_f32_e32 v57, 1.0, v59
	v_rcp_f32_e32 v69, v57
	v_pk_add_f32 v[70:71], v[112:113], v[106:107] op_sel:[0,1] neg_lo:[0,1] neg_hi:[0,1]
	v_cvt_pk_bf16_f32 v26, v64, v65
	v_pk_mul_f32 v[70:71], v[70:71], v[104:105] op_sel_hi:[1,0]
	v_pk_mul_f32 v[66:67], v[68:69], v[66:67]
	v_pk_mul_f32 v[70:71], v[34:35], v[70:71]
	v_ashrrev_i32_e32 v59, 31, v58
	v_pk_mul_f32 v[66:67], v[66:67], v[70:71]
	s_nop 0
	v_cvt_pk_bf16_f32 v27, v66, v67
	global_store_dwordx4 v[62:63], v[24:27], off offset:256
	ds_read_b32 v25, v152 offset:576
	ds_read_b32 v27, v152 offset:1600
	ds_read_b32 v63, v152 offset:2624
	ds_read_b32 v65, v152 offset:3648
	ds_read_b32 v24, v152 offset:4672
	ds_read_b32 v26, v152 offset:5696
	ds_read_b32 v62, v152 offset:6720
	ds_read_b32 v64, v152 offset:7744
	s_waitcnt lgkmcnt(0)
	v_pk_add_f32 v[24:25], v[24:25], v[26:27]
	s_nop 0
	v_pk_add_f32 v[24:25], v[24:25], v[62:63]
	v_lshlrev_b32_e32 v62, 16, v52
	v_pk_add_f32 v[24:25], v[24:25], v[64:65]
	v_and_b32_e32 v63, 0xffff0000, v52
	v_pk_mul_f32 v[24:25], v[24:25], s[16:17] op_sel_hi:[1,0]
	v_mul_f32_e32 v52, 0xbfb8aa3b, v63
	v_fma_f32 v26, -v25, v25, v24
	v_max_f32_e32 v26, 0, v26
	v_add_f32_e32 v26, 0x358637bd, v26
	v_mul_f32_e32 v27, 0x4b800000, v26
	v_cmp_gt_f32_e32 vcc, s78, v26
	v_exp_f32_e32 v52, v52
	v_pk_add_f32 v[12:13], v[12:13], v[24:25] op_sel:[0,1] neg_lo:[0,1] neg_hi:[0,1]
	v_cndmask_b32_e32 v26, v26, v27, vcc
	v_rsq_f32_e32 v26, v26
	v_pk_add_f32 v[14:15], v[14:15], v[24:25] op_sel:[0,1] neg_lo:[0,1] neg_hi:[0,1]
	v_mul_f32_e32 v27, 0x45800000, v26
	v_cndmask_b32_e32 v26, v26, v27, vcc
	v_mul_f32_e32 v27, 0xbfb8aa3b, v62
	v_exp_f32_e32 v27, v27
	s_nop 0
	v_add_f32_e32 v27, 1.0, v27
	v_rcp_f32_e32 v64, v27
	v_add_f32_e32 v27, 1.0, v52
	v_lshlrev_b32_e32 v52, 16, v53
	v_rcp_f32_e32 v65, v27
	v_pk_mul_f32 v[12:13], v[12:13], v[26:27] op_sel_hi:[1,0]
	v_and_b32_e32 v53, 0xffff0000, v53
	v_mul_f32_e32 v27, 0xbfb8aa3b, v52
	v_exp_f32_e32 v27, v27
	v_mul_f32_e32 v57, 0xbfb8aa3b, v53
	v_exp_f32_e32 v57, v57
	v_pk_mul_f32 v[12:13], v[44:45], v[12:13]
	v_pk_mul_f32 v[62:63], v[64:65], v[62:63]
	v_add_f32_e32 v27, 1.0, v27
	v_pk_mul_f32 v[12:13], v[62:63], v[12:13]
	v_rcp_f32_e32 v62, v27
	v_add_f32_e32 v27, 1.0, v57
	v_rcp_f32_e32 v63, v27
	v_pk_mul_f32 v[14:15], v[14:15], v[26:27] op_sel_hi:[1,0]
	v_pk_add_f32 v[64:65], v[124:125], v[24:25] op_sel:[0,1] neg_lo:[0,1] neg_hi:[0,1]
	v_pk_mul_f32 v[14:15], v[46:47], v[14:15]
	v_pk_mul_f32 v[52:53], v[62:63], v[52:53]
	v_lshlrev_b32_e32 v62, 16, v54
	v_and_b32_e32 v63, 0xffff0000, v54
	v_mul_f32_e32 v27, 0xbfb8aa3b, v62
	v_exp_f32_e32 v27, v27
	v_mul_f32_e32 v54, 0xbfb8aa3b, v63
	v_exp_f32_e32 v54, v54
	v_pk_mul_f32 v[14:15], v[52:53], v[14:15]
	v_add_f32_e32 v27, 1.0, v27
	v_rcp_f32_e32 v52, v27
	v_add_f32_e32 v27, 1.0, v54
	v_lshlrev_b32_e32 v54, 16, v55
	v_rcp_f32_e32 v53, v27
	v_pk_mul_f32 v[64:65], v[64:65], v[26:27] op_sel_hi:[1,0]
	v_and_b32_e32 v55, 0xffff0000, v55
	v_mul_f32_e32 v27, 0xbfb8aa3b, v54
	v_exp_f32_e32 v27, v27
	v_mul_f32_e32 v57, 0xbfb8aa3b, v55
	v_exp_f32_e32 v57, v57
	v_pk_mul_f32 v[52:53], v[52:53], v[62:63]
	v_add_f32_e32 v27, 1.0, v27
	v_rcp_f32_e32 v62, v27
	v_add_f32_e32 v27, 1.0, v57
	v_rcp_f32_e32 v63, v27
	v_pk_mul_f32 v[64:65], v[36:37], v[64:65]
	v_cvt_pk_bf16_f32 v12, v12, v13
	v_pk_mul_f32 v[52:53], v[52:53], v[64:65]
	v_pk_add_f32 v[64:65], v[100:101], v[24:25] op_sel:[0,1] neg_lo:[0,1] neg_hi:[0,1]
	v_pk_mul_f32 v[54:55], v[62:63], v[54:55]
	v_pk_mul_f32 v[64:65], v[64:65], v[26:27] op_sel_hi:[1,0]
	v_cvt_pk_bf16_f32 v13, v14, v15
	v_pk_mul_f32 v[64:65], v[38:39], v[64:65]
	v_cvt_pk_bf16_f32 v14, v52, v53
	v_pk_mul_f32 v[54:55], v[54:55], v[64:65]
	v_lshl_add_u64 v[52:53], v[60:61], 0, v[86:87]
	v_cvt_pk_bf16_f32 v15, v54, v55
	v_lshlrev_b32_e32 v54, 16, v48
	v_and_b32_e32 v55, 0xffff0000, v48
	v_mul_f32_e32 v27, 0xbfb8aa3b, v54
	v_mul_f32_e32 v48, 0xbfb8aa3b, v55
	v_exp_f32_e32 v27, v27
	v_exp_f32_e32 v48, v48
	global_store_dwordx4 v[52:53], v[12:15], off
	v_pk_add_f32 v[60:61], v[98:99], v[24:25] op_sel:[0,1] neg_lo:[0,1] neg_hi:[0,1]
	v_ashrrev_i32_e32 v57, 31, v56
	v_add_f32_e32 v12, 1.0, v27
	v_add_f32_e32 v13, 1.0, v48
	v_rcp_f32_e32 v12, v12
	v_rcp_f32_e32 v13, v13
	v_pk_add_f32 v[14:15], v[144:145], v[24:25] op_sel:[0,1] neg_lo:[0,1] neg_hi:[0,1]
	v_lshlrev_b32_e32 v48, 16, v49
	v_and_b32_e32 v49, 0xffff0000, v49
	v_pk_mul_f32 v[14:15], v[14:15], v[26:27] op_sel_hi:[1,0]
	v_pk_mul_f32 v[12:13], v[12:13], v[54:55]
	v_mul_f32_e32 v27, 0xbfb8aa3b, v48
	v_mul_f32_e32 v54, 0xbfb8aa3b, v49
	v_exp_f32_e32 v27, v27
	v_exp_f32_e32 v54, v54
	v_pk_mul_f32 v[14:15], v[40:41], v[14:15]
	s_nop 0
	v_pk_mul_f32 v[12:13], v[12:13], v[14:15]
	v_add_f32_e32 v14, 1.0, v27
	v_add_f32_e32 v15, 1.0, v54
	v_rcp_f32_e32 v14, v14
	v_rcp_f32_e32 v15, v15
	v_pk_add_f32 v[54:55], v[126:127], v[24:25] op_sel:[0,1] neg_lo:[0,1] neg_hi:[0,1]
	v_pk_add_f32 v[24:25], v[96:97], v[24:25] op_sel:[0,1] neg_lo:[0,1] neg_hi:[0,1]
	v_pk_mul_f32 v[54:55], v[54:55], v[26:27] op_sel_hi:[1,0]
	v_pk_mul_f32 v[14:15], v[14:15], v[48:49]
	v_lshlrev_b32_e32 v48, 16, v50
	v_and_b32_e32 v49, 0xffff0000, v50
	v_mul_f32_e32 v27, 0xbfb8aa3b, v48
	v_exp_f32_e32 v27, v27
	v_mul_f32_e32 v50, 0xbfb8aa3b, v49
	v_exp_f32_e32 v50, v50
	v_pk_mul_f32 v[54:55], v[42:43], v[54:55]
	v_add_f32_e32 v27, 1.0, v27
	v_pk_mul_f32 v[14:15], v[14:15], v[54:55]
	v_rcp_f32_e32 v54, v27
	v_add_f32_e32 v27, 1.0, v50
	v_rcp_f32_e32 v55, v27
	v_lshlrev_b32_e32 v50, 16, v51
	v_pk_mul_f32 v[60:61], v[60:61], v[26:27] op_sel_hi:[1,0]
	v_and_b32_e32 v51, 0xffff0000, v51
	v_mul_f32_e32 v27, 0xbfb8aa3b, v50
	v_pk_mul_f32 v[48:49], v[54:55], v[48:49]
	v_exp_f32_e32 v27, v27
	v_mul_f32_e32 v54, 0xbfb8aa3b, v51
	v_exp_f32_e32 v55, v54
	v_pk_mul_f32 v[60:61], v[32:33], v[60:61]
	v_add_f32_e32 v27, 1.0, v27
	v_rcp_f32_e32 v54, v27
	v_add_f32_e32 v27, 1.0, v55
	v_rcp_f32_e32 v55, v27
	v_pk_mul_f32 v[24:25], v[24:25], v[26:27] op_sel_hi:[1,0]
	v_pk_mul_f32 v[48:49], v[48:49], v[60:61]
	v_pk_mul_f32 v[24:25], v[34:35], v[24:25]
	v_pk_mul_f32 v[26:27], v[54:55], v[50:51]
	v_cvt_pk_bf16_f32 v12, v12, v13
	v_pk_mul_f32 v[24:25], v[26:27], v[24:25]
	v_cvt_pk_bf16_f32 v13, v14, v15
	v_cvt_pk_bf16_f32 v14, v48, v49
	v_cvt_pk_bf16_f32 v15, v24, v25
	global_store_dwordx4 v[52:53], v[12:15], off offset:256
	ds_read_b32 v13, v152 offset:640
	ds_read_b32 v15, v152 offset:1664
	ds_read_b32 v25, v152 offset:2688
	ds_read_b32 v27, v152 offset:3712
	ds_read_b32 v12, v152 offset:4736
	ds_read_b32 v14, v152 offset:5760
	ds_read_b32 v24, v152 offset:6784
	ds_read_b32 v26, v152 offset:7808
	s_waitcnt lgkmcnt(0)
	v_pk_add_f32 v[12:13], v[12:13], v[14:15]
	s_nop 0
	v_pk_add_f32 v[12:13], v[12:13], v[24:25]
	v_lshlrev_b64 v[24:25], 11, v[58:59]
	v_pk_add_f32 v[12:13], v[12:13], v[26:27]
	v_lshlrev_b32_e32 v26, 16, v28
	v_pk_mul_f32 v[12:13], v[12:13], s[16:17] op_sel_hi:[1,0]
	v_and_b32_e32 v27, 0xffff0000, v28
	v_fma_f32 v14, -v13, v13, v12
	v_max_f32_e32 v14, 0, v14
	v_add_f32_e32 v14, 0x358637bd, v14
	v_mul_f32_e32 v15, 0x4b800000, v14
	v_cmp_gt_f32_e32 vcc, s78, v14
	v_mul_f32_e32 v28, 0xbfb8aa3b, v27
	v_exp_f32_e32 v28, v28
	v_cndmask_b32_e32 v14, v14, v15, vcc
	v_rsq_f32_e32 v14, v14
	v_pk_add_f32 v[4:5], v[4:5], v[12:13] op_sel:[0,1] neg_lo:[0,1] neg_hi:[0,1]
	v_pk_add_f32 v[6:7], v[6:7], v[12:13] op_sel:[0,1] neg_lo:[0,1] neg_hi:[0,1]
	v_lshl_add_u64 v[24:25], s[0:1], 0, v[24:25]
	v_mul_f32_e32 v15, 0x45800000, v14
	v_cndmask_b32_e32 v14, v14, v15, vcc
	v_mul_f32_e32 v15, 0xbfb8aa3b, v26
	v_exp_f32_e32 v15, v15
	v_lshl_add_u64 v[24:25], v[24:25], 0, v[86:87]
	v_add_f32_e32 v15, 1.0, v15
	v_rcp_f32_e32 v48, v15
	v_add_f32_e32 v15, 1.0, v28
	v_rcp_f32_e32 v49, v15
	v_lshlrev_b32_e32 v28, 16, v29
	v_pk_mul_f32 v[4:5], v[4:5], v[14:15] op_sel_hi:[1,0]
	v_and_b32_e32 v29, 0xffff0000, v29
	v_mul_f32_e32 v15, 0xbfb8aa3b, v28
	v_pk_mul_f32 v[26:27], v[48:49], v[26:27]
	v_exp_f32_e32 v15, v15
	v_mul_f32_e32 v48, 0xbfb8aa3b, v29
	v_exp_f32_e32 v48, v48
	v_pk_mul_f32 v[4:5], v[44:45], v[4:5]
	v_add_f32_e32 v15, 1.0, v15
	v_pk_mul_f32 v[4:5], v[26:27], v[4:5]
	v_rcp_f32_e32 v26, v15
	v_add_f32_e32 v15, 1.0, v48
	v_rcp_f32_e32 v27, v15
	v_pk_mul_f32 v[6:7], v[6:7], v[14:15] op_sel_hi:[1,0]
	v_pk_add_f32 v[48:49], v[94:95], v[12:13] op_sel:[0,1] neg_lo:[0,1] neg_hi:[0,1]
	v_pk_mul_f32 v[6:7], v[46:47], v[6:7]
	v_pk_mul_f32 v[26:27], v[26:27], v[28:29]
	v_lshlrev_b32_e32 v28, 16, v30
	v_and_b32_e32 v29, 0xffff0000, v30
	v_mul_f32_e32 v15, 0xbfb8aa3b, v28
	v_exp_f32_e32 v15, v15
	v_mul_f32_e32 v30, 0xbfb8aa3b, v29
	v_exp_f32_e32 v30, v30
	v_pk_mul_f32 v[6:7], v[26:27], v[6:7]
	v_add_f32_e32 v15, 1.0, v15
	v_rcp_f32_e32 v26, v15
	v_add_f32_e32 v15, 1.0, v30
	v_rcp_f32_e32 v27, v15
	v_pk_mul_f32 v[48:49], v[48:49], v[14:15] op_sel_hi:[1,0]
	v_cvt_pk_bf16_f32 v4, v4, v5
	v_pk_mul_f32 v[48:49], v[36:37], v[48:49]
	v_pk_mul_f32 v[26:27], v[26:27], v[28:29]
	v_lshlrev_b32_e32 v28, 16, v31
	v_and_b32_e32 v29, 0xffff0000, v31
	v_mul_f32_e32 v15, 0xbfb8aa3b, v28
	v_exp_f32_e32 v15, v15
	v_mul_f32_e32 v30, 0xbfb8aa3b, v29
	v_exp_f32_e32 v31, v30
	v_pk_mul_f32 v[26:27], v[26:27], v[48:49]
	v_add_f32_e32 v15, 1.0, v15
	v_rcp_f32_e32 v30, v15
	v_add_f32_e32 v15, 1.0, v31
	v_rcp_f32_e32 v31, v15
	v_pk_add_f32 v[48:49], v[92:93], v[12:13] op_sel:[0,1] neg_lo:[0,1] neg_hi:[0,1]
	v_cvt_pk_bf16_f32 v5, v6, v7
	v_cvt_pk_bf16_f32 v6, v26, v27
	v_lshlrev_b32_e32 v26, 16, v20
	v_and_b32_e32 v27, 0xffff0000, v20
	v_pk_mul_f32 v[48:49], v[48:49], v[14:15] op_sel_hi:[1,0]
	v_mul_f32_e32 v15, 0xbfb8aa3b, v26
	v_mul_f32_e32 v20, 0xbfb8aa3b, v27
	v_exp_f32_e32 v15, v15
	v_exp_f32_e32 v20, v20
	v_pk_mul_f32 v[48:49], v[38:39], v[48:49]
	v_pk_mul_f32 v[28:29], v[30:31], v[28:29]
	s_nop 0
	v_pk_mul_f32 v[28:29], v[28:29], v[48:49]
	s_nop 0
	v_cvt_pk_bf16_f32 v7, v28, v29
	global_store_dwordx4 v[24:25], v[4:7], off
	v_pk_add_f32 v[28:29], v[88:89], v[12:13] op_sel:[0,1] neg_lo:[0,1] neg_hi:[0,1]
	s_nop 0
	v_add_f32_e32 v4, 1.0, v15
	v_add_f32_e32 v5, 1.0, v20
	v_rcp_f32_e32 v4, v4
	v_rcp_f32_e32 v5, v5
	v_pk_add_f32 v[6:7], v[102:103], v[12:13] op_sel:[0,1] neg_lo:[0,1] neg_hi:[0,1]
	v_lshlrev_b32_e32 v20, 16, v21
	v_and_b32_e32 v21, 0xffff0000, v21
	v_pk_mul_f32 v[6:7], v[6:7], v[14:15] op_sel_hi:[1,0]
	v_pk_mul_f32 v[4:5], v[4:5], v[26:27]
	v_mul_f32_e32 v15, 0xbfb8aa3b, v20
	v_mul_f32_e32 v26, 0xbfb8aa3b, v21
	v_exp_f32_e32 v15, v15
	v_exp_f32_e32 v26, v26
	v_pk_mul_f32 v[6:7], v[40:41], v[6:7]
	s_nop 0
	v_pk_mul_f32 v[4:5], v[4:5], v[6:7]
	v_add_f32_e32 v6, 1.0, v15
	v_add_f32_e32 v7, 1.0, v26
	v_rcp_f32_e32 v6, v6
	v_rcp_f32_e32 v7, v7
	v_pk_add_f32 v[26:27], v[90:91], v[12:13] op_sel:[0,1] neg_lo:[0,1] neg_hi:[0,1]
	v_pk_add_f32 v[12:13], v[78:79], v[12:13] op_sel:[0,1] neg_lo:[0,1] neg_hi:[0,1]
	v_pk_mul_f32 v[26:27], v[26:27], v[14:15] op_sel_hi:[1,0]
	v_pk_mul_f32 v[6:7], v[6:7], v[20:21]
	v_lshlrev_b32_e32 v20, 16, v22
	v_and_b32_e32 v21, 0xffff0000, v22
	v_mul_f32_e32 v15, 0xbfb8aa3b, v20
	v_exp_f32_e32 v15, v15
	v_mul_f32_e32 v22, 0xbfb8aa3b, v21
	v_exp_f32_e32 v22, v22
	v_pk_mul_f32 v[26:27], v[42:43], v[26:27]
	v_add_f32_e32 v15, 1.0, v15
	v_pk_mul_f32 v[6:7], v[6:7], v[26:27]
	v_rcp_f32_e32 v26, v15
	v_add_f32_e32 v15, 1.0, v22
	v_rcp_f32_e32 v27, v15
	v_lshlrev_b32_e32 v22, 16, v23
	v_pk_mul_f32 v[28:29], v[28:29], v[14:15] op_sel_hi:[1,0]
	v_and_b32_e32 v23, 0xffff0000, v23
	v_mul_f32_e32 v15, 0xbfb8aa3b, v22
	v_pk_mul_f32 v[20:21], v[26:27], v[20:21]
	v_exp_f32_e32 v15, v15
	v_mul_f32_e32 v26, 0xbfb8aa3b, v23
	v_exp_f32_e32 v27, v26
	v_pk_mul_f32 v[28:29], v[32:33], v[28:29]
	v_add_f32_e32 v15, 1.0, v15
	v_rcp_f32_e32 v26, v15
	v_add_f32_e32 v15, 1.0, v27
	v_rcp_f32_e32 v27, v15
	v_pk_mul_f32 v[12:13], v[12:13], v[14:15] op_sel_hi:[1,0]
	v_pk_mul_f32 v[20:21], v[20:21], v[28:29]
	v_pk_mul_f32 v[12:13], v[34:35], v[12:13]
	v_pk_mul_f32 v[14:15], v[26:27], v[22:23]
	v_cvt_pk_bf16_f32 v4, v4, v5
	v_pk_mul_f32 v[12:13], v[14:15], v[12:13]
	v_cvt_pk_bf16_f32 v5, v6, v7
	v_cvt_pk_bf16_f32 v6, v20, v21
	v_cvt_pk_bf16_f32 v7, v12, v13
	global_store_dwordx4 v[24:25], v[4:7], off offset:256
	ds_read_b32 v5, v152 offset:704
	ds_read_b32 v7, v152 offset:1728
	ds_read_b32 v13, v152 offset:2752
	ds_read_b32 v15, v152 offset:3776
	ds_read_b32 v4, v152 offset:4800
	ds_read_b32 v6, v152 offset:5824
	ds_read_b32 v12, v152 offset:6848
	ds_read_b32 v14, v152 offset:7872
	s_waitcnt lgkmcnt(0)
	v_pk_add_f32 v[4:5], v[4:5], v[6:7]
	s_nop 0
	v_pk_add_f32 v[4:5], v[4:5], v[12:13]
	v_lshlrev_b64 v[12:13], 11, v[56:57]
	v_pk_add_f32 v[4:5], v[4:5], v[14:15]
	s_waitcnt vmcnt(0)
	v_lshlrev_b32_e32 v14, 16, v16
	v_pk_mul_f32 v[4:5], v[4:5], s[16:17] op_sel_hi:[1,0]
	v_and_b32_e32 v15, 0xffff0000, v16
	v_fma_f32 v6, -v5, v5, v4
	v_max_f32_e32 v6, 0, v6
	v_add_f32_e32 v6, 0x358637bd, v6
	v_mul_f32_e32 v7, 0x4b800000, v6
	v_cmp_gt_f32_e32 vcc, s78, v6
	v_mul_f32_e32 v16, 0xbfb8aa3b, v15
	v_exp_f32_e32 v16, v16
	v_cndmask_b32_e32 v6, v6, v7, vcc
	v_rsq_f32_e32 v6, v6
	v_pk_add_f32 v[0:1], v[0:1], v[4:5] op_sel:[0,1] neg_lo:[0,1] neg_hi:[0,1]
	v_pk_add_f32 v[2:3], v[2:3], v[4:5] op_sel:[0,1] neg_lo:[0,1] neg_hi:[0,1]
	v_lshl_add_u64 v[12:13], s[0:1], 0, v[12:13]
	v_mul_f32_e32 v7, 0x45800000, v6
	v_cndmask_b32_e32 v6, v6, v7, vcc
	v_mul_f32_e32 v7, 0xbfb8aa3b, v14
	v_exp_f32_e32 v7, v7
	v_lshl_add_u64 v[12:13], v[12:13], 0, v[86:87]
	v_add_f32_e32 v7, 1.0, v7
	v_rcp_f32_e32 v20, v7
	v_add_f32_e32 v7, 1.0, v16
	v_rcp_f32_e32 v21, v7
	v_lshlrev_b32_e32 v16, 16, v17
	v_pk_mul_f32 v[0:1], v[0:1], v[6:7] op_sel_hi:[1,0]
	v_and_b32_e32 v17, 0xffff0000, v17
	v_mul_f32_e32 v7, 0xbfb8aa3b, v16
	v_pk_mul_f32 v[14:15], v[20:21], v[14:15]
	v_exp_f32_e32 v7, v7
	v_mul_f32_e32 v20, 0xbfb8aa3b, v17
	v_exp_f32_e32 v20, v20
	v_pk_mul_f32 v[0:1], v[44:45], v[0:1]
	v_add_f32_e32 v7, 1.0, v7
	v_pk_mul_f32 v[0:1], v[14:15], v[0:1]
	v_rcp_f32_e32 v14, v7
	v_add_f32_e32 v7, 1.0, v20
	v_rcp_f32_e32 v15, v7
	v_pk_mul_f32 v[2:3], v[2:3], v[6:7] op_sel_hi:[1,0]
	v_pk_add_f32 v[20:21], v[84:85], v[4:5] op_sel:[0,1] neg_lo:[0,1] neg_hi:[0,1]
	v_pk_mul_f32 v[2:3], v[46:47], v[2:3]
	v_pk_mul_f32 v[14:15], v[14:15], v[16:17]
	v_lshlrev_b32_e32 v16, 16, v18
	v_and_b32_e32 v17, 0xffff0000, v18
	v_mul_f32_e32 v7, 0xbfb8aa3b, v16
	v_exp_f32_e32 v7, v7
	v_mul_f32_e32 v18, 0xbfb8aa3b, v17
	v_exp_f32_e32 v18, v18
	v_pk_mul_f32 v[2:3], v[14:15], v[2:3]
	v_add_f32_e32 v7, 1.0, v7
	v_rcp_f32_e32 v14, v7
	v_add_f32_e32 v7, 1.0, v18
	v_rcp_f32_e32 v15, v7
	v_pk_mul_f32 v[20:21], v[20:21], v[6:7] op_sel_hi:[1,0]
	v_cvt_pk_bf16_f32 v0, v0, v1
	v_pk_mul_f32 v[20:21], v[36:37], v[20:21]
	v_pk_mul_f32 v[14:15], v[14:15], v[16:17]
	v_lshlrev_b32_e32 v16, 16, v19
	v_and_b32_e32 v17, 0xffff0000, v19
	v_mul_f32_e32 v7, 0xbfb8aa3b, v16
	v_exp_f32_e32 v7, v7
	v_mul_f32_e32 v18, 0xbfb8aa3b, v17
	v_exp_f32_e32 v19, v18
	v_pk_mul_f32 v[14:15], v[14:15], v[20:21]
	v_add_f32_e32 v7, 1.0, v7
	v_rcp_f32_e32 v18, v7
	v_add_f32_e32 v7, 1.0, v19
	v_rcp_f32_e32 v19, v7
	v_pk_add_f32 v[20:21], v[76:77], v[4:5] op_sel:[0,1] neg_lo:[0,1] neg_hi:[0,1]
	v_cvt_pk_bf16_f32 v1, v2, v3
	v_cvt_pk_bf16_f32 v2, v14, v15
	v_lshlrev_b32_e32 v14, 16, v8
	v_and_b32_e32 v15, 0xffff0000, v8
	v_pk_mul_f32 v[20:21], v[20:21], v[6:7] op_sel_hi:[1,0]
	v_mul_f32_e32 v7, 0xbfb8aa3b, v14
	v_mul_f32_e32 v8, 0xbfb8aa3b, v15
	v_exp_f32_e32 v7, v7
	v_exp_f32_e32 v8, v8
	v_pk_mul_f32 v[20:21], v[38:39], v[20:21]
	v_pk_mul_f32 v[16:17], v[18:19], v[16:17]
	s_nop 0
	v_pk_mul_f32 v[16:17], v[16:17], v[20:21]
	s_nop 0
	v_cvt_pk_bf16_f32 v3, v16, v17
	global_store_dwordx4 v[12:13], v[0:3], off
	v_pk_add_f32 v[16:17], v[74:75], v[4:5] op_sel:[0,1] neg_lo:[0,1] neg_hi:[0,1]
	s_nop 0
	v_add_f32_e32 v0, 1.0, v7
	v_add_f32_e32 v1, 1.0, v8
	v_rcp_f32_e32 v0, v0
	v_rcp_f32_e32 v1, v1
	v_pk_add_f32 v[2:3], v[82:83], v[4:5] op_sel:[0,1] neg_lo:[0,1] neg_hi:[0,1]
	v_lshlrev_b32_e32 v8, 16, v9
	v_and_b32_e32 v9, 0xffff0000, v9
	v_pk_mul_f32 v[2:3], v[2:3], v[6:7] op_sel_hi:[1,0]
	v_pk_mul_f32 v[0:1], v[0:1], v[14:15]
	v_mul_f32_e32 v7, 0xbfb8aa3b, v8
	v_mul_f32_e32 v14, 0xbfb8aa3b, v9
	v_exp_f32_e32 v7, v7
	v_exp_f32_e32 v14, v14
	v_pk_mul_f32 v[2:3], v[40:41], v[2:3]
	s_nop 0
	v_pk_mul_f32 v[0:1], v[0:1], v[2:3]
	v_add_f32_e32 v2, 1.0, v7
	v_add_f32_e32 v3, 1.0, v14
	v_rcp_f32_e32 v2, v2
	v_rcp_f32_e32 v3, v3
	v_pk_add_f32 v[14:15], v[80:81], v[4:5] op_sel:[0,1] neg_lo:[0,1] neg_hi:[0,1]
	v_pk_add_f32 v[4:5], v[72:73], v[4:5] op_sel:[0,1] neg_lo:[0,1] neg_hi:[0,1]
	v_pk_mul_f32 v[14:15], v[14:15], v[6:7] op_sel_hi:[1,0]
	v_pk_mul_f32 v[2:3], v[2:3], v[8:9]
	v_lshlrev_b32_e32 v8, 16, v10
	v_and_b32_e32 v9, 0xffff0000, v10
	v_mul_f32_e32 v7, 0xbfb8aa3b, v8
	v_exp_f32_e32 v7, v7
	v_mul_f32_e32 v10, 0xbfb8aa3b, v9
	v_exp_f32_e32 v10, v10
	v_pk_mul_f32 v[14:15], v[42:43], v[14:15]
	v_add_f32_e32 v7, 1.0, v7
	v_pk_mul_f32 v[2:3], v[2:3], v[14:15]
	v_rcp_f32_e32 v14, v7
	v_add_f32_e32 v7, 1.0, v10
	v_rcp_f32_e32 v15, v7
	v_lshlrev_b32_e32 v10, 16, v11
	v_pk_mul_f32 v[16:17], v[16:17], v[6:7] op_sel_hi:[1,0]
	v_and_b32_e32 v11, 0xffff0000, v11
	v_mul_f32_e32 v7, 0xbfb8aa3b, v10
	v_pk_mul_f32 v[8:9], v[14:15], v[8:9]
	v_exp_f32_e32 v7, v7
	v_mul_f32_e32 v14, 0xbfb8aa3b, v11
	v_exp_f32_e32 v15, v14
	v_pk_mul_f32 v[16:17], v[32:33], v[16:17]
	v_add_f32_e32 v7, 1.0, v7
	v_rcp_f32_e32 v14, v7
	v_add_f32_e32 v7, 1.0, v15
	v_rcp_f32_e32 v15, v7
	v_pk_mul_f32 v[4:5], v[4:5], v[6:7] op_sel_hi:[1,0]
	v_pk_mul_f32 v[8:9], v[8:9], v[16:17]
	v_pk_mul_f32 v[4:5], v[34:35], v[4:5]
	v_pk_mul_f32 v[6:7], v[14:15], v[10:11]
	v_cvt_pk_bf16_f32 v0, v0, v1
	v_pk_mul_f32 v[4:5], v[6:7], v[4:5]
	v_cvt_pk_bf16_f32 v1, v2, v3
	v_cvt_pk_bf16_f32 v2, v8, v9
	v_cvt_pk_bf16_f32 v3, v4, v5
	global_store_dwordx4 v[12:13], v[0:3], off offset:256
	s_cbranch_scc1 .LBB0_679

.LBB0_639:
	v_and_b32_e32 v131, 64, v183
	s_and_b32 s42, s2, 3
	s_lshl_b64 s[0:1], s[18:19], 17
	v_xor_b32_e32 v130, 16, v183
	v_add_u32_e32 v131, 64, v131
	v_mov_b32_e32 v128, v182
	s_add_u32 s22, s41, s0
	v_cmp_lt_i32_e32 vcc, v130, v131
	s_addc_u32 s23, s44, s1
	v_and_b32_e32 v129, 63, v128
	s_ashr_i32 s79, s81, 2
	v_cndmask_b32_e32 v130, v183, v130, vcc
	s_andn2_b32 s79, s79, 63
	v_ashrrev_i32_e32 v128, 1, v129
	v_lshlrev_b32_e32 v172, 2, v130
	v_xor_b32_e32 v130, 32, v183
	v_and_or_b32 v132, v129, 15, s79
	s_lshl_b32 s80, s42, 5
	v_and_b32_e32 v128, -8, v128
	v_cmp_lt_i32_e32 vcc, v130, v131
	v_add_u32_e32 v128, s80, v128
	s_mov_b64 s[26:27], s[22:23]
	v_cndmask_b32_e32 v130, v183, v130, vcc
	v_cmp_gt_u32_e32 vcc, 16, v129
	v_lshl_add_u32 v129, v132, 2, 0
	v_add_u32_e32 v135, 0x20000, v129
	v_lshl_add_u32 v129, v128, 2, 0
	v_add_u32_e32 v134, 0x20800, v129
	ds_read_b32 v150, v135
	ds_read_b128 v[136:139], v134
	ds_read_b128 v[140:143], v134 offset:16
	s_lshl_b32 s0, s42, 10
	v_ashrrev_i32_e32 v133, 31, v132
	v_lshlrev_b32_e32 v173, 2, v130
	s_add_i32 s2, s0, 0
	v_lshlrev_b64 v[130:131], 9, v[132:133]
	v_cmp_gt_i32_e64 s[0:1], v128, v132
	v_lshl_add_u64 v[144:145], s[26:27], 0, v[130:131]
	s_waitcnt lgkmcnt(0)
	v_sub_f32_e32 v129, v136, v150
	v_cndmask_b32_e64 v130, 1.0, 0, s[0:1]
	v_mul_f32_e32 v130, v124, v130
	v_sub_f32_e32 v124, v140, v150
	v_min_f32_e32 v124, 0, v124
	v_mul_f32_e32 v124, 0x3fb8aa3b, v124
	v_exp_f32_e32 v136, v124
	v_sub_f32_e32 v124, v137, v150
	v_sub_f32_e32 v137, v141, v150
	v_min_f32_e32 v124, 0, v124
	v_min_f32_e32 v137, 0, v137
	v_min_f32_e32 v129, 0, v129
	v_cmp_lt_i32_e64 s[0:1], v128, v132
	v_mul_f32_e32 v124, 0x3fb8aa3b, v124
	v_or_b32_e32 v131, 5, v128
	v_mul_f32_e32 v137, 0x3fb8aa3b, v137
	v_mul_f32_e32 v129, 0x3fb8aa3b, v129
	v_cndmask_b32_e64 v140, 0, 1.0, s[0:1]
	v_exp_f32_e32 v146, v124
	v_or_b32_e32 v124, 4, v128
	v_exp_f32_e32 v137, v137
	v_cmp_gt_i32_e64 s[0:1], v131, v132
	v_exp_f32_e32 v129, v129
	v_mul_f32_e32 v125, v125, v140
	v_cndmask_b32_e64 v141, 1.0, 0, s[0:1]
	v_cmp_gt_i32_e64 s[0:1], v124, v132
	v_mul_f32_e32 v133, v130, v129
	v_mul_f32_e32 v148, v125, v146
	v_cndmask_b32_e64 v140, 1.0, 0, s[0:1]
	v_pk_mul_f32 v[120:121], v[120:121], v[140:141]
	s_add_i32 s2, s2, 0x21400
	v_pk_mul_f32 v[140:141], v[120:121], v[136:137]
	s_nop 0
	v_fma_f32 v120, v130, v129, v140
	v_add_f32_e32 v120, 0, v120
	v_fma_f32 v121, v125, v146, v141
	v_add_f32_e32 v149, v121, v120
	v_sub_f32_e32 v120, v138, v150
	v_sub_f32_e32 v129, v139, v150
	v_min_f32_e32 v120, 0, v120
	v_min_f32_e32 v129, 0, v129
	v_mul_f32_e32 v120, 0x3fb8aa3b, v120
	v_mul_f32_e32 v129, 0x3fb8aa3b, v129
	v_exp_f32_e32 v136, v120
	v_sub_f32_e32 v120, v142, v150
	v_or_b32_e32 v125, 3, v128
	v_exp_f32_e32 v137, v129
	v_sub_f32_e32 v129, v143, v150
	v_min_f32_e32 v120, 0, v120
	v_or_b32_e32 v130, 2, v128
	v_cmp_gt_i32_e64 s[0:1], v125, v132
	v_min_f32_e32 v129, 0, v129
	v_mul_f32_e32 v120, 0x3fb8aa3b, v120
	v_or_b32_e32 v121, 7, v128
	v_cndmask_b32_e64 v147, 1.0, 0, s[0:1]
	v_cmp_gt_i32_e64 s[0:1], v130, v132
	v_mul_f32_e32 v129, 0x3fb8aa3b, v129
	v_exp_f32_e32 v138, v120
	v_or_b32_e32 v120, 6, v128
	v_cndmask_b32_e64 v146, 1.0, 0, s[0:1]
	v_exp_f32_e32 v139, v129
	v_cmp_gt_i32_e64 s[0:1], v121, v132
	v_pk_mul_f32 v[126:127], v[126:127], v[146:147]
	v_ashrrev_i32_e32 v129, 31, v128
	v_cndmask_b32_e64 v143, 1.0, 0, s[0:1]
	v_cmp_gt_i32_e64 s[0:1], v120, v132
	v_pk_mul_f32 v[146:147], v[126:127], v[136:137]
	v_lshl_add_u64 v[144:145], v[128:129], 1, v[144:145]
	v_cndmask_b32_e64 v142, 1.0, 0, s[0:1]
	v_pk_mul_f32 v[122:123], v[122:123], v[142:143]
	s_nop 0
	v_pk_mul_f32 v[122:123], v[122:123], v[138:139]
	v_cvt_pk_bf16_f32 v138, v140, v141
	v_pk_fma_f32 v[126:127], v[126:127], v[136:137], v[122:123]
	v_cvt_pk_bf16_f32 v136, v133, v148
	v_cvt_pk_bf16_f32 v137, v146, v147
	v_cvt_pk_bf16_f32 v139, v122, v123
	global_store_dwordx4 v[144:145], v[136:139], off
	ds_read_b128 v[136:139], v134 offset:512
	ds_read_b128 v[140:143], v134 offset:528
	v_add_f32_e32 v122, v126, v149
	v_add_u32_e32 v126, 0x80, v128
	v_add_f32_e32 v127, v127, v122
	s_waitcnt lgkmcnt(0)
	v_sub_f32_e32 v122, v136, v150
	v_cmp_gt_i32_e64 s[0:1], v132, v126
	v_min_f32_e32 v122, 0, v122
	v_mul_f32_e32 v122, 0x3fb8aa3b, v122
	v_cndmask_b32_e64 v147, 0, 1.0, s[0:1]
	v_cmp_gt_i32_e64 s[0:1], v126, v132
	v_exp_f32_e32 v136, v122
	v_sub_f32_e32 v122, v140, v150
	v_cndmask_b32_e64 v146, 1.0, 0, s[0:1]
	v_pk_mul_f32 v[146:147], v[116:117], v[146:147]
	v_sub_f32_e32 v116, v141, v150
	v_min_f32_e32 v122, 0, v122
	v_sub_f32_e32 v133, v137, v150
	v_min_f32_e32 v116, 0, v116
	v_mul_f32_e32 v122, 0x3fb8aa3b, v122
	v_or_b32_e32 v123, 5, v126
	v_min_f32_e32 v133, 0, v133
	v_mul_f32_e32 v116, 0x3fb8aa3b, v116
	v_exp_f32_e32 v140, v122
	v_or_b32_e32 v122, 4, v126
	v_mul_f32_e32 v133, 0x3fb8aa3b, v133
	v_exp_f32_e32 v141, v116
	v_cmp_gt_i32_e64 s[0:1], v123, v132
	v_exp_f32_e32 v137, v133
	v_sub_f32_e32 v133, v139, v150
	v_cndmask_b32_e64 v117, 1.0, 0, s[0:1]
	v_cmp_gt_i32_e64 s[0:1], v122, v132
	v_min_f32_e32 v133, 0, v133
	v_mul_f32_e32 v133, 0x3fb8aa3b, v133
	v_cndmask_b32_e64 v116, 1.0, 0, s[0:1]
	v_pk_mul_f32 v[112:113], v[112:113], v[116:117]
	v_or_b32_e32 v117, 3, v126
	v_pk_mul_f32 v[140:141], v[112:113], v[140:141]
	v_exp_f32_e32 v139, v133
	v_pk_fma_f32 v[112:113], v[146:147], v[136:137], v[140:141]
	v_sub_f32_e32 v133, v143, v150
	v_add_f32_e32 v112, v112, v127
	v_add_f32_e32 v127, v113, v112
	v_sub_f32_e32 v112, v138, v150
	v_min_f32_e32 v112, 0, v112
	v_mul_f32_e32 v112, 0x3fb8aa3b, v112
	v_exp_f32_e32 v138, v112
	v_sub_f32_e32 v112, v142, v150
	v_min_f32_e32 v112, 0, v112
	v_or_b32_e32 v116, 2, v126
	v_cmp_gt_i32_e64 s[0:1], v117, v132
	v_min_f32_e32 v133, 0, v133
	v_mul_f32_e32 v112, 0x3fb8aa3b, v112
	v_or_b32_e32 v113, 7, v126
	v_cndmask_b32_e64 v149, 1.0, 0, s[0:1]
	v_cmp_gt_i32_e64 s[0:1], v116, v132
	v_mul_f32_e32 v133, 0x3fb8aa3b, v133
	v_exp_f32_e32 v142, v112
	v_or_b32_e32 v112, 6, v126
	v_cndmask_b32_e64 v148, 1.0, 0, s[0:1]
	v_exp_f32_e32 v143, v133
	v_cmp_gt_i32_e64 s[0:1], v113, v132
	v_pk_mul_f32 v[118:119], v[118:119], v[148:149]
	s_nop 0
	v_cndmask_b32_e64 v149, 1.0, 0, s[0:1]
	v_cmp_gt_i32_e64 s[0:1], v112, v132
	s_nop 1
	v_cndmask_b32_e64 v148, 1.0, 0, s[0:1]
	v_pk_mul_f32 v[114:115], v[114:115], v[148:149]
	s_nop 0
	v_pk_mul_f32 v[142:143], v[114:115], v[142:143]
	s_nop 0
	v_pk_fma_f32 v[114:115], v[118:119], v[138:139], v[142:143]
	v_pk_mul_f32 v[118:119], v[118:119], v[138:139]
	v_add_f32_e32 v114, v114, v127
	v_add_f32_e32 v127, v115, v114
	ds_bpermute_b32 v133, v172, v127
	v_pk_mul_f32 v[114:115], v[146:147], v[136:137]
	v_cvt_pk_bf16_f32 v137, v118, v119
	v_cvt_pk_bf16_f32 v136, v114, v115
	v_cvt_pk_bf16_f32 v138, v140, v141
	s_waitcnt lgkmcnt(0)
	v_add_f32_e32 v115, v127, v133
	ds_bpermute_b32 v118, v173, v115
	v_cvt_pk_bf16_f32 v139, v142, v143
	v_lshl_add_u32 v114, v132, 2, s2
	global_store_dwordx4 v[144:145], v[136:139], off offset:256
	s_and_saveexec_b64 s[0:1], vcc
	s_cbranch_execz .LBB0_641
	s_waitcnt lgkmcnt(0)
	v_add_f32_e32 v115, v115, v118
	ds_write_b32 v114, v115
.LBB0_641:
	s_or_b64 exec, exec, s[0:1]
	s_waitcnt lgkmcnt(0)
	v_or_b32_e32 v118, 16, v132
	v_lshl_add_u32 v115, v118, 2, 0
	v_add_u32_e32 v115, 0x20000, v115
	ds_read_b32 v115, v115
	ds_read_b128 v[136:139], v134
	v_ashrrev_i32_e32 v119, 31, v118
	v_lshlrev_b64 v[140:141], 9, v[118:119]
	v_lshl_add_u64 v[144:145], s[26:27], 0, v[140:141]
	ds_read_b128 v[140:143], v134 offset:16
	s_waitcnt lgkmcnt(0)
	v_sub_f32_e32 v119, v136, v115
	v_min_f32_e32 v119, 0, v119
	v_mul_f32_e32 v119, 0x3fb8aa3b, v119
	v_exp_f32_e32 v136, v119
	v_sub_f32_e32 v119, v140, v115
	v_min_f32_e32 v119, 0, v119
	v_mul_f32_e32 v119, 0x3fb8aa3b, v119
	v_exp_f32_e32 v140, v119
	v_sub_f32_e32 v119, v137, v115
	v_min_f32_e32 v119, 0, v119
	v_mul_f32_e32 v119, 0x3fb8aa3b, v119
	v_exp_f32_e32 v137, v119
	v_sub_f32_e32 v119, v141, v115
	v_cmp_gt_i32_e64 s[0:1], v118, v128
	v_min_f32_e32 v119, 0, v119
	v_mul_f32_e32 v119, 0x3fb8aa3b, v119
	v_cndmask_b32_e64 v147, 0, 1.0, s[0:1]
	v_cmp_gt_i32_e64 s[0:1], v128, v118
	v_exp_f32_e32 v141, v119
	s_nop 0
	v_cndmask_b32_e64 v146, 1.0, 0, s[0:1]
	v_cmp_gt_i32_e64 s[0:1], v131, v118
	v_pk_mul_f32 v[108:109], v[108:109], v[146:147]
	s_nop 0
	v_cndmask_b32_e64 v149, 1.0, 0, s[0:1]
	v_cmp_gt_i32_e64 s[0:1], v124, v118
	v_pk_mul_f32 v[146:147], v[108:109], v[136:137]
	s_nop 0
	v_cndmask_b32_e64 v148, 1.0, 0, s[0:1]
	v_pk_mul_f32 v[104:105], v[104:105], v[148:149]
	v_cmp_gt_i32_e64 s[0:1], v125, v118
	v_pk_mul_f32 v[140:141], v[104:105], v[140:141]
	s_nop 0
	v_pk_fma_f32 v[104:105], v[108:109], v[136:137], v[140:141]
	v_cndmask_b32_e64 v137, 1.0, 0, s[0:1]
	v_add_f32_e32 v104, 0, v104
	v_add_f32_e32 v119, v105, v104
	v_sub_f32_e32 v104, v138, v115
	v_sub_f32_e32 v105, v139, v115
	v_min_f32_e32 v104, 0, v104
	v_min_f32_e32 v105, 0, v105
	v_mul_f32_e32 v104, 0x3fb8aa3b, v104
	v_mul_f32_e32 v105, 0x3fb8aa3b, v105
	v_exp_f32_e32 v108, v104
	v_sub_f32_e32 v104, v142, v115
	v_exp_f32_e32 v109, v105
	v_sub_f32_e32 v105, v143, v115
	v_min_f32_e32 v104, 0, v104
	v_min_f32_e32 v105, 0, v105
	v_mul_f32_e32 v104, 0x3fb8aa3b, v104
	v_cmp_gt_i32_e64 s[0:1], v130, v118
	v_mul_f32_e32 v105, 0x3fb8aa3b, v105
	v_exp_f32_e32 v104, v104
	v_cndmask_b32_e64 v136, 1.0, 0, s[0:1]
	v_exp_f32_e32 v105, v105
	v_cmp_gt_i32_e64 s[0:1], v121, v118
	v_pk_mul_f32 v[110:111], v[110:111], v[136:137]
	s_nop 0
	v_cndmask_b32_e64 v139, 1.0, 0, s[0:1]
	v_cmp_gt_i32_e64 s[0:1], v120, v118
	v_pk_mul_f32 v[136:137], v[110:111], v[108:109]
	s_nop 0
	v_cndmask_b32_e64 v138, 1.0, 0, s[0:1]
	v_pk_mul_f32 v[106:107], v[106:107], v[138:139]
	v_cmp_gt_i32_e64 s[0:1], v118, v126
	v_pk_mul_f32 v[138:139], v[106:107], v[104:105]
	v_cvt_pk_bf16_f32 v104, v146, v147
	v_cvt_pk_bf16_f32 v105, v136, v137
	v_cvt_pk_bf16_f32 v106, v140, v141
	v_cvt_pk_bf16_f32 v107, v138, v139
	v_lshl_add_u64 v[136:137], v[128:129], 1, v[144:145]
	v_pk_fma_f32 v[108:109], v[110:111], v[108:109], v[138:139]
	global_store_dwordx4 v[136:137], v[104:107], off
	v_add_f32_e32 v108, v108, v119
	ds_read_b128 v[104:107], v134 offset:512
	v_add_f32_e32 v119, v109, v108
	ds_read_b128 v[108:111], v134 offset:528
	v_cndmask_b32_e64 v139, 0, 1.0, s[0:1]
	v_cmp_gt_i32_e64 s[0:1], v126, v118
	s_waitcnt lgkmcnt(0)
	v_sub_f32_e32 v104, v104, v115
	v_sub_f32_e32 v105, v105, v115
	v_sub_f32_e32 v108, v108, v115
	v_sub_f32_e32 v109, v109, v115
	v_min_f32_e32 v108, 0, v108
	v_min_f32_e32 v109, 0, v109
	v_min_f32_e32 v104, 0, v104
	v_mul_f32_e32 v108, 0x3fb8aa3b, v108
	v_min_f32_e32 v105, 0, v105
	v_mul_f32_e32 v109, 0x3fb8aa3b, v109
	v_mul_f32_e32 v104, 0x3fb8aa3b, v104
	v_exp_f32_e32 v108, v108
	v_mul_f32_e32 v105, 0x3fb8aa3b, v105
	v_cndmask_b32_e64 v138, 1.0, 0, s[0:1]
	v_exp_f32_e32 v109, v109
	v_cmp_gt_i32_e64 s[0:1], v123, v118
	v_exp_f32_e32 v104, v104
	v_exp_f32_e32 v105, v105
	v_pk_mul_f32 v[100:101], v[100:101], v[138:139]
	v_cndmask_b32_e64 v139, 1.0, 0, s[0:1]
	v_cmp_gt_i32_e64 s[0:1], v122, v118
	s_nop 1
	v_cndmask_b32_e64 v138, 1.0, 0, s[0:1]
	v_pk_mul_f32 v[96:97], v[96:97], v[138:139]
	v_cmp_gt_i32_e64 s[0:1], v117, v118
	v_pk_mul_f32 v[108:109], v[96:97], v[108:109]
	s_nop 0
	v_pk_fma_f32 v[96:97], v[100:101], v[104:105], v[108:109]
	v_cndmask_b32_e64 v139, 1.0, 0, s[0:1]
	v_add_f32_e32 v96, v96, v119
	v_add_f32_e32 v119, v97, v96
	v_sub_f32_e32 v97, v110, v115
	v_min_f32_e32 v97, 0, v97
	v_mul_f32_e32 v97, 0x3fb8aa3b, v97
	v_sub_f32_e32 v96, v106, v115
	v_exp_f32_e32 v106, v97
	v_sub_f32_e32 v97, v107, v115
	v_sub_f32_e32 v107, v111, v115
	v_min_f32_e32 v107, 0, v107
	v_min_f32_e32 v96, 0, v96
	v_min_f32_e32 v97, 0, v97
	v_cmp_gt_i32_e64 s[0:1], v116, v118
	v_mul_f32_e32 v107, 0x3fb8aa3b, v107
	v_mul_f32_e32 v96, 0x3fb8aa3b, v96
	v_mul_f32_e32 v97, 0x3fb8aa3b, v97
	v_cndmask_b32_e64 v138, 1.0, 0, s[0:1]
	v_exp_f32_e32 v107, v107
	v_cmp_gt_i32_e64 s[0:1], v113, v118
	v_exp_f32_e32 v96, v96
	v_exp_f32_e32 v97, v97
	v_cndmask_b32_e64 v111, 1.0, 0, s[0:1]
	v_cmp_gt_i32_e64 s[0:1], v112, v118
	v_pk_mul_f32 v[102:103], v[102:103], v[138:139]
	s_nop 0
	v_cndmask_b32_e64 v110, 1.0, 0, s[0:1]
	v_pk_mul_f32 v[98:99], v[98:99], v[110:111]
	s_nop 0
	v_pk_mul_f32 v[106:107], v[98:99], v[106:107]
	s_nop 0
	v_pk_fma_f32 v[98:99], v[102:103], v[96:97], v[106:107]
	s_nop 0
	v_add_f32_e32 v98, v98, v119
	v_add_f32_e32 v110, v99, v98
	ds_bpermute_b32 v111, v172, v110
	v_pk_mul_f32 v[98:99], v[100:101], v[104:105]
	v_pk_mul_f32 v[100:101], v[102:103], v[96:97]
	v_cvt_pk_bf16_f32 v98, v98, v99
	v_cvt_pk_bf16_f32 v99, v100, v101
	s_waitcnt lgkmcnt(0)
	v_add_f32_e32 v96, v110, v111
	ds_bpermute_b32 v97, v173, v96
	v_cvt_pk_bf16_f32 v100, v108, v109
	v_cvt_pk_bf16_f32 v101, v106, v107
	global_store_dwordx4 v[136:137], v[98:101], off offset:256
	s_and_saveexec_b64 s[0:1], vcc
	s_cbranch_execz .LBB0_643
	s_waitcnt lgkmcnt(0)
	v_add_f32_e32 v96, v96, v97
	ds_write_b32 v114, v96 offset:64
.LBB0_643:
	s_or_b64 exec, exec, s[0:1]
	v_or_b32_e32 v104, 32, v132
	v_lshl_add_u32 v96, v104, 2, 0
	v_ashrrev_i32_e32 v105, 31, v104
	v_add_u32_e32 v96, 0x20000, v96
	v_lshlrev_b64 v[100:101], 9, v[104:105]
	ds_read_b32 v115, v96
	s_waitcnt lgkmcnt(0)
	ds_read_b128 v[96:99], v134
	v_lshl_add_u64 v[106:107], s[26:27], 0, v[100:101]
	ds_read_b128 v[100:103], v134 offset:16
	v_cmp_gt_i32_e64 s[0:1], v104, v128
	s_waitcnt lgkmcnt(0)
	v_sub_f32_e32 v96, v96, v115
	v_sub_f32_e32 v97, v97, v115
	v_sub_f32_e32 v100, v100, v115
	v_sub_f32_e32 v101, v101, v115
	v_min_f32_e32 v100, 0, v100
	v_min_f32_e32 v101, 0, v101
	v_min_f32_e32 v96, 0, v96
	v_mul_f32_e32 v100, 0x3fb8aa3b, v100
	v_min_f32_e32 v97, 0, v97
	v_cndmask_b32_e64 v109, 0, 1.0, s[0:1]
	v_cmp_gt_i32_e64 s[0:1], v128, v104
	v_mul_f32_e32 v101, 0x3fb8aa3b, v101
	v_mul_f32_e32 v96, 0x3fb8aa3b, v96
	v_exp_f32_e32 v100, v100
	v_mul_f32_e32 v97, 0x3fb8aa3b, v97
	v_cndmask_b32_e64 v108, 1.0, 0, s[0:1]
	v_exp_f32_e32 v101, v101
	v_cmp_gt_i32_e64 s[0:1], v131, v104
	v_exp_f32_e32 v96, v96
	v_exp_f32_e32 v97, v97
	v_cndmask_b32_e64 v111, 1.0, 0, s[0:1]
	v_cmp_gt_i32_e64 s[0:1], v124, v104
	v_pk_mul_f32 v[92:93], v[92:93], v[108:109]
	s_nop 0
	v_cndmask_b32_e64 v110, 1.0, 0, s[0:1]
	v_pk_mul_f32 v[88:89], v[88:89], v[110:111]
	v_pk_mul_f32 v[108:109], v[92:93], v[96:97]
	v_pk_mul_f32 v[100:101], v[88:89], v[100:101]
	v_cmp_gt_i32_e64 s[0:1], v125, v104
	v_pk_fma_f32 v[88:89], v[92:93], v[96:97], v[100:101]
	s_nop 0
	v_add_f32_e32 v88, 0, v88
	v_add_f32_e32 v105, v89, v88
	v_sub_f32_e32 v88, v98, v115
	v_sub_f32_e32 v89, v99, v115
	v_min_f32_e32 v88, 0, v88
	v_min_f32_e32 v89, 0, v89
	v_mul_f32_e32 v88, 0x3fb8aa3b, v88
	v_mul_f32_e32 v89, 0x3fb8aa3b, v89
	v_exp_f32_e32 v92, v88
	v_sub_f32_e32 v88, v102, v115
	v_exp_f32_e32 v93, v89
	v_sub_f32_e32 v89, v103, v115
	v_min_f32_e32 v88, 0, v88
	v_min_f32_e32 v89, 0, v89
	v_mul_f32_e32 v88, 0x3fb8aa3b, v88
	v_cndmask_b32_e64 v97, 1.0, 0, s[0:1]
	v_cmp_gt_i32_e64 s[0:1], v130, v104
	v_mul_f32_e32 v89, 0x3fb8aa3b, v89
	v_exp_f32_e32 v88, v88
	v_cndmask_b32_e64 v96, 1.0, 0, s[0:1]
	v_exp_f32_e32 v89, v89
	v_cmp_gt_i32_e64 s[0:1], v121, v104
	v_pk_mul_f32 v[94:95], v[94:95], v[96:97]
	s_nop 0
	v_cndmask_b32_e64 v99, 1.0, 0, s[0:1]
	v_cmp_gt_i32_e64 s[0:1], v120, v104
	v_pk_mul_f32 v[96:97], v[94:95], v[92:93]
	s_nop 0
	v_cndmask_b32_e64 v98, 1.0, 0, s[0:1]
	v_pk_mul_f32 v[90:91], v[90:91], v[98:99]
	v_cmp_gt_i32_e64 s[0:1], v104, v126
	v_pk_mul_f32 v[98:99], v[90:91], v[88:89]
	v_cvt_pk_bf16_f32 v88, v108, v109
	v_cvt_pk_bf16_f32 v89, v96, v97
	v_cvt_pk_bf16_f32 v90, v100, v101
	v_cvt_pk_bf16_f32 v91, v98, v99
	v_lshl_add_u64 v[96:97], v[128:129], 1, v[106:107]
	v_pk_fma_f32 v[92:93], v[94:95], v[92:93], v[98:99]
	global_store_dwordx4 v[96:97], v[88:91], off
	v_add_f32_e32 v92, v92, v105
	ds_read_b128 v[88:91], v134 offset:512
	v_add_f32_e32 v100, v93, v92
	ds_read_b128 v[92:95], v134 offset:528
	v_cndmask_b32_e64 v99, 0, 1.0, s[0:1]
	v_cmp_gt_i32_e64 s[0:1], v126, v104
	s_waitcnt lgkmcnt(0)
	v_sub_f32_e32 v88, v88, v115
	v_sub_f32_e32 v89, v89, v115
	v_sub_f32_e32 v92, v92, v115
	v_sub_f32_e32 v93, v93, v115
	v_min_f32_e32 v92, 0, v92
	v_min_f32_e32 v93, 0, v93
	v_min_f32_e32 v88, 0, v88
	v_mul_f32_e32 v92, 0x3fb8aa3b, v92
	v_min_f32_e32 v89, 0, v89
	v_mul_f32_e32 v93, 0x3fb8aa3b, v93
	v_mul_f32_e32 v88, 0x3fb8aa3b, v88
	v_exp_f32_e32 v92, v92
	v_mul_f32_e32 v89, 0x3fb8aa3b, v89
	v_cndmask_b32_e64 v98, 1.0, 0, s[0:1]
	v_exp_f32_e32 v93, v93
	v_cmp_gt_i32_e64 s[0:1], v123, v104
	v_exp_f32_e32 v88, v88
	v_exp_f32_e32 v89, v89
	v_pk_mul_f32 v[84:85], v[84:85], v[98:99]
	v_cndmask_b32_e64 v99, 1.0, 0, s[0:1]
	v_cmp_gt_i32_e64 s[0:1], v122, v104
	s_nop 1
	v_cndmask_b32_e64 v98, 1.0, 0, s[0:1]
	v_pk_mul_f32 v[80:81], v[80:81], v[98:99]
	v_cmp_gt_i32_e64 s[0:1], v117, v104
	v_pk_mul_f32 v[92:93], v[80:81], v[92:93]
	s_nop 0
	v_pk_fma_f32 v[80:81], v[84:85], v[88:89], v[92:93]
	v_cndmask_b32_e64 v99, 1.0, 0, s[0:1]
	v_add_f32_e32 v80, v80, v100
	v_add_f32_e32 v100, v81, v80
	v_sub_f32_e32 v81, v94, v115
	v_min_f32_e32 v81, 0, v81
	v_mul_f32_e32 v81, 0x3fb8aa3b, v81
	v_sub_f32_e32 v80, v90, v115
	v_exp_f32_e32 v90, v81
	v_sub_f32_e32 v81, v91, v115
	v_sub_f32_e32 v91, v95, v115
	v_min_f32_e32 v91, 0, v91
	v_min_f32_e32 v80, 0, v80
	v_min_f32_e32 v81, 0, v81
	v_cmp_gt_i32_e64 s[0:1], v116, v104
	v_mul_f32_e32 v91, 0x3fb8aa3b, v91
	v_mul_f32_e32 v80, 0x3fb8aa3b, v80
	v_mul_f32_e32 v81, 0x3fb8aa3b, v81
	v_cndmask_b32_e64 v98, 1.0, 0, s[0:1]
	v_exp_f32_e32 v91, v91
	v_cmp_gt_i32_e64 s[0:1], v113, v104
	v_exp_f32_e32 v80, v80
	v_exp_f32_e32 v81, v81
	v_cndmask_b32_e64 v95, 1.0, 0, s[0:1]
	v_cmp_gt_i32_e64 s[0:1], v112, v104
	v_pk_mul_f32 v[86:87], v[86:87], v[98:99]
	s_nop 0
	v_cndmask_b32_e64 v94, 1.0, 0, s[0:1]
	v_pk_mul_f32 v[82:83], v[82:83], v[94:95]
	s_nop 0
	v_pk_mul_f32 v[90:91], v[82:83], v[90:91]
	s_nop 0
	v_pk_fma_f32 v[82:83], v[86:87], v[80:81], v[90:91]
	s_nop 0
	v_add_f32_e32 v82, v82, v100
	v_add_f32_e32 v94, v83, v82
	ds_bpermute_b32 v95, v172, v94
	v_pk_mul_f32 v[82:83], v[84:85], v[88:89]
	v_pk_mul_f32 v[84:85], v[86:87], v[80:81]
	v_cvt_pk_bf16_f32 v82, v82, v83
	v_cvt_pk_bf16_f32 v83, v84, v85
	s_waitcnt lgkmcnt(0)
	v_add_f32_e32 v80, v94, v95
	ds_bpermute_b32 v81, v173, v80
	v_cvt_pk_bf16_f32 v84, v92, v93
	v_cvt_pk_bf16_f32 v85, v90, v91
	global_store_dwordx4 v[96:97], v[82:85], off offset:256
	s_and_saveexec_b64 s[0:1], vcc
	s_cbranch_execz .LBB0_645
	s_waitcnt lgkmcnt(0)
	v_add_f32_e32 v80, v80, v81
	ds_write_b32 v114, v80 offset:128
.LBB0_645:
	s_or_b64 exec, exec, s[0:1]
	v_or_b32_e32 v88, 48, v132
	v_lshl_add_u32 v80, v88, 2, 0
	v_ashrrev_i32_e32 v89, 31, v88
	v_add_u32_e32 v80, 0x20000, v80
	v_lshlrev_b64 v[84:85], 9, v[88:89]
	ds_read_b32 v96, v80
	s_waitcnt lgkmcnt(0)
	ds_read_b128 v[80:83], v134
	v_lshl_add_u64 v[90:91], s[26:27], 0, v[84:85]
	ds_read_b128 v[84:87], v134 offset:16
	v_cmp_gt_i32_e64 s[0:1], v88, v128
	s_waitcnt lgkmcnt(0)
	v_sub_f32_e32 v80, v80, v96
	v_sub_f32_e32 v81, v81, v96
	v_sub_f32_e32 v84, v84, v96
	v_sub_f32_e32 v85, v85, v96
	v_min_f32_e32 v84, 0, v84
	v_min_f32_e32 v85, 0, v85
	v_min_f32_e32 v80, 0, v80
	v_mul_f32_e32 v84, 0x3fb8aa3b, v84
	v_min_f32_e32 v81, 0, v81
	v_cndmask_b32_e64 v93, 0, 1.0, s[0:1]
	v_cmp_gt_i32_e64 s[0:1], v128, v88
	v_mul_f32_e32 v85, 0x3fb8aa3b, v85
	v_mul_f32_e32 v80, 0x3fb8aa3b, v80
	v_exp_f32_e32 v84, v84
	v_mul_f32_e32 v81, 0x3fb8aa3b, v81
	v_cndmask_b32_e64 v92, 1.0, 0, s[0:1]
	v_exp_f32_e32 v85, v85
	v_cmp_gt_i32_e64 s[0:1], v131, v88
	v_exp_f32_e32 v80, v80
	v_exp_f32_e32 v81, v81
	v_cndmask_b32_e64 v95, 1.0, 0, s[0:1]
	v_cmp_gt_i32_e64 s[0:1], v124, v88
	v_pk_mul_f32 v[76:77], v[76:77], v[92:93]
	s_nop 0
	v_cndmask_b32_e64 v94, 1.0, 0, s[0:1]
	v_pk_mul_f32 v[72:73], v[72:73], v[94:95]
	v_pk_mul_f32 v[92:93], v[76:77], v[80:81]
	v_pk_mul_f32 v[84:85], v[72:73], v[84:85]
	v_cmp_gt_i32_e64 s[0:1], v125, v88
	v_pk_fma_f32 v[72:73], v[76:77], v[80:81], v[84:85]
	s_nop 0
	v_add_f32_e32 v72, 0, v72
	v_add_f32_e32 v89, v73, v72
	v_sub_f32_e32 v72, v82, v96
	v_sub_f32_e32 v73, v83, v96
	v_min_f32_e32 v72, 0, v72
	v_min_f32_e32 v73, 0, v73
	v_mul_f32_e32 v72, 0x3fb8aa3b, v72
	v_mul_f32_e32 v73, 0x3fb8aa3b, v73
	v_exp_f32_e32 v76, v72
	v_sub_f32_e32 v72, v86, v96
	v_exp_f32_e32 v77, v73
	v_sub_f32_e32 v73, v87, v96
	v_min_f32_e32 v72, 0, v72
	v_min_f32_e32 v73, 0, v73
	v_mul_f32_e32 v72, 0x3fb8aa3b, v72
	v_cndmask_b32_e64 v81, 1.0, 0, s[0:1]
	v_cmp_gt_i32_e64 s[0:1], v130, v88
	v_mul_f32_e32 v73, 0x3fb8aa3b, v73
	v_exp_f32_e32 v72, v72
	v_cndmask_b32_e64 v80, 1.0, 0, s[0:1]
	v_exp_f32_e32 v73, v73
	v_cmp_gt_i32_e64 s[0:1], v121, v88
	v_pk_mul_f32 v[78:79], v[78:79], v[80:81]
	s_nop 0
	v_cndmask_b32_e64 v83, 1.0, 0, s[0:1]
	v_cmp_gt_i32_e64 s[0:1], v120, v88
	v_pk_mul_f32 v[80:81], v[78:79], v[76:77]
	s_nop 0
	v_cndmask_b32_e64 v82, 1.0, 0, s[0:1]
	v_pk_mul_f32 v[74:75], v[74:75], v[82:83]
	v_cmp_gt_i32_e64 s[0:1], v88, v126
	v_pk_mul_f32 v[82:83], v[74:75], v[72:73]
	v_cvt_pk_bf16_f32 v72, v92, v93
	v_cvt_pk_bf16_f32 v73, v80, v81
	v_cvt_pk_bf16_f32 v74, v84, v85
	v_cvt_pk_bf16_f32 v75, v82, v83
	v_lshl_add_u64 v[80:81], v[128:129], 1, v[90:91]
	v_pk_fma_f32 v[76:77], v[78:79], v[76:77], v[82:83]
	global_store_dwordx4 v[80:81], v[72:75], off
	v_add_f32_e32 v76, v76, v89
	ds_read_b128 v[72:75], v134 offset:512
	v_add_f32_e32 v84, v77, v76
	ds_read_b128 v[76:79], v134 offset:528
	v_cndmask_b32_e64 v83, 0, 1.0, s[0:1]
	v_cmp_gt_i32_e64 s[0:1], v126, v88
	s_waitcnt lgkmcnt(0)
	v_sub_f32_e32 v72, v72, v96
	v_sub_f32_e32 v73, v73, v96
	v_sub_f32_e32 v76, v76, v96
	v_sub_f32_e32 v77, v77, v96
	v_min_f32_e32 v76, 0, v76
	v_min_f32_e32 v77, 0, v77
	v_min_f32_e32 v72, 0, v72
	v_mul_f32_e32 v76, 0x3fb8aa3b, v76
	v_min_f32_e32 v73, 0, v73
	v_mul_f32_e32 v77, 0x3fb8aa3b, v77
	v_mul_f32_e32 v72, 0x3fb8aa3b, v72
	v_exp_f32_e32 v76, v76
	v_mul_f32_e32 v73, 0x3fb8aa3b, v73
	v_cndmask_b32_e64 v82, 1.0, 0, s[0:1]
	v_exp_f32_e32 v77, v77
	v_cmp_gt_i32_e64 s[0:1], v123, v88
	v_exp_f32_e32 v72, v72
	v_exp_f32_e32 v73, v73
	v_pk_mul_f32 v[68:69], v[68:69], v[82:83]
	v_cndmask_b32_e64 v83, 1.0, 0, s[0:1]
	v_cmp_gt_i32_e64 s[0:1], v122, v88
	s_nop 1
	v_cndmask_b32_e64 v82, 1.0, 0, s[0:1]
	v_pk_mul_f32 v[64:65], v[64:65], v[82:83]
	v_cmp_gt_i32_e64 s[0:1], v117, v88
	v_pk_mul_f32 v[76:77], v[64:65], v[76:77]
	s_nop 0
	v_pk_fma_f32 v[64:65], v[68:69], v[72:73], v[76:77]
	v_cndmask_b32_e64 v83, 1.0, 0, s[0:1]
	v_add_f32_e32 v64, v64, v84
	v_add_f32_e32 v84, v65, v64
	v_sub_f32_e32 v65, v78, v96
	v_min_f32_e32 v65, 0, v65
	v_mul_f32_e32 v65, 0x3fb8aa3b, v65
	v_sub_f32_e32 v64, v74, v96
	v_exp_f32_e32 v74, v65
	v_sub_f32_e32 v65, v75, v96
	v_sub_f32_e32 v75, v79, v96
	v_min_f32_e32 v75, 0, v75
	v_min_f32_e32 v64, 0, v64
	v_min_f32_e32 v65, 0, v65
	v_cmp_gt_i32_e64 s[0:1], v116, v88
	v_mul_f32_e32 v75, 0x3fb8aa3b, v75
	v_mul_f32_e32 v64, 0x3fb8aa3b, v64
	v_mul_f32_e32 v65, 0x3fb8aa3b, v65
	v_cndmask_b32_e64 v82, 1.0, 0, s[0:1]
	v_exp_f32_e32 v75, v75
	v_cmp_gt_i32_e64 s[0:1], v113, v88
	v_exp_f32_e32 v64, v64
	v_exp_f32_e32 v65, v65
	v_cndmask_b32_e64 v79, 1.0, 0, s[0:1]
	v_cmp_gt_i32_e64 s[0:1], v112, v88
	v_pk_mul_f32 v[70:71], v[70:71], v[82:83]
	s_nop 0
	v_cndmask_b32_e64 v78, 1.0, 0, s[0:1]
	v_pk_mul_f32 v[66:67], v[66:67], v[78:79]
	s_nop 0
	v_pk_mul_f32 v[74:75], v[66:67], v[74:75]
	s_nop 0
	v_pk_fma_f32 v[66:67], v[70:71], v[64:65], v[74:75]
	s_nop 0
	v_add_f32_e32 v66, v66, v84
	v_add_f32_e32 v78, v67, v66
	ds_bpermute_b32 v79, v172, v78
	v_pk_mul_f32 v[66:67], v[68:69], v[72:73]
	v_pk_mul_f32 v[68:69], v[70:71], v[64:65]
	v_cvt_pk_bf16_f32 v66, v66, v67
	v_cvt_pk_bf16_f32 v67, v68, v69
	s_waitcnt lgkmcnt(0)
	v_add_f32_e32 v64, v78, v79
	ds_bpermute_b32 v65, v173, v64
	v_cvt_pk_bf16_f32 v68, v76, v77
	v_cvt_pk_bf16_f32 v69, v74, v75
	global_store_dwordx4 v[80:81], v[66:69], off offset:256
	s_and_saveexec_b64 s[0:1], vcc
	s_cbranch_execz .LBB0_647
	s_waitcnt lgkmcnt(0)
	v_add_f32_e32 v64, v64, v65
	ds_write_b32 v114, v64 offset:192
.LBB0_647:
	s_or_b64 exec, exec, s[0:1]
	v_add_u32_e32 v64, 0x80, v132
	ds_read_b32 v80, v135 offset:512
	ds_read_b128 v[66:69], v134
	s_waitcnt lgkmcnt(0)
	v_ashrrev_i32_e32 v65, 31, v64
	v_lshlrev_b64 v[70:71], 9, v[64:65]
	v_lshl_add_u64 v[74:75], s[26:27], 0, v[70:71]
	ds_read_b128 v[70:73], v134 offset:16
	v_sub_f32_e32 v65, v66, v80
	v_min_f32_e32 v65, 0, v65
	v_mul_f32_e32 v65, 0x3fb8aa3b, v65
	v_exp_f32_e32 v66, v65
	s_waitcnt lgkmcnt(0)
	v_sub_f32_e32 v65, v70, v80
	v_min_f32_e32 v65, 0, v65
	v_mul_f32_e32 v65, 0x3fb8aa3b, v65
	v_exp_f32_e32 v70, v65
	v_sub_f32_e32 v65, v67, v80
	v_min_f32_e32 v65, 0, v65
	v_mul_f32_e32 v65, 0x3fb8aa3b, v65
	v_exp_f32_e32 v67, v65
	v_sub_f32_e32 v65, v71, v80
	v_cmp_gt_i32_e64 s[0:1], v64, v128
	v_min_f32_e32 v65, 0, v65
	v_mul_f32_e32 v65, 0x3fb8aa3b, v65
	v_cndmask_b32_e64 v77, 0, 1.0, s[0:1]
	v_cmp_gt_i32_e64 s[0:1], v128, v64
	v_exp_f32_e32 v71, v65
	s_nop 0
	v_cndmask_b32_e64 v76, 1.0, 0, s[0:1]
	v_cmp_gt_i32_e64 s[0:1], v131, v64
	v_pk_mul_f32 v[60:61], v[60:61], v[76:77]
	s_nop 0
	v_cndmask_b32_e64 v79, 1.0, 0, s[0:1]
	v_cmp_gt_i32_e64 s[0:1], v124, v64
	v_pk_mul_f32 v[76:77], v[60:61], v[66:67]
	s_nop 0
	v_cndmask_b32_e64 v78, 1.0, 0, s[0:1]
	v_pk_mul_f32 v[56:57], v[56:57], v[78:79]
	v_cmp_gt_i32_e64 s[0:1], v125, v64
	v_pk_mul_f32 v[70:71], v[56:57], v[70:71]
	s_nop 0
	v_pk_fma_f32 v[56:57], v[60:61], v[66:67], v[70:71]
	v_cndmask_b32_e64 v67, 1.0, 0, s[0:1]
	v_add_f32_e32 v56, 0, v56
	v_add_f32_e32 v65, v57, v56
	v_sub_f32_e32 v56, v68, v80
	v_sub_f32_e32 v57, v69, v80
	v_min_f32_e32 v56, 0, v56
	v_min_f32_e32 v57, 0, v57
	v_mul_f32_e32 v56, 0x3fb8aa3b, v56
	v_mul_f32_e32 v57, 0x3fb8aa3b, v57
	v_exp_f32_e32 v60, v56
	v_sub_f32_e32 v56, v72, v80
	v_exp_f32_e32 v61, v57
	v_sub_f32_e32 v57, v73, v80
	v_min_f32_e32 v56, 0, v56
	v_min_f32_e32 v57, 0, v57
	v_mul_f32_e32 v56, 0x3fb8aa3b, v56
	v_cmp_gt_i32_e64 s[0:1], v130, v64
	v_mul_f32_e32 v57, 0x3fb8aa3b, v57
	v_exp_f32_e32 v56, v56
	v_cndmask_b32_e64 v66, 1.0, 0, s[0:1]
	v_exp_f32_e32 v57, v57
	v_cmp_gt_i32_e64 s[0:1], v121, v64
	v_pk_mul_f32 v[62:63], v[62:63], v[66:67]
	s_nop 0
	v_cndmask_b32_e64 v69, 1.0, 0, s[0:1]
	v_cmp_gt_i32_e64 s[0:1], v120, v64
	v_pk_mul_f32 v[66:67], v[62:63], v[60:61]
	s_nop 0
	v_cndmask_b32_e64 v68, 1.0, 0, s[0:1]
	v_pk_mul_f32 v[58:59], v[58:59], v[68:69]
	v_cmp_gt_i32_e64 s[0:1], v64, v126
	v_pk_mul_f32 v[68:69], v[58:59], v[56:57]
	v_cvt_pk_bf16_f32 v56, v76, v77
	v_cvt_pk_bf16_f32 v57, v66, v67
	v_cvt_pk_bf16_f32 v58, v70, v71
	v_cvt_pk_bf16_f32 v59, v68, v69
	v_lshl_add_u64 v[66:67], v[128:129], 1, v[74:75]
	v_pk_fma_f32 v[60:61], v[62:63], v[60:61], v[68:69]
	global_store_dwordx4 v[66:67], v[56:59], off
	v_add_f32_e32 v60, v60, v65
	ds_read_b128 v[56:59], v134 offset:512
	v_add_f32_e32 v65, v61, v60
	ds_read_b128 v[60:63], v134 offset:528
	v_cndmask_b32_e64 v69, 0, 1.0, s[0:1]
	v_cmp_gt_i32_e64 s[0:1], v126, v64
	s_waitcnt lgkmcnt(0)
	v_sub_f32_e32 v56, v56, v80
	v_sub_f32_e32 v57, v57, v80
	v_sub_f32_e32 v60, v60, v80
	v_sub_f32_e32 v61, v61, v80
	v_min_f32_e32 v60, 0, v60
	v_min_f32_e32 v61, 0, v61
	v_min_f32_e32 v56, 0, v56
	v_mul_f32_e32 v60, 0x3fb8aa3b, v60
	v_min_f32_e32 v57, 0, v57
	v_mul_f32_e32 v61, 0x3fb8aa3b, v61
	v_mul_f32_e32 v56, 0x3fb8aa3b, v56
	v_exp_f32_e32 v60, v60
	v_mul_f32_e32 v57, 0x3fb8aa3b, v57
	v_cndmask_b32_e64 v68, 1.0, 0, s[0:1]
	v_exp_f32_e32 v61, v61
	v_cmp_gt_i32_e64 s[0:1], v123, v64
	v_exp_f32_e32 v56, v56
	v_exp_f32_e32 v57, v57
	v_pk_mul_f32 v[52:53], v[52:53], v[68:69]
	v_cndmask_b32_e64 v69, 1.0, 0, s[0:1]
	v_cmp_gt_i32_e64 s[0:1], v122, v64
	s_nop 1
	v_cndmask_b32_e64 v68, 1.0, 0, s[0:1]
	v_pk_mul_f32 v[48:49], v[48:49], v[68:69]
	v_cmp_gt_i32_e64 s[0:1], v117, v64
	v_pk_mul_f32 v[60:61], v[48:49], v[60:61]
	s_nop 0
	v_pk_fma_f32 v[48:49], v[52:53], v[56:57], v[60:61]
	v_cndmask_b32_e64 v69, 1.0, 0, s[0:1]
	v_add_f32_e32 v48, v48, v65
	v_add_f32_e32 v65, v49, v48
	v_sub_f32_e32 v49, v62, v80
	v_min_f32_e32 v49, 0, v49
	v_mul_f32_e32 v49, 0x3fb8aa3b, v49
	v_sub_f32_e32 v48, v58, v80
	v_exp_f32_e32 v58, v49
	v_sub_f32_e32 v49, v59, v80
	v_sub_f32_e32 v59, v63, v80
	v_min_f32_e32 v59, 0, v59
	v_min_f32_e32 v48, 0, v48
	v_min_f32_e32 v49, 0, v49
	v_cmp_gt_i32_e64 s[0:1], v116, v64
	v_mul_f32_e32 v59, 0x3fb8aa3b, v59
	v_mul_f32_e32 v48, 0x3fb8aa3b, v48
	v_mul_f32_e32 v49, 0x3fb8aa3b, v49
	v_cndmask_b32_e64 v68, 1.0, 0, s[0:1]
	v_exp_f32_e32 v59, v59
	v_cmp_gt_i32_e64 s[0:1], v113, v64
	v_exp_f32_e32 v48, v48
	v_exp_f32_e32 v49, v49
	v_cndmask_b32_e64 v63, 1.0, 0, s[0:1]
	v_cmp_gt_i32_e64 s[0:1], v112, v64
	v_pk_mul_f32 v[54:55], v[54:55], v[68:69]
	s_nop 0
	v_cndmask_b32_e64 v62, 1.0, 0, s[0:1]
	v_pk_mul_f32 v[50:51], v[50:51], v[62:63]
	s_nop 0
	v_pk_mul_f32 v[58:59], v[50:51], v[58:59]
	s_nop 0
	v_pk_fma_f32 v[50:51], v[54:55], v[48:49], v[58:59]
	s_nop 0
	v_add_f32_e32 v50, v50, v65
	v_add_f32_e32 v62, v51, v50
	ds_bpermute_b32 v63, v172, v62
	v_pk_mul_f32 v[50:51], v[52:53], v[56:57]
	v_pk_mul_f32 v[52:53], v[54:55], v[48:49]
	v_cvt_pk_bf16_f32 v50, v50, v51
	v_cvt_pk_bf16_f32 v51, v52, v53
	s_waitcnt lgkmcnt(0)
	v_add_f32_e32 v48, v62, v63
	ds_bpermute_b32 v49, v173, v48
	v_cvt_pk_bf16_f32 v52, v60, v61
	v_cvt_pk_bf16_f32 v53, v58, v59
	global_store_dwordx4 v[66:67], v[50:53], off offset:256
	s_and_saveexec_b64 s[0:1], vcc
	s_cbranch_execz .LBB0_649
	s_waitcnt lgkmcnt(0)
	v_add_f32_e32 v48, v48, v49
	ds_write_b32 v114, v48 offset:512
.LBB0_649:
	s_or_b64 exec, exec, s[0:1]
	v_or_b32_e32 v56, 16, v64
	v_lshl_add_u32 v48, v56, 2, 0
	v_ashrrev_i32_e32 v57, 31, v56
	v_add_u32_e32 v48, 0x20000, v48
	v_lshlrev_b64 v[52:53], 9, v[56:57]
	ds_read_b32 v65, v48
	s_waitcnt lgkmcnt(0)
	ds_read_b128 v[48:51], v134
	v_lshl_add_u64 v[58:59], s[26:27], 0, v[52:53]
	ds_read_b128 v[52:55], v134 offset:16
	v_cmp_gt_i32_e64 s[0:1], v56, v128
	s_waitcnt lgkmcnt(0)
	v_sub_f32_e32 v48, v48, v65
	v_sub_f32_e32 v49, v49, v65
	v_sub_f32_e32 v52, v52, v65
	v_sub_f32_e32 v53, v53, v65
	v_min_f32_e32 v52, 0, v52
	v_min_f32_e32 v53, 0, v53
	v_min_f32_e32 v48, 0, v48
	v_mul_f32_e32 v52, 0x3fb8aa3b, v52
	v_min_f32_e32 v49, 0, v49
	v_cndmask_b32_e64 v61, 0, 1.0, s[0:1]
	v_cmp_gt_i32_e64 s[0:1], v128, v56
	v_mul_f32_e32 v53, 0x3fb8aa3b, v53
	v_mul_f32_e32 v48, 0x3fb8aa3b, v48
	v_exp_f32_e32 v52, v52
	v_mul_f32_e32 v49, 0x3fb8aa3b, v49
	v_cndmask_b32_e64 v60, 1.0, 0, s[0:1]
	v_exp_f32_e32 v53, v53
	v_cmp_gt_i32_e64 s[0:1], v131, v56
	v_exp_f32_e32 v48, v48
	v_exp_f32_e32 v49, v49
	v_cndmask_b32_e64 v63, 1.0, 0, s[0:1]
	v_cmp_gt_i32_e64 s[0:1], v124, v56
	v_pk_mul_f32 v[44:45], v[44:45], v[60:61]
	s_nop 0
	v_cndmask_b32_e64 v62, 1.0, 0, s[0:1]
	v_pk_mul_f32 v[40:41], v[40:41], v[62:63]
	v_pk_mul_f32 v[60:61], v[44:45], v[48:49]
	v_pk_mul_f32 v[52:53], v[40:41], v[52:53]
	v_cmp_gt_i32_e64 s[0:1], v125, v56
	v_pk_fma_f32 v[40:41], v[44:45], v[48:49], v[52:53]
	s_nop 0
	v_add_f32_e32 v40, 0, v40
	v_add_f32_e32 v57, v41, v40
	v_sub_f32_e32 v40, v50, v65
	v_sub_f32_e32 v41, v51, v65
	v_min_f32_e32 v40, 0, v40
	v_min_f32_e32 v41, 0, v41
	v_mul_f32_e32 v40, 0x3fb8aa3b, v40
	v_mul_f32_e32 v41, 0x3fb8aa3b, v41
	v_exp_f32_e32 v44, v40
	v_sub_f32_e32 v40, v54, v65
	v_exp_f32_e32 v45, v41
	v_sub_f32_e32 v41, v55, v65
	v_min_f32_e32 v40, 0, v40
	v_min_f32_e32 v41, 0, v41
	v_mul_f32_e32 v40, 0x3fb8aa3b, v40
	v_cndmask_b32_e64 v49, 1.0, 0, s[0:1]
	v_cmp_gt_i32_e64 s[0:1], v130, v56
	v_mul_f32_e32 v41, 0x3fb8aa3b, v41
	v_exp_f32_e32 v40, v40
	v_cndmask_b32_e64 v48, 1.0, 0, s[0:1]
	v_exp_f32_e32 v41, v41
	v_cmp_gt_i32_e64 s[0:1], v121, v56
	v_pk_mul_f32 v[46:47], v[46:47], v[48:49]
	s_nop 0
	v_cndmask_b32_e64 v51, 1.0, 0, s[0:1]
	v_cmp_gt_i32_e64 s[0:1], v120, v56
	v_pk_mul_f32 v[48:49], v[46:47], v[44:45]
	s_nop 0
	v_cndmask_b32_e64 v50, 1.0, 0, s[0:1]
	v_pk_mul_f32 v[42:43], v[42:43], v[50:51]
	v_cmp_gt_i32_e64 s[0:1], v56, v126
	v_pk_mul_f32 v[50:51], v[42:43], v[40:41]
	v_cvt_pk_bf16_f32 v40, v60, v61
	v_cvt_pk_bf16_f32 v41, v48, v49
	v_cvt_pk_bf16_f32 v42, v52, v53
	v_cvt_pk_bf16_f32 v43, v50, v51
	v_lshl_add_u64 v[48:49], v[128:129], 1, v[58:59]
	v_pk_fma_f32 v[44:45], v[46:47], v[44:45], v[50:51]
	global_store_dwordx4 v[48:49], v[40:43], off
	v_add_f32_e32 v44, v44, v57
	ds_read_b128 v[40:43], v134 offset:512
	v_add_f32_e32 v52, v45, v44
	ds_read_b128 v[44:47], v134 offset:528
	v_cndmask_b32_e64 v51, 0, 1.0, s[0:1]
	v_cmp_gt_i32_e64 s[0:1], v126, v56
	s_waitcnt lgkmcnt(0)
	v_sub_f32_e32 v40, v40, v65
	v_sub_f32_e32 v41, v41, v65
	v_sub_f32_e32 v44, v44, v65
	v_sub_f32_e32 v45, v45, v65
	v_min_f32_e32 v44, 0, v44
	v_min_f32_e32 v45, 0, v45
	v_min_f32_e32 v40, 0, v40
	v_mul_f32_e32 v44, 0x3fb8aa3b, v44
	v_min_f32_e32 v41, 0, v41
	v_mul_f32_e32 v45, 0x3fb8aa3b, v45
	v_mul_f32_e32 v40, 0x3fb8aa3b, v40
	v_exp_f32_e32 v44, v44
	v_mul_f32_e32 v41, 0x3fb8aa3b, v41
	v_cndmask_b32_e64 v50, 1.0, 0, s[0:1]
	v_exp_f32_e32 v45, v45
	v_cmp_gt_i32_e64 s[0:1], v123, v56
	v_exp_f32_e32 v40, v40
	v_exp_f32_e32 v41, v41
	v_pk_mul_f32 v[36:37], v[36:37], v[50:51]
	v_cndmask_b32_e64 v51, 1.0, 0, s[0:1]
	v_cmp_gt_i32_e64 s[0:1], v122, v56
	s_nop 1
	v_cndmask_b32_e64 v50, 1.0, 0, s[0:1]
	v_pk_mul_f32 v[32:33], v[32:33], v[50:51]
	v_cmp_gt_i32_e64 s[0:1], v117, v56
	v_pk_mul_f32 v[44:45], v[32:33], v[44:45]
	s_nop 0
	v_pk_fma_f32 v[32:33], v[36:37], v[40:41], v[44:45]
	v_cndmask_b32_e64 v51, 1.0, 0, s[0:1]
	v_add_f32_e32 v32, v32, v52
	v_add_f32_e32 v52, v33, v32
	v_sub_f32_e32 v33, v46, v65
	v_min_f32_e32 v33, 0, v33
	v_mul_f32_e32 v33, 0x3fb8aa3b, v33
	v_sub_f32_e32 v32, v42, v65
	v_exp_f32_e32 v42, v33
	v_sub_f32_e32 v33, v43, v65
	v_sub_f32_e32 v43, v47, v65
	v_min_f32_e32 v43, 0, v43
	v_min_f32_e32 v32, 0, v32
	v_min_f32_e32 v33, 0, v33
	v_cmp_gt_i32_e64 s[0:1], v116, v56
	v_mul_f32_e32 v43, 0x3fb8aa3b, v43
	v_mul_f32_e32 v32, 0x3fb8aa3b, v32
	v_mul_f32_e32 v33, 0x3fb8aa3b, v33
	v_cndmask_b32_e64 v50, 1.0, 0, s[0:1]
	v_exp_f32_e32 v43, v43
	v_cmp_gt_i32_e64 s[0:1], v113, v56
	v_exp_f32_e32 v32, v32
	v_exp_f32_e32 v33, v33
	v_cndmask_b32_e64 v47, 1.0, 0, s[0:1]
	v_cmp_gt_i32_e64 s[0:1], v112, v56
	v_pk_mul_f32 v[38:39], v[38:39], v[50:51]
	s_nop 0
	v_cndmask_b32_e64 v46, 1.0, 0, s[0:1]
	v_pk_mul_f32 v[34:35], v[34:35], v[46:47]
	s_nop 0
	v_pk_mul_f32 v[42:43], v[34:35], v[42:43]
	s_nop 0
	v_pk_fma_f32 v[34:35], v[38:39], v[32:33], v[42:43]
	s_nop 0
	v_add_f32_e32 v34, v34, v52
	v_add_f32_e32 v46, v35, v34
	ds_bpermute_b32 v47, v172, v46
	v_pk_mul_f32 v[34:35], v[36:37], v[40:41]
	v_pk_mul_f32 v[36:37], v[38:39], v[32:33]
	v_cvt_pk_bf16_f32 v34, v34, v35
	v_cvt_pk_bf16_f32 v35, v36, v37
	s_waitcnt lgkmcnt(0)
	v_add_f32_e32 v32, v46, v47
	ds_bpermute_b32 v33, v173, v32
	v_cvt_pk_bf16_f32 v36, v44, v45
	v_cvt_pk_bf16_f32 v37, v42, v43
	global_store_dwordx4 v[48:49], v[34:37], off offset:256
	s_and_saveexec_b64 s[0:1], vcc
	s_cbranch_execz .LBB0_651
	s_waitcnt lgkmcnt(0)
	v_add_f32_e32 v32, v32, v33
	ds_write_b32 v114, v32 offset:576
.LBB0_651:
	s_or_b64 exec, exec, s[0:1]
	v_or_b32_e32 v40, 32, v64
	v_lshl_add_u32 v32, v40, 2, 0
	v_ashrrev_i32_e32 v41, 31, v40
	v_add_u32_e32 v32, 0x20000, v32
	v_lshlrev_b64 v[36:37], 9, v[40:41]
	ds_read_b32 v48, v32
	s_waitcnt lgkmcnt(0)
	ds_read_b128 v[32:35], v134
	v_lshl_add_u64 v[42:43], s[26:27], 0, v[36:37]
	ds_read_b128 v[36:39], v134 offset:16
	v_cmp_gt_i32_e64 s[0:1], v40, v128
	s_waitcnt lgkmcnt(0)
	v_sub_f32_e32 v32, v32, v48
	v_sub_f32_e32 v33, v33, v48
	v_sub_f32_e32 v36, v36, v48
	v_sub_f32_e32 v37, v37, v48
	v_min_f32_e32 v36, 0, v36
	v_min_f32_e32 v37, 0, v37
	v_min_f32_e32 v32, 0, v32
	v_mul_f32_e32 v36, 0x3fb8aa3b, v36
	v_min_f32_e32 v33, 0, v33
	v_cndmask_b32_e64 v45, 0, 1.0, s[0:1]
	v_cmp_gt_i32_e64 s[0:1], v128, v40
	v_mul_f32_e32 v37, 0x3fb8aa3b, v37
	v_mul_f32_e32 v32, 0x3fb8aa3b, v32
	v_exp_f32_e32 v36, v36
	v_mul_f32_e32 v33, 0x3fb8aa3b, v33
	v_cndmask_b32_e64 v44, 1.0, 0, s[0:1]
	v_exp_f32_e32 v37, v37
	v_cmp_gt_i32_e64 s[0:1], v131, v40
	v_exp_f32_e32 v32, v32
	v_exp_f32_e32 v33, v33
	v_cndmask_b32_e64 v47, 1.0, 0, s[0:1]
	v_cmp_gt_i32_e64 s[0:1], v124, v40
	v_pk_mul_f32 v[28:29], v[28:29], v[44:45]
	s_nop 0
	v_cndmask_b32_e64 v46, 1.0, 0, s[0:1]
	v_pk_mul_f32 v[24:25], v[24:25], v[46:47]
	v_pk_mul_f32 v[44:45], v[28:29], v[32:33]
	v_pk_mul_f32 v[36:37], v[24:25], v[36:37]
	v_cmp_gt_i32_e64 s[0:1], v125, v40
	v_pk_fma_f32 v[24:25], v[28:29], v[32:33], v[36:37]
	s_nop 0
	v_add_f32_e32 v24, 0, v24
	v_add_f32_e32 v41, v25, v24
	v_sub_f32_e32 v24, v34, v48
	v_sub_f32_e32 v25, v35, v48
	v_min_f32_e32 v24, 0, v24
	v_min_f32_e32 v25, 0, v25
	v_mul_f32_e32 v24, 0x3fb8aa3b, v24
	v_mul_f32_e32 v25, 0x3fb8aa3b, v25
	v_exp_f32_e32 v28, v24
	v_sub_f32_e32 v24, v38, v48
	v_exp_f32_e32 v29, v25
	v_sub_f32_e32 v25, v39, v48
	v_min_f32_e32 v24, 0, v24
	v_min_f32_e32 v25, 0, v25
	v_mul_f32_e32 v24, 0x3fb8aa3b, v24
	v_cndmask_b32_e64 v33, 1.0, 0, s[0:1]
	v_cmp_gt_i32_e64 s[0:1], v130, v40
	v_mul_f32_e32 v25, 0x3fb8aa3b, v25
	v_exp_f32_e32 v24, v24
	v_cndmask_b32_e64 v32, 1.0, 0, s[0:1]
	v_exp_f32_e32 v25, v25
	v_cmp_gt_i32_e64 s[0:1], v121, v40
	v_pk_mul_f32 v[30:31], v[30:31], v[32:33]
	s_nop 0
	v_cndmask_b32_e64 v35, 1.0, 0, s[0:1]
	v_cmp_gt_i32_e64 s[0:1], v120, v40
	v_pk_mul_f32 v[32:33], v[30:31], v[28:29]
	s_nop 0
	v_cndmask_b32_e64 v34, 1.0, 0, s[0:1]
	v_pk_mul_f32 v[26:27], v[26:27], v[34:35]
	v_cmp_gt_i32_e64 s[0:1], v40, v126
	v_pk_mul_f32 v[34:35], v[26:27], v[24:25]
	v_cvt_pk_bf16_f32 v24, v44, v45
	v_cvt_pk_bf16_f32 v25, v32, v33
	v_cvt_pk_bf16_f32 v26, v36, v37
	v_cvt_pk_bf16_f32 v27, v34, v35
	v_lshl_add_u64 v[32:33], v[128:129], 1, v[42:43]
	v_pk_fma_f32 v[28:29], v[30:31], v[28:29], v[34:35]
	global_store_dwordx4 v[32:33], v[24:27], off
	v_add_f32_e32 v28, v28, v41
	ds_read_b128 v[24:27], v134 offset:512
	v_add_f32_e32 v36, v29, v28
	ds_read_b128 v[28:31], v134 offset:528
	v_cndmask_b32_e64 v35, 0, 1.0, s[0:1]
	v_cmp_gt_i32_e64 s[0:1], v126, v40
	s_waitcnt lgkmcnt(0)
	v_sub_f32_e32 v24, v24, v48
	v_sub_f32_e32 v25, v25, v48
	v_sub_f32_e32 v28, v28, v48
	v_sub_f32_e32 v29, v29, v48
	v_min_f32_e32 v28, 0, v28
	v_min_f32_e32 v29, 0, v29
	v_min_f32_e32 v24, 0, v24
	v_mul_f32_e32 v28, 0x3fb8aa3b, v28
	v_min_f32_e32 v25, 0, v25
	v_mul_f32_e32 v29, 0x3fb8aa3b, v29
	v_mul_f32_e32 v24, 0x3fb8aa3b, v24
	v_exp_f32_e32 v28, v28
	v_mul_f32_e32 v25, 0x3fb8aa3b, v25
	v_cndmask_b32_e64 v34, 1.0, 0, s[0:1]
	v_exp_f32_e32 v29, v29
	v_cmp_gt_i32_e64 s[0:1], v123, v40
	v_exp_f32_e32 v24, v24
	v_exp_f32_e32 v25, v25
	v_pk_mul_f32 v[20:21], v[20:21], v[34:35]
	v_cndmask_b32_e64 v35, 1.0, 0, s[0:1]
	v_cmp_gt_i32_e64 s[0:1], v122, v40
	s_nop 1
	v_cndmask_b32_e64 v34, 1.0, 0, s[0:1]
	v_pk_mul_f32 v[16:17], v[16:17], v[34:35]
	v_cmp_gt_i32_e64 s[0:1], v117, v40
	v_pk_mul_f32 v[28:29], v[16:17], v[28:29]
	s_nop 0
	v_pk_fma_f32 v[16:17], v[20:21], v[24:25], v[28:29]
	v_cndmask_b32_e64 v35, 1.0, 0, s[0:1]
	v_add_f32_e32 v16, v16, v36
	v_add_f32_e32 v36, v17, v16
	v_sub_f32_e32 v17, v30, v48
	v_min_f32_e32 v17, 0, v17
	v_mul_f32_e32 v17, 0x3fb8aa3b, v17
	v_sub_f32_e32 v16, v26, v48
	v_exp_f32_e32 v26, v17
	v_sub_f32_e32 v17, v27, v48
	v_sub_f32_e32 v27, v31, v48
	v_min_f32_e32 v27, 0, v27
	v_min_f32_e32 v16, 0, v16
	v_min_f32_e32 v17, 0, v17
	v_cmp_gt_i32_e64 s[0:1], v116, v40
	v_mul_f32_e32 v27, 0x3fb8aa3b, v27
	v_mul_f32_e32 v16, 0x3fb8aa3b, v16
	v_mul_f32_e32 v17, 0x3fb8aa3b, v17
	v_cndmask_b32_e64 v34, 1.0, 0, s[0:1]
	v_exp_f32_e32 v27, v27
	v_cmp_gt_i32_e64 s[0:1], v113, v40
	v_exp_f32_e32 v16, v16
	v_exp_f32_e32 v17, v17
	v_cndmask_b32_e64 v31, 1.0, 0, s[0:1]
	v_cmp_gt_i32_e64 s[0:1], v112, v40
	v_pk_mul_f32 v[22:23], v[22:23], v[34:35]
	s_nop 0
	v_cndmask_b32_e64 v30, 1.0, 0, s[0:1]
	v_pk_mul_f32 v[18:19], v[18:19], v[30:31]
	s_nop 0
	v_pk_mul_f32 v[26:27], v[18:19], v[26:27]
	s_nop 0
	v_pk_fma_f32 v[18:19], v[22:23], v[16:17], v[26:27]
	s_nop 0
	v_add_f32_e32 v18, v18, v36
	v_add_f32_e32 v30, v19, v18
	ds_bpermute_b32 v31, v172, v30
	v_pk_mul_f32 v[18:19], v[20:21], v[24:25]
	v_pk_mul_f32 v[20:21], v[22:23], v[16:17]
	v_cvt_pk_bf16_f32 v18, v18, v19
	v_cvt_pk_bf16_f32 v19, v20, v21
	s_waitcnt lgkmcnt(0)
	v_add_f32_e32 v16, v30, v31
	ds_bpermute_b32 v17, v173, v16
	v_cvt_pk_bf16_f32 v20, v28, v29
	v_cvt_pk_bf16_f32 v21, v26, v27
	global_store_dwordx4 v[32:33], v[18:21], off offset:256
	s_and_saveexec_b64 s[0:1], vcc
	s_cbranch_execz .LBB0_653
	s_waitcnt lgkmcnt(0)
	v_add_f32_e32 v16, v16, v17
	ds_write_b32 v114, v16 offset:640
.LBB0_653:
	s_or_b64 exec, exec, s[0:1]
	v_or_b32_e32 v24, 48, v64
	v_lshl_add_u32 v16, v24, 2, 0
	v_ashrrev_i32_e32 v25, 31, v24
	v_add_u32_e32 v16, 0x20000, v16
	v_lshlrev_b64 v[20:21], 9, v[24:25]
	ds_read_b32 v32, v16
	s_waitcnt lgkmcnt(0)
	ds_read_b128 v[16:19], v134
	v_lshl_add_u64 v[26:27], s[26:27], 0, v[20:21]
	ds_read_b128 v[20:23], v134 offset:16
	v_cmp_gt_i32_e64 s[0:1], v24, v128
	s_waitcnt lgkmcnt(0)
	v_sub_f32_e32 v16, v16, v32
	v_sub_f32_e32 v17, v17, v32
	v_sub_f32_e32 v20, v20, v32
	v_sub_f32_e32 v21, v21, v32
	v_min_f32_e32 v20, 0, v20
	v_min_f32_e32 v21, 0, v21
	v_min_f32_e32 v16, 0, v16
	v_mul_f32_e32 v20, 0x3fb8aa3b, v20
	v_min_f32_e32 v17, 0, v17
	v_cndmask_b32_e64 v29, 0, 1.0, s[0:1]
	v_cmp_gt_i32_e64 s[0:1], v128, v24
	v_mul_f32_e32 v21, 0x3fb8aa3b, v21
	v_mul_f32_e32 v16, 0x3fb8aa3b, v16
	v_exp_f32_e32 v20, v20
	v_mul_f32_e32 v17, 0x3fb8aa3b, v17
	v_cndmask_b32_e64 v28, 1.0, 0, s[0:1]
	v_exp_f32_e32 v21, v21
	v_cmp_gt_i32_e64 s[0:1], v131, v24
	v_exp_f32_e32 v16, v16
	v_exp_f32_e32 v17, v17
	v_cndmask_b32_e64 v31, 1.0, 0, s[0:1]
	v_cmp_gt_i32_e64 s[0:1], v124, v24
	v_pk_mul_f32 v[12:13], v[12:13], v[28:29]
	s_nop 0
	v_cndmask_b32_e64 v30, 1.0, 0, s[0:1]
	v_pk_mul_f32 v[8:9], v[8:9], v[30:31]
	v_pk_mul_f32 v[28:29], v[12:13], v[16:17]
	v_pk_mul_f32 v[20:21], v[8:9], v[20:21]
	v_cmp_gt_i32_e64 s[0:1], v125, v24
	v_pk_fma_f32 v[8:9], v[12:13], v[16:17], v[20:21]
	s_nop 0
	v_add_f32_e32 v8, 0, v8
	v_add_f32_e32 v25, v9, v8
	v_sub_f32_e32 v8, v18, v32
	v_sub_f32_e32 v9, v19, v32
	v_min_f32_e32 v8, 0, v8
	v_min_f32_e32 v9, 0, v9
	v_mul_f32_e32 v8, 0x3fb8aa3b, v8
	v_mul_f32_e32 v9, 0x3fb8aa3b, v9
	v_exp_f32_e32 v12, v8
	v_sub_f32_e32 v8, v22, v32
	v_exp_f32_e32 v13, v9
	v_sub_f32_e32 v9, v23, v32
	v_min_f32_e32 v8, 0, v8
	v_min_f32_e32 v9, 0, v9
	v_mul_f32_e32 v8, 0x3fb8aa3b, v8
	v_cndmask_b32_e64 v17, 1.0, 0, s[0:1]
	v_cmp_gt_i32_e64 s[0:1], v130, v24
	v_mul_f32_e32 v9, 0x3fb8aa3b, v9
	v_exp_f32_e32 v8, v8
	v_cndmask_b32_e64 v16, 1.0, 0, s[0:1]
	v_exp_f32_e32 v9, v9
	v_cmp_gt_i32_e64 s[0:1], v121, v24
	v_pk_mul_f32 v[14:15], v[14:15], v[16:17]
	s_nop 0
	v_cndmask_b32_e64 v19, 1.0, 0, s[0:1]
	v_cmp_gt_i32_e64 s[0:1], v120, v24
	v_pk_mul_f32 v[16:17], v[14:15], v[12:13]
	s_nop 0
	v_cndmask_b32_e64 v18, 1.0, 0, s[0:1]
	v_pk_mul_f32 v[10:11], v[10:11], v[18:19]
	v_cmp_gt_i32_e64 s[0:1], v24, v126
	v_pk_mul_f32 v[18:19], v[10:11], v[8:9]
	v_cvt_pk_bf16_f32 v8, v28, v29
	v_cvt_pk_bf16_f32 v9, v16, v17
	v_cvt_pk_bf16_f32 v10, v20, v21
	v_cvt_pk_bf16_f32 v11, v18, v19
	v_lshl_add_u64 v[16:17], v[128:129], 1, v[26:27]
	v_pk_fma_f32 v[12:13], v[14:15], v[12:13], v[18:19]
	global_store_dwordx4 v[16:17], v[8:11], off
	v_add_f32_e32 v12, v12, v25
	ds_read_b128 v[8:11], v134 offset:512
	v_add_f32_e32 v20, v13, v12
	ds_read_b128 v[12:15], v134 offset:528
	v_cndmask_b32_e64 v19, 0, 1.0, s[0:1]
	v_cmp_gt_i32_e64 s[0:1], v126, v24
	s_waitcnt lgkmcnt(0)
	v_sub_f32_e32 v8, v8, v32
	v_sub_f32_e32 v9, v9, v32
	v_sub_f32_e32 v12, v12, v32
	v_sub_f32_e32 v13, v13, v32
	v_min_f32_e32 v12, 0, v12
	v_min_f32_e32 v13, 0, v13
	v_min_f32_e32 v8, 0, v8
	v_mul_f32_e32 v12, 0x3fb8aa3b, v12
	v_min_f32_e32 v9, 0, v9
	v_mul_f32_e32 v13, 0x3fb8aa3b, v13
	v_mul_f32_e32 v8, 0x3fb8aa3b, v8
	v_exp_f32_e32 v12, v12
	v_mul_f32_e32 v9, 0x3fb8aa3b, v9
	v_cndmask_b32_e64 v18, 1.0, 0, s[0:1]
	v_exp_f32_e32 v13, v13
	v_cmp_gt_i32_e64 s[0:1], v123, v24
	v_exp_f32_e32 v8, v8
	v_exp_f32_e32 v9, v9
	v_pk_mul_f32 v[4:5], v[4:5], v[18:19]
	v_cndmask_b32_e64 v19, 1.0, 0, s[0:1]
	v_cmp_gt_i32_e64 s[0:1], v122, v24
	s_nop 1
	v_cndmask_b32_e64 v18, 1.0, 0, s[0:1]
	v_pk_mul_f32 v[0:1], v[0:1], v[18:19]
	v_cmp_gt_i32_e64 s[0:1], v117, v24
	v_pk_mul_f32 v[12:13], v[0:1], v[12:13]
	s_nop 0
	v_pk_fma_f32 v[0:1], v[4:5], v[8:9], v[12:13]
	v_cndmask_b32_e64 v19, 1.0, 0, s[0:1]
	v_add_f32_e32 v0, v0, v20
	v_add_f32_e32 v20, v1, v0
	v_sub_f32_e32 v1, v14, v32
	v_min_f32_e32 v1, 0, v1
	v_mul_f32_e32 v1, 0x3fb8aa3b, v1
	v_sub_f32_e32 v0, v10, v32
	v_exp_f32_e32 v10, v1
	v_sub_f32_e32 v1, v11, v32
	v_sub_f32_e32 v11, v15, v32
	v_min_f32_e32 v11, 0, v11
	v_min_f32_e32 v0, 0, v0
	v_min_f32_e32 v1, 0, v1
	v_cmp_gt_i32_e64 s[0:1], v116, v24
	v_mul_f32_e32 v11, 0x3fb8aa3b, v11
	v_mul_f32_e32 v0, 0x3fb8aa3b, v0
	v_mul_f32_e32 v1, 0x3fb8aa3b, v1
	v_cndmask_b32_e64 v18, 1.0, 0, s[0:1]
	v_exp_f32_e32 v11, v11
	v_cmp_gt_i32_e64 s[0:1], v113, v24
	v_exp_f32_e32 v0, v0
	v_exp_f32_e32 v1, v1
	v_cndmask_b32_e64 v15, 1.0, 0, s[0:1]
	v_cmp_gt_i32_e64 s[0:1], v112, v24
	v_pk_mul_f32 v[6:7], v[6:7], v[18:19]
	s_nop 0
	v_cndmask_b32_e64 v14, 1.0, 0, s[0:1]
	v_pk_mul_f32 v[2:3], v[2:3], v[14:15]
	s_lshl_b64 s[0:1], s[18:19], 16
	v_pk_mul_f32 v[10:11], v[2:3], v[10:11]
	s_nop 0
	v_pk_fma_f32 v[2:3], v[6:7], v[0:1], v[10:11]
	s_nop 0
	v_add_f32_e32 v2, v2, v20
	v_add_f32_e32 v14, v3, v2
	ds_bpermute_b32 v15, v172, v14
	v_pk_mul_f32 v[2:3], v[4:5], v[8:9]
	v_pk_mul_f32 v[4:5], v[6:7], v[0:1]
	v_cvt_pk_bf16_f32 v2, v2, v3
	v_cvt_pk_bf16_f32 v3, v4, v5
	s_waitcnt lgkmcnt(0)
	v_add_f32_e32 v0, v14, v15
	ds_bpermute_b32 v1, v173, v0
	v_cvt_pk_bf16_f32 v4, v12, v13
	v_cvt_pk_bf16_f32 v5, v10, v11
	global_store_dwordx4 v[16:17], v[2:5], off offset:256
	s_and_saveexec_b64 s[26:27], vcc
	s_cbranch_execz .LBB0_655
	s_waitcnt lgkmcnt(0)
	v_add_f32_e32 v0, v0, v1
	ds_write_b32 v114, v0 offset:704

.LBB0_663:
	s_lshl_b32 s2, s33, 8
	s_mul_i32 s1, s20, 0x1800
	s_mul_hi_i32 s0, s20, 0x1800
	s_add_u32 s24, s58, s1
	v_mov_b32_e32 v92, v182
	s_addc_u32 s25, s59, s0
	s_lshl_b32 s19, s2, 1
	s_add_u32 s0, s24, s19
	v_and_b32_e32 v155, 63, v92
	s_addc_u32 s1, s25, 0
	v_ashrrev_i32_e32 v92, 1, v155
	s_add_u32 s0, s0, 0x8800800
	v_and_b32_e32 v92, -8, v92
	s_addc_u32 s1, s1, 0
	v_add_u32_e32 v92, s80, v92
	v_and_or_b32 v162, v155, 15, s79
	v_ashrrev_i32_e32 v93, 31, v92
	v_mov_b64_e32 v[94:95], s[0:1]
	v_mad_i64_i32 v[96:97], s[22:23], v162, s77, v[94:95]
	v_lshlrev_b64 v[158:159], 1, v[92:93]
	v_lshl_add_u64 v[92:93], v[96:97], 0, v[158:159]
	global_load_dwordx4 v[164:167], v[92:93], off nt
	v_lshl_add_u32 v96, v162, 2, 0
	v_add_u32_e32 v152, 0x21400, v96
	v_add_u32_e32 v174, 0x20400, v96
	v_add_u32_e32 v175, 0x21000, v96
	v_add_u32_e32 v176, 0x20c00, v96
	ds_read2st64_b32 v[96:97], v152 offset1:4
	ds_read2st64_b32 v[98:99], v152 offset0:8 offset1:12
	ds_read_b32 v116, v174
	ds_read_b32 v117, v175
	ds_read_b32 v118, v176
	global_load_dwordx4 v[168:171], v[92:93], off offset:256 nt
	v_or_b32_e32 v154, 16, v162
	v_mad_i64_i32 v[112:113], s[22:23], v154, s77, v[94:95]
	v_lshl_add_u64 v[92:93], v[112:113], 0, v[158:159]
	global_load_dwordx4 v[136:139], v[92:93], off nt
	global_load_dwordx4 v[132:135], v[92:93], off offset:256 nt
	s_waitcnt lgkmcnt(0)
	v_add_f32_e32 v92, v96, v97
	v_add_f32_e32 v92, v92, v98
	v_or_b32_e32 v160, 32, v162
	v_or_b32_e32 v163, 48, v162
	v_add_f32_e32 v92, v92, v99
	v_mad_i64_i32 v[114:115], s[22:23], v160, s77, v[94:95]
	v_mad_i64_i32 v[94:95], s[22:23], v163, s77, v[94:95]
	v_max_f32_e32 v93, v118, v118
	v_fmac_f32_e32 v92, v116, v117
	v_lshl_add_u64 v[112:113], v[114:115], 0, v[158:159]
	v_lshl_add_u64 v[94:95], v[94:95], 0, v[158:159]
	v_max_f32_e64 v92, |v92|, v93
	v_rcp_f32_e32 v156, v92
	global_load_dwordx4 v[116:119], v[112:113], off nt
	s_nop 0
	global_load_dwordx4 v[112:115], v[112:113], off offset:256 nt
	s_nop 0
	global_load_dwordx4 v[96:99], v[94:95], off nt
	s_nop 0
	global_load_dwordx4 v[92:95], v[94:95], off offset:256 nt
	s_lshl_b32 s3, s42, 8
	v_cmp_gt_u32_e32 vcc, 16, v155
	v_pk_mul_f32 v[150:151], v[150:151], v[156:157] op_sel_hi:[1,0]
	v_pk_mul_f32 v[148:149], v[148:149], v[156:157] op_sel_hi:[1,0]
	v_pk_mul_f32 v[178:179], v[30:31], v[156:157] op_sel_hi:[1,0]
	v_pk_mul_f32 v[180:181], v[28:29], v[156:157] op_sel_hi:[1,0]
	s_waitcnt vmcnt(0)
	v_lshlrev_b32_e32 v157, 16, v166
	v_lshlrev_b32_e32 v28, 16, v164
	v_and_b32_e32 v29, 0xffff0000, v164
	v_mul_f32_e32 v157, 0xbfb8aa3b, v157
	v_lshlrev_b32_e32 v30, 16, v165
	v_and_b32_e32 v31, 0xffff0000, v165
	v_and_b32_e32 v161, 0xffff0000, v166
	v_mul_f32_e32 v28, 0xbfb8aa3b, v28
	v_mul_f32_e32 v29, 0xbfb8aa3b, v29
	v_exp_f32_e32 v157, v157
	v_mul_f32_e32 v30, 0xbfb8aa3b, v30
	v_mul_f32_e32 v31, 0xbfb8aa3b, v31
	v_mul_f32_e32 v161, 0xbfb8aa3b, v161
	v_exp_f32_e32 v28, v28
	v_exp_f32_e32 v29, v29
	v_exp_f32_e32 v30, v30
	v_exp_f32_e32 v31, v31
	v_exp_f32_e32 v161, v161
	v_lshlrev_b32_e32 v164, 16, v167
	v_and_b32_e32 v165, 0xffff0000, v167
	v_mul_f32_e32 v164, 0xbfb8aa3b, v164
	v_add_f32_e32 v157, 1.0, v157
	v_exp_f32_e32 v166, v164
	v_add_f32_e32 v28, 1.0, v28
	v_add_f32_e32 v29, 1.0, v29
	v_rcp_f32_e32 v164, v157
	v_mul_f32_e32 v157, 0xbfb8aa3b, v165
	v_add_f32_e32 v30, 1.0, v30
	v_add_f32_e32 v31, 1.0, v31
	v_add_f32_e32 v161, 1.0, v161
	v_rcp_f32_e32 v28, v28
	v_rcp_f32_e32 v29, v29
	v_exp_f32_e32 v157, v157
	v_rcp_f32_e32 v30, v30
	v_rcp_f32_e32 v31, v31
	v_rcp_f32_e32 v165, v161
	v_add_f32_e32 v161, 1.0, v166
	v_add_f32_e32 v157, 1.0, v157
	v_pk_mul_f32 v[28:29], v[28:29], v[148:149]
	v_rcp_f32_e32 v186, v161
	v_rcp_f32_e32 v187, v157
	v_pk_mul_f32 v[30:31], v[30:31], v[150:151]
	v_pk_mul_f32 v[166:167], v[164:165], v[180:181]
	v_add_f32_e32 v148, v28, v29
	v_lshlrev_b32_e32 v164, 16, v170
	v_add_f32_e32 v148, v30, v148
	v_mul_f32_e32 v164, 0xbfb8aa3b, v164
	v_and_b32_e32 v165, 0xffff0000, v170
	v_add_f32_e32 v148, v31, v148
	v_exp_f32_e32 v164, v164
	v_mul_f32_e32 v165, 0xbfb8aa3b, v165
	v_add_f32_e32 v148, v166, v148
	v_exp_f32_e32 v165, v165
	v_pk_mul_f32 v[150:151], v[186:187], v[178:179]
	v_add_f32_e32 v148, v167, v148
	v_add_f32_e32 v148, v150, v148
	v_add_f32_e32 v148, v151, v148
	v_add_f32_e32 v164, 1.0, v164
	v_add_f32_e32 v161, 0, v148
	v_lshlrev_b32_e32 v148, 16, v168
	v_and_b32_e32 v149, 0xffff0000, v168
	v_rcp_f32_e32 v168, v164
	v_add_f32_e32 v164, 1.0, v165
	v_lshlrev_b32_e32 v165, 16, v171
	v_pk_mul_f32 v[146:147], v[146:147], v[156:157] op_sel_hi:[1,0]
	v_pk_mul_f32 v[144:145], v[144:145], v[156:157] op_sel_hi:[1,0]
	v_pk_mul_f32 v[142:143], v[142:143], v[156:157] op_sel_hi:[1,0]
	v_mul_f32_e32 v148, 0xbfb8aa3b, v148
	v_mul_f32_e32 v149, 0xbfb8aa3b, v149
	v_pk_mul_f32 v[140:141], v[140:141], v[156:157] op_sel_hi:[1,0]
	v_lshlrev_b32_e32 v156, 16, v169
	v_and_b32_e32 v157, 0xffff0000, v169
	v_mul_f32_e32 v165, 0xbfb8aa3b, v165
	v_and_b32_e32 v169, 0xffff0000, v171
	v_exp_f32_e32 v148, v148
	v_exp_f32_e32 v149, v149
	v_mul_f32_e32 v156, 0xbfb8aa3b, v156
	v_mul_f32_e32 v157, 0xbfb8aa3b, v157
	v_exp_f32_e32 v165, v165
	v_mul_f32_e32 v169, 0xbfb8aa3b, v169
	v_exp_f32_e32 v156, v156
	v_exp_f32_e32 v157, v157
	v_exp_f32_e32 v170, v169
	v_add_f32_e32 v148, 1.0, v148
	v_add_f32_e32 v149, 1.0, v149
	v_rcp_f32_e32 v169, v164
	v_add_f32_e32 v164, 1.0, v165
	v_rcp_f32_e32 v148, v148
	v_rcp_f32_e32 v149, v149
	v_add_f32_e32 v156, 1.0, v156
	v_add_f32_e32 v157, 1.0, v157
	v_rcp_f32_e32 v190, v164
	v_add_f32_e32 v164, 1.0, v170
	v_rcp_f32_e32 v156, v156
	v_rcp_f32_e32 v157, v157
	v_rcp_f32_e32 v191, v164
	v_pk_mul_f32 v[170:171], v[148:149], v[144:145]
	v_pk_mul_f32 v[148:149], v[168:169], v[140:141]
	v_pk_mul_f32 v[164:165], v[156:157], v[146:147]
	v_pk_mul_f32 v[140:141], v[190:191], v[142:143]
	v_add_f32_e32 v142, v170, v171
	v_add_f32_e32 v142, v164, v142
	v_add_f32_e32 v142, v165, v142
	v_add_f32_e32 v142, v148, v142
	v_add_f32_e32 v142, v149, v142
	v_add_f32_e32 v142, v140, v142
	v_add_f32_e32 v142, v141, v142
	v_pk_mul_f32 v[178:179], v[28:29], v[28:29]
	v_add_f32_e32 v161, v142, v161
	v_pk_mul_f32 v[142:143], v[170:171], v[170:171]
	v_pk_mul_f32 v[180:181], v[30:31], v[30:31]
	v_pk_mul_f32 v[144:145], v[164:165], v[164:165]
	v_add_f32_e32 v142, v142, v143
	v_add_f32_e32 v143, v178, v179
	v_add_f32_e32 v142, v144, v142
	v_add_f32_e32 v143, v180, v143
	v_pk_mul_f32 v[186:187], v[166:167], v[166:167]
	v_pk_mul_f32 v[146:147], v[148:149], v[148:149]
	v_add_f32_e32 v142, v145, v142
	v_add_f32_e32 v143, v181, v143
	v_add_f32_e32 v142, v146, v142
	v_add_f32_e32 v143, v186, v143
	v_pk_mul_f32 v[188:189], v[150:151], v[150:151]
	v_pk_mul_f32 v[156:157], v[140:141], v[140:141]
	v_add_f32_e32 v142, v147, v142
	v_add_f32_e32 v143, v187, v143
	v_add_f32_e32 v142, v156, v142
	v_add_f32_e32 v143, v188, v143
	v_add_f32_e32 v142, v157, v142
	v_add_f32_e32 v143, v189, v143
	v_add_f32_e32 v145, v143, v142
	ds_bpermute_b32 v144, v172, v161
	ds_bpermute_b32 v146, v172, v145
	s_waitcnt lgkmcnt(0)
	v_add_f32_e32 v142, v161, v144
	v_add_f32_e32 v144, v145, v146
	ds_bpermute_b32 v143, v173, v142
	ds_bpermute_b32 v145, v173, v144
	v_add_u32_e32 v146, s3, v162
	v_lshl_add_u32 v177, v146, 2, 0
	s_and_saveexec_b64 s[22:23], vcc
	s_cbranch_execz .LBB0_665
	s_waitcnt lgkmcnt(1)
	v_add_f32_e32 v142, v142, v143
	s_waitcnt lgkmcnt(0)
	v_add_f32_e32 v143, v144, v145
	ds_write2st64_b32 v177, v142, v143 offset1:16

.LBB0_671:
	s_or_b64 exec, exec, s[22:23]
	v_add_u32_e32 v82, 0x80, v162
	s_waitcnt lgkmcnt(1)
	v_mov_b64_e32 v[80:81], s[0:1]
	s_waitcnt lgkmcnt(0)
	v_mad_i64_i32 v[82:83], s[0:1], v82, s77, v[80:81]
	v_lshl_add_u64 v[82:83], v[82:83], 0, v[158:159]
	global_load_dwordx4 v[124:127], v[82:83], off nt
	global_load_dwordx4 v[144:147], v[82:83], off offset:256 nt
	v_add_u32_e32 v82, 0x90, v162
	v_add_u32_e32 v84, 0xa0, v162
	v_add_u32_e32 v86, 0xb0, v162
	v_mad_i64_i32 v[82:83], s[0:1], v82, s77, v[80:81]
	v_mad_i64_i32 v[84:85], s[0:1], v84, s77, v[80:81]
	v_mad_i64_i32 v[80:81], s[0:1], v86, s77, v[80:81]
	ds_read2st64_b32 v[86:87], v152 offset0:2 offset1:6
	ds_read2st64_b32 v[88:89], v152 offset0:10 offset1:14
	ds_read_b32 v90, v174 offset:512
	ds_read_b32 v91, v175 offset:512
	ds_read_b32 v92, v176 offset:512
	v_lshl_add_u64 v[82:83], v[82:83], 0, v[158:159]
	global_load_dwordx4 v[100:103], v[82:83], off nt
	global_load_dwordx4 v[96:99], v[82:83], off offset:256 nt
	s_waitcnt lgkmcnt(0)
	v_add_f32_e32 v82, v86, v87
	v_add_f32_e32 v82, v82, v88
	v_add_f32_e32 v82, v82, v89
	v_max_f32_e32 v83, v92, v92
	v_fmac_f32_e32 v82, v90, v91
	v_lshl_add_u64 v[84:85], v[84:85], 0, v[158:159]
	v_lshl_add_u64 v[80:81], v[80:81], 0, v[158:159]
	v_max_f32_e64 v82, |v82|, v83
	v_rcp_f32_e32 v112, v82
	global_load_dwordx4 v[92:95], v[84:85], off nt
	global_load_dwordx4 v[88:91], v[84:85], off offset:256 nt
	s_nop 0
	global_load_dwordx4 v[84:87], v[80:81], off nt
	s_nop 0
	global_load_dwordx4 v[80:83], v[80:81], off offset:256 nt
	v_pk_mul_f32 v[162:163], v[24:25], v[112:113] op_sel_hi:[1,0]
	v_pk_mul_f32 v[128:129], v[26:27], v[112:113] op_sel_hi:[1,0]
	v_pk_mul_f32 v[78:79], v[78:79], v[112:113] op_sel_hi:[1,0]
	v_pk_mul_f32 v[76:77], v[76:77], v[112:113] op_sel_hi:[1,0]
	v_pk_mul_f32 v[74:75], v[74:75], v[112:113] op_sel_hi:[1,0]
	v_pk_mul_f32 v[72:73], v[72:73], v[112:113] op_sel_hi:[1,0]
	v_pk_mul_f32 v[70:71], v[70:71], v[112:113] op_sel_hi:[1,0]
	s_waitcnt vmcnt(0)
	v_lshlrev_b32_e32 v24, 16, v124
	v_and_b32_e32 v25, 0xffff0000, v124
	v_lshlrev_b32_e32 v26, 16, v125
	v_and_b32_e32 v27, 0xffff0000, v125
	v_mul_f32_e32 v24, 0xbfb8aa3b, v24
	v_mul_f32_e32 v25, 0xbfb8aa3b, v25
	v_mul_f32_e32 v26, 0xbfb8aa3b, v26
	v_mul_f32_e32 v27, 0xbfb8aa3b, v27
	v_exp_f32_e32 v24, v24
	v_exp_f32_e32 v25, v25
	v_lshlrev_b32_e32 v113, 16, v126
	v_and_b32_e32 v124, 0xffff0000, v126
	v_exp_f32_e32 v26, v26
	v_exp_f32_e32 v27, v27
	v_lshlrev_b32_e32 v125, 16, v127
	v_mul_f32_e32 v113, 0xbfb8aa3b, v113
	v_mul_f32_e32 v124, 0xbfb8aa3b, v124
	v_and_b32_e32 v126, 0xffff0000, v127
	v_mul_f32_e32 v125, 0xbfb8aa3b, v125
	v_exp_f32_e32 v113, v113
	v_exp_f32_e32 v124, v124
	v_mul_f32_e32 v126, 0xbfb8aa3b, v126
	v_exp_f32_e32 v125, v125
	v_add_f32_e32 v24, 1.0, v24
	v_add_f32_e32 v25, 1.0, v25
	v_exp_f32_e32 v126, v126
	v_add_f32_e32 v26, 1.0, v26
	v_add_f32_e32 v27, 1.0, v27
	v_rcp_f32_e32 v24, v24
	v_rcp_f32_e32 v25, v25
	v_lshlrev_b32_e32 v127, 16, v144
	v_rcp_f32_e32 v26, v26
	v_rcp_f32_e32 v27, v27
	v_mul_f32_e32 v178, 0xbfb8aa3b, v127
	v_add_f32_e32 v113, 1.0, v113
	v_add_f32_e32 v127, 1.0, v124
	v_add_f32_e32 v132, 1.0, v125
	v_rcp_f32_e32 v124, v113
	v_rcp_f32_e32 v125, v127
	v_add_f32_e32 v133, 1.0, v126
	v_pk_mul_f32 v[24:25], v[24:25], v[76:77]
	v_rcp_f32_e32 v126, v132
	v_rcp_f32_e32 v127, v133
	v_pk_mul_f32 v[26:27], v[26:27], v[78:79]
	v_add_f32_e32 v113, v24, v25
	v_add_f32_e32 v113, v26, v113
	v_pk_mul_f32 v[158:159], v[124:125], v[72:73]
	v_add_f32_e32 v113, v27, v113
	v_add_f32_e32 v113, v158, v113
	v_pk_mul_f32 v[132:133], v[126:127], v[74:75]
	v_add_f32_e32 v113, v159, v113
	v_add_f32_e32 v113, v132, v113
	v_and_b32_e32 v124, 0xffff0000, v144
	v_add_f32_e32 v113, v133, v113
	v_mul_f32_e32 v124, 0xbfb8aa3b, v124
	v_add_f32_e32 v179, 0, v113
	v_exp_f32_e32 v113, v178
	v_exp_f32_e32 v124, v124
	v_and_b32_e32 v125, 0xffff0000, v145
	v_lshlrev_b32_e32 v126, 16, v146
	v_pk_mul_f32 v[68:69], v[68:69], v[112:113] op_sel_hi:[1,0]
	v_add_f32_e32 v112, 1.0, v113
	v_add_f32_e32 v113, 1.0, v124
	v_lshlrev_b32_e32 v124, 16, v145
	v_and_b32_e32 v127, 0xffff0000, v146
	v_mul_f32_e32 v124, 0xbfb8aa3b, v124
	v_mul_f32_e32 v125, 0xbfb8aa3b, v125
	v_mul_f32_e32 v126, 0xbfb8aa3b, v126
	v_mul_f32_e32 v127, 0xbfb8aa3b, v127
	v_exp_f32_e32 v124, v124
	v_exp_f32_e32 v125, v125
	v_exp_f32_e32 v126, v126
	v_exp_f32_e32 v127, v127
	v_lshlrev_b32_e32 v144, 16, v147
	v_and_b32_e32 v145, 0xffff0000, v147
	v_mul_f32_e32 v144, 0xbfb8aa3b, v144
	v_mul_f32_e32 v145, 0xbfb8aa3b, v145
	v_rcp_f32_e32 v112, v112
	v_rcp_f32_e32 v113, v113
	v_add_f32_e32 v124, 1.0, v124
	v_add_f32_e32 v125, 1.0, v125
	v_add_f32_e32 v126, 1.0, v126
	v_add_f32_e32 v127, 1.0, v127
	v_exp_f32_e32 v144, v144
	v_exp_f32_e32 v145, v145
	v_rcp_f32_e32 v124, v124
	v_rcp_f32_e32 v125, v125
	v_rcp_f32_e32 v126, v126
	v_rcp_f32_e32 v127, v127
	v_add_f32_e32 v144, 1.0, v144
	v_add_f32_e32 v145, 1.0, v145
	v_pk_mul_f32 v[162:163], v[112:113], v[162:163]
	v_rcp_f32_e32 v144, v144
	v_rcp_f32_e32 v145, v145
	v_pk_mul_f32 v[146:147], v[124:125], v[128:129]
	v_pk_mul_f32 v[128:129], v[126:127], v[68:69]
	v_add_f32_e32 v68, v162, v163
	v_add_f32_e32 v68, v146, v68
	v_add_f32_e32 v68, v147, v68
	v_add_f32_e32 v68, v128, v68
	v_pk_mul_f32 v[112:113], v[144:145], v[70:71]
	v_add_f32_e32 v68, v129, v68
	v_add_f32_e32 v68, v112, v68
	v_add_f32_e32 v68, v113, v68
	v_pk_mul_f32 v[72:73], v[24:25], v[24:25]
	v_add_f32_e32 v144, v68, v179
	v_pk_mul_f32 v[68:69], v[162:163], v[162:163]
	v_pk_mul_f32 v[74:75], v[26:27], v[26:27]
	v_pk_mul_f32 v[70:71], v[146:147], v[146:147]
	v_add_f32_e32 v68, v68, v69
	v_add_f32_e32 v69, v72, v73
	v_add_f32_e32 v68, v70, v68
	v_add_f32_e32 v69, v74, v69
	v_pk_mul_f32 v[76:77], v[158:159], v[158:159]
	v_pk_mul_f32 v[124:125], v[128:129], v[128:129]
	v_add_f32_e32 v68, v71, v68
	v_add_f32_e32 v69, v75, v69
	v_add_f32_e32 v68, v124, v68
	v_add_f32_e32 v69, v76, v69
	v_pk_mul_f32 v[78:79], v[132:133], v[132:133]
	v_pk_mul_f32 v[126:127], v[112:113], v[112:113]
	v_add_f32_e32 v68, v125, v68
	v_add_f32_e32 v69, v77, v69
	v_add_f32_e32 v68, v126, v68
	v_add_f32_e32 v69, v78, v69
	v_add_f32_e32 v68, v127, v68
	v_add_f32_e32 v69, v79, v69
	v_add_f32_e32 v71, v69, v68
	ds_bpermute_b32 v70, v172, v144
	ds_bpermute_b32 v72, v172, v71
	s_waitcnt lgkmcnt(0)
	v_add_f32_e32 v68, v144, v70
	v_add_f32_e32 v70, v71, v72
	ds_bpermute_b32 v69, v173, v68
	ds_bpermute_b32 v71, v173, v70
	s_and_saveexec_b64 s[0:1], vcc
	s_cbranch_execz .LBB0_673
	s_waitcnt lgkmcnt(1)
	v_add_f32_e32 v68, v68, v69
	s_waitcnt lgkmcnt(0)
	v_add_f32_e32 v69, v70, v71
	ds_write2st64_b32 v177, v68, v69 offset0:2 offset1:18

.LBB0_758:
	v_mul_f32_e32 v122, 0xbfb8aa3b, v122
	v_mul_f32_e32 v124, 0xbfb8aa3b, v124
	v_mul_f32_e32 v125, 0xbfb8aa3b, v125
	v_mul_f32_e32 v126, 0xbfb8aa3b, v126
	v_mul_f32_e32 v127, 0xbfb8aa3b, v127
	v_mul_f32_e32 v120, 0xbfb8aa3b, v120
	v_mul_f32_e32 v121, 0xbfb8aa3b, v121
	v_exp_f32_e32 v122, v122
	v_mul_f32_e32 v123, 0xbfb8aa3b, v123
	v_exp_f32_e32 v124, v124
	v_exp_f32_e32 v125, v125
	v_exp_f32_e32 v126, v126
	v_exp_f32_e32 v127, v127
	v_exp_f32_e32 v120, v120
	v_exp_f32_e32 v121, v121
	v_exp_f32_e32 v123, v123
	v_mov_b32_e32 v128, v182
	v_add_f32_e32 v122, 1.0, v122
	v_and_b32_e32 v128, 63, v128
	s_mov_b64 s[0:1], s[16:17]
	s_lshl_b32 s2, s12, 4
	v_add_f32_e32 v124, 1.0, v124
	v_add_f32_e32 v125, 1.0, v125
	v_add_f32_e32 v126, 1.0, v126
	v_add_f32_e32 v127, 1.0, v127
	v_add_f32_e32 v120, 1.0, v120
	v_add_f32_e32 v121, 1.0, v121
	v_rcp_f32_e32 v130, v122
	v_add_f32_e32 v122, 1.0, v123
	v_mul_f32_e32 v112, 0xbfb8aa3b, v112
	s_add_i32 s36, s2, s24
	s_mov_b32 s37, s13
	v_ashrrev_i32_e32 v129, 31, v128
	v_rcp_f32_e32 v124, v124
	v_rcp_f32_e32 v125, v125
	v_rcp_f32_e32 v126, v126
	v_rcp_f32_e32 v127, v127
	v_rcp_f32_e32 v120, v120
	v_rcp_f32_e32 v121, v121
	v_rcp_f32_e32 v131, v122
	v_exp_f32_e32 v112, v112
	v_mul_f32_e32 v113, 0xbfb8aa3b, v113
	v_lshl_add_u64 v[128:129], v[128:129], 4, s[0:1]
	s_lshl_b64 s[0:1], s[36:37], 17
	v_exp_f32_e32 v113, v113
	s_add_u32 s4, s0, s22
	s_addc_u32 s5, s1, s23
	v_cvt_pk_bf16_f32 v122, v124, v125
	v_cvt_pk_bf16_f32 v123, v126, v127
	v_cvt_pk_bf16_f32 v124, v120, v121
	v_cvt_pk_bf16_f32 v125, v130, v131
	v_lshl_add_u64 v[120:121], v[128:129], 0, s[4:5]
	v_add_f32_e32 v112, 1.0, v112
	global_store_dwordx4 v[120:121], v[122:125], off
	v_mul_f32_e32 v116, 0xbfb8aa3b, v116
	v_mul_f32_e32 v117, 0xbfb8aa3b, v117
	v_rcp_f32_e32 v122, v112
	v_add_f32_e32 v112, 1.0, v113
	v_mul_f32_e32 v113, 0xbfb8aa3b, v114
	v_mul_f32_e32 v118, 0xbfb8aa3b, v118
	v_mul_f32_e32 v119, 0xbfb8aa3b, v119
	v_exp_f32_e32 v113, v113
	v_mul_f32_e32 v114, 0xbfb8aa3b, v115
	v_exp_f32_e32 v116, v116
	v_exp_f32_e32 v117, v117
	v_exp_f32_e32 v118, v118
	v_exp_f32_e32 v119, v119
	v_exp_f32_e32 v114, v114
	v_rcp_f32_e32 v115, v112
	v_add_f32_e32 v112, 1.0, v113
	v_add_f32_e32 v116, 1.0, v116
	v_add_f32_e32 v117, 1.0, v117
	v_add_f32_e32 v118, 1.0, v118
	v_add_f32_e32 v119, 1.0, v119
	v_rcp_f32_e32 v123, v112
	v_add_f32_e32 v112, 1.0, v114
	v_mul_f32_e32 v104, 0xbfb8aa3b, v104
	v_rcp_f32_e32 v116, v116
	v_rcp_f32_e32 v117, v117
	v_rcp_f32_e32 v118, v118
	v_rcp_f32_e32 v119, v119
	v_rcp_f32_e32 v124, v112
	v_exp_f32_e32 v104, v104
	v_mul_f32_e32 v105, 0xbfb8aa3b, v105
	v_exp_f32_e32 v105, v105
	v_cvt_pk_bf16_f32 v112, v116, v117
	v_cvt_pk_bf16_f32 v113, v118, v119
	v_cvt_pk_bf16_f32 v114, v122, v115
	v_cvt_pk_bf16_f32 v115, v123, v124
	v_add_f32_e32 v104, 1.0, v104
	global_store_dwordx4 v[120:121], v[112:115], off offset:1024
	v_mul_f32_e32 v108, 0xbfb8aa3b, v108
	v_mul_f32_e32 v109, 0xbfb8aa3b, v109
	v_rcp_f32_e32 v112, v104
	v_add_f32_e32 v104, 1.0, v105
	v_mul_f32_e32 v105, 0xbfb8aa3b, v106
	v_mul_f32_e32 v110, 0xbfb8aa3b, v110
	v_mul_f32_e32 v111, 0xbfb8aa3b, v111
	v_exp_f32_e32 v105, v105
	v_mul_f32_e32 v106, 0xbfb8aa3b, v107
	v_exp_f32_e32 v108, v108
	v_exp_f32_e32 v109, v109
	v_exp_f32_e32 v110, v110
	v_exp_f32_e32 v111, v111
	v_exp_f32_e32 v106, v106
	v_rcp_f32_e32 v107, v104
	v_add_f32_e32 v104, 1.0, v105
	v_add_f32_e32 v108, 1.0, v108
	v_add_f32_e32 v109, 1.0, v109
	v_add_f32_e32 v110, 1.0, v110
	v_add_f32_e32 v111, 1.0, v111
	v_rcp_f32_e32 v113, v104
	v_add_f32_e32 v104, 1.0, v106
	v_mul_f32_e32 v96, 0xbfb8aa3b, v96
	v_rcp_f32_e32 v108, v108
	v_rcp_f32_e32 v109, v109
	v_rcp_f32_e32 v110, v110
	v_rcp_f32_e32 v111, v111
	v_rcp_f32_e32 v114, v104
	v_exp_f32_e32 v96, v96
	v_mul_f32_e32 v97, 0xbfb8aa3b, v97
	v_exp_f32_e32 v97, v97
	v_cvt_pk_bf16_f32 v104, v108, v109
	v_cvt_pk_bf16_f32 v105, v110, v111
	v_cvt_pk_bf16_f32 v106, v112, v107
	v_cvt_pk_bf16_f32 v107, v113, v114
	v_add_f32_e32 v96, 1.0, v96
	global_store_dwordx4 v[120:121], v[104:107], off offset:2048
	v_mul_f32_e32 v100, 0xbfb8aa3b, v100
	v_mul_f32_e32 v101, 0xbfb8aa3b, v101
	v_rcp_f32_e32 v104, v96
	v_add_f32_e32 v96, 1.0, v97
	v_mul_f32_e32 v97, 0xbfb8aa3b, v98
	v_mul_f32_e32 v102, 0xbfb8aa3b, v102
	v_mul_f32_e32 v103, 0xbfb8aa3b, v103
	v_exp_f32_e32 v97, v97
	v_mul_f32_e32 v98, 0xbfb8aa3b, v99
	v_exp_f32_e32 v100, v100
	v_exp_f32_e32 v101, v101
	v_exp_f32_e32 v102, v102
	v_exp_f32_e32 v103, v103
	v_exp_f32_e32 v98, v98
	v_rcp_f32_e32 v99, v96
	v_add_f32_e32 v96, 1.0, v97
	v_add_f32_e32 v100, 1.0, v100
	v_add_f32_e32 v101, 1.0, v101
	v_add_f32_e32 v102, 1.0, v102
	v_add_f32_e32 v103, 1.0, v103
	v_rcp_f32_e32 v105, v96
	v_add_f32_e32 v96, 1.0, v98
	v_mul_f32_e32 v88, 0xbfb8aa3b, v88
	v_rcp_f32_e32 v100, v100
	v_rcp_f32_e32 v101, v101
	v_rcp_f32_e32 v102, v102
	v_rcp_f32_e32 v103, v103
	v_rcp_f32_e32 v106, v96
	v_exp_f32_e32 v88, v88
	v_mul_f32_e32 v89, 0xbfb8aa3b, v89
	v_exp_f32_e32 v89, v89
	v_cvt_pk_bf16_f32 v96, v100, v101
	v_cvt_pk_bf16_f32 v97, v102, v103
	v_cvt_pk_bf16_f32 v98, v104, v99
	v_cvt_pk_bf16_f32 v99, v105, v106
	v_add_f32_e32 v88, 1.0, v88
	v_mul_f32_e32 v92, 0xbfb8aa3b, v92
	v_mul_f32_e32 v93, 0xbfb8aa3b, v93
	global_store_dwordx4 v[120:121], v[96:99], off offset:3072
	v_exp_f32_e32 v92, v92
	v_exp_f32_e32 v93, v93
	v_rcp_f32_e32 v96, v88
	v_add_f32_e32 v88, 1.0, v89
	v_mul_f32_e32 v89, 0xbfb8aa3b, v90
	v_mul_f32_e32 v94, 0xbfb8aa3b, v94
	v_mul_f32_e32 v95, 0xbfb8aa3b, v95
	v_exp_f32_e32 v89, v89
	v_mul_f32_e32 v90, 0xbfb8aa3b, v91
	v_exp_f32_e32 v94, v94
	v_exp_f32_e32 v95, v95
	v_exp_f32_e32 v90, v90
	v_add_f32_e32 v92, 1.0, v92
	v_add_f32_e32 v93, 1.0, v93
	v_rcp_f32_e32 v91, v88
	v_add_f32_e32 v88, 1.0, v89
	v_rcp_f32_e32 v92, v92
	v_rcp_f32_e32 v93, v93
	v_add_f32_e32 v94, 1.0, v94
	v_add_f32_e32 v95, 1.0, v95
	v_rcp_f32_e32 v97, v88
	v_add_f32_e32 v88, 1.0, v90
	v_mul_f32_e32 v80, 0xbfb8aa3b, v80
	v_rcp_f32_e32 v94, v94
	v_rcp_f32_e32 v95, v95
	v_rcp_f32_e32 v98, v88
	v_exp_f32_e32 v80, v80
	v_mul_f32_e32 v81, 0xbfb8aa3b, v81
	v_exp_f32_e32 v81, v81
	v_cvt_pk_bf16_f32 v88, v92, v93
	v_add_co_u32_e32 v92, vcc, s82, v120
	v_cvt_pk_bf16_f32 v89, v94, v95
	v_cvt_pk_bf16_f32 v90, v96, v91
	v_cvt_pk_bf16_f32 v91, v97, v98
	v_addc_co_u32_e32 v93, vcc, 0, v121, vcc
	v_add_f32_e32 v80, 1.0, v80
	global_store_dwordx4 v[92:93], v[88:91], off
	v_mul_f32_e32 v84, 0xbfb8aa3b, v84
	v_mul_f32_e32 v85, 0xbfb8aa3b, v85
	v_rcp_f32_e32 v88, v80
	v_add_f32_e32 v80, 1.0, v81
	v_mul_f32_e32 v81, 0xbfb8aa3b, v82
	v_mul_f32_e32 v86, 0xbfb8aa3b, v86
	v_mul_f32_e32 v87, 0xbfb8aa3b, v87
	v_exp_f32_e32 v81, v81
	v_mul_f32_e32 v82, 0xbfb8aa3b, v83
	v_exp_f32_e32 v84, v84
	v_exp_f32_e32 v85, v85
	v_exp_f32_e32 v86, v86
	v_exp_f32_e32 v87, v87
	v_exp_f32_e32 v82, v82
	v_rcp_f32_e32 v83, v80
	v_add_f32_e32 v80, 1.0, v81
	v_add_f32_e32 v84, 1.0, v84
	v_add_f32_e32 v85, 1.0, v85
	v_add_f32_e32 v86, 1.0, v86
	v_add_f32_e32 v87, 1.0, v87
	v_rcp_f32_e32 v89, v80
	v_add_f32_e32 v80, 1.0, v82
	v_mul_f32_e32 v72, 0xbfb8aa3b, v72
	v_rcp_f32_e32 v84, v84
	v_rcp_f32_e32 v85, v85
	v_rcp_f32_e32 v86, v86
	v_rcp_f32_e32 v87, v87
	v_rcp_f32_e32 v90, v80
	v_exp_f32_e32 v72, v72
	v_mul_f32_e32 v73, 0xbfb8aa3b, v73
	v_exp_f32_e32 v73, v73
	v_cvt_pk_bf16_f32 v80, v84, v85
	v_cvt_pk_bf16_f32 v81, v86, v87
	v_cvt_pk_bf16_f32 v82, v88, v83
	v_cvt_pk_bf16_f32 v83, v89, v90
	v_add_f32_e32 v72, 1.0, v72
	global_store_dwordx4 v[92:93], v[80:83], off offset:1024
	v_mul_f32_e32 v76, 0xbfb8aa3b, v76
	v_mul_f32_e32 v77, 0xbfb8aa3b, v77
	v_rcp_f32_e32 v80, v72
	v_add_f32_e32 v72, 1.0, v73
	v_mul_f32_e32 v73, 0xbfb8aa3b, v74
	v_mul_f32_e32 v78, 0xbfb8aa3b, v78
	v_mul_f32_e32 v79, 0xbfb8aa3b, v79
	v_exp_f32_e32 v73, v73
	v_mul_f32_e32 v74, 0xbfb8aa3b, v75
	v_exp_f32_e32 v76, v76
	v_exp_f32_e32 v77, v77
	v_exp_f32_e32 v78, v78
	v_exp_f32_e32 v79, v79
	v_exp_f32_e32 v74, v74
	v_rcp_f32_e32 v75, v72
	v_add_f32_e32 v72, 1.0, v73
	v_add_f32_e32 v76, 1.0, v76
	v_add_f32_e32 v77, 1.0, v77
	v_add_f32_e32 v78, 1.0, v78
	v_add_f32_e32 v79, 1.0, v79
	v_rcp_f32_e32 v81, v72
	v_add_f32_e32 v72, 1.0, v74
	v_mul_f32_e32 v64, 0xbfb8aa3b, v64
	v_rcp_f32_e32 v76, v76
	v_rcp_f32_e32 v77, v77
	v_rcp_f32_e32 v78, v78
	v_rcp_f32_e32 v79, v79
	v_rcp_f32_e32 v82, v72
	v_exp_f32_e32 v64, v64
	v_mul_f32_e32 v65, 0xbfb8aa3b, v65
	v_exp_f32_e32 v65, v65
	v_cvt_pk_bf16_f32 v72, v76, v77
	v_cvt_pk_bf16_f32 v73, v78, v79
	v_cvt_pk_bf16_f32 v74, v80, v75
	v_cvt_pk_bf16_f32 v75, v81, v82
	v_add_f32_e32 v64, 1.0, v64
	global_store_dwordx4 v[92:93], v[72:75], off offset:2048
	v_mul_f32_e32 v68, 0xbfb8aa3b, v68
	v_mul_f32_e32 v69, 0xbfb8aa3b, v69
	v_rcp_f32_e32 v72, v64
	v_add_f32_e32 v64, 1.0, v65
	v_mul_f32_e32 v65, 0xbfb8aa3b, v66
	v_mul_f32_e32 v70, 0xbfb8aa3b, v70
	v_mul_f32_e32 v71, 0xbfb8aa3b, v71
	v_exp_f32_e32 v65, v65
	v_mul_f32_e32 v66, 0xbfb8aa3b, v67
	v_exp_f32_e32 v68, v68
	v_exp_f32_e32 v69, v69
	v_exp_f32_e32 v70, v70
	v_exp_f32_e32 v71, v71
	v_exp_f32_e32 v66, v66
	v_rcp_f32_e32 v67, v64
	v_add_f32_e32 v64, 1.0, v65
	v_add_f32_e32 v68, 1.0, v68
	v_add_f32_e32 v69, 1.0, v69
	v_add_f32_e32 v70, 1.0, v70
	v_add_f32_e32 v71, 1.0, v71
	v_rcp_f32_e32 v73, v64
	v_add_f32_e32 v64, 1.0, v66
	v_mul_f32_e32 v56, 0xbfb8aa3b, v56
	v_rcp_f32_e32 v68, v68
	v_rcp_f32_e32 v69, v69
	v_rcp_f32_e32 v70, v70
	v_rcp_f32_e32 v71, v71
	v_rcp_f32_e32 v74, v64
	v_exp_f32_e32 v56, v56
	v_mul_f32_e32 v57, 0xbfb8aa3b, v57
	v_exp_f32_e32 v57, v57
	v_cvt_pk_bf16_f32 v64, v68, v69
	v_cvt_pk_bf16_f32 v65, v70, v71
	v_cvt_pk_bf16_f32 v66, v72, v67
	v_cvt_pk_bf16_f32 v67, v73, v74
	v_add_f32_e32 v56, 1.0, v56
	v_mul_f32_e32 v60, 0xbfb8aa3b, v60
	v_mul_f32_e32 v61, 0xbfb8aa3b, v61
	global_store_dwordx4 v[92:93], v[64:67], off offset:3072
	v_exp_f32_e32 v60, v60
	v_exp_f32_e32 v61, v61
	v_rcp_f32_e32 v64, v56
	v_add_f32_e32 v56, 1.0, v57
	v_mul_f32_e32 v57, 0xbfb8aa3b, v58
	v_mul_f32_e32 v62, 0xbfb8aa3b, v62
	v_mul_f32_e32 v63, 0xbfb8aa3b, v63
	v_exp_f32_e32 v57, v57
	v_mul_f32_e32 v58, 0xbfb8aa3b, v59
	v_exp_f32_e32 v62, v62
	v_exp_f32_e32 v63, v63
	v_exp_f32_e32 v58, v58
	v_add_f32_e32 v60, 1.0, v60
	v_add_f32_e32 v61, 1.0, v61
	v_rcp_f32_e32 v59, v56
	v_add_f32_e32 v56, 1.0, v57
	v_rcp_f32_e32 v60, v60
	v_rcp_f32_e32 v61, v61
	v_add_f32_e32 v62, 1.0, v62
	v_add_f32_e32 v63, 1.0, v63
	v_rcp_f32_e32 v65, v56
	v_add_f32_e32 v56, 1.0, v58
	v_mul_f32_e32 v48, 0xbfb8aa3b, v48
	v_rcp_f32_e32 v62, v62
	v_rcp_f32_e32 v63, v63
	v_rcp_f32_e32 v66, v56
	v_exp_f32_e32 v48, v48
	v_mul_f32_e32 v49, 0xbfb8aa3b, v49
	v_exp_f32_e32 v49, v49
	v_cvt_pk_bf16_f32 v56, v60, v61
	v_add_co_u32_e32 v60, vcc, s51, v120
	v_cvt_pk_bf16_f32 v57, v62, v63
	v_cvt_pk_bf16_f32 v58, v64, v59
	v_cvt_pk_bf16_f32 v59, v65, v66
	v_addc_co_u32_e32 v61, vcc, 0, v121, vcc
	v_add_f32_e32 v48, 1.0, v48
	global_store_dwordx4 v[60:61], v[56:59], off
	v_mul_f32_e32 v52, 0xbfb8aa3b, v52
	v_mul_f32_e32 v53, 0xbfb8aa3b, v53
	v_rcp_f32_e32 v56, v48
	v_add_f32_e32 v48, 1.0, v49
	v_mul_f32_e32 v49, 0xbfb8aa3b, v50
	v_mul_f32_e32 v54, 0xbfb8aa3b, v54
	v_mul_f32_e32 v55, 0xbfb8aa3b, v55
	v_exp_f32_e32 v49, v49
	v_mul_f32_e32 v50, 0xbfb8aa3b, v51
	v_exp_f32_e32 v52, v52
	v_exp_f32_e32 v53, v53
	v_exp_f32_e32 v54, v54
	v_exp_f32_e32 v55, v55
	v_exp_f32_e32 v50, v50
	v_rcp_f32_e32 v51, v48
	v_add_f32_e32 v48, 1.0, v49
	v_add_f32_e32 v52, 1.0, v52
	v_add_f32_e32 v53, 1.0, v53
	v_add_f32_e32 v54, 1.0, v54
	v_add_f32_e32 v55, 1.0, v55
	v_rcp_f32_e32 v57, v48
	v_add_f32_e32 v48, 1.0, v50
	v_mul_f32_e32 v40, 0xbfb8aa3b, v40
	v_rcp_f32_e32 v52, v52
	v_rcp_f32_e32 v53, v53
	v_rcp_f32_e32 v54, v54
	v_rcp_f32_e32 v55, v55
	v_rcp_f32_e32 v58, v48
	v_exp_f32_e32 v40, v40
	v_mul_f32_e32 v41, 0xbfb8aa3b, v41
	v_exp_f32_e32 v41, v41
	v_cvt_pk_bf16_f32 v48, v52, v53
	v_cvt_pk_bf16_f32 v49, v54, v55
	v_cvt_pk_bf16_f32 v50, v56, v51
	v_cvt_pk_bf16_f32 v51, v57, v58
	v_add_f32_e32 v40, 1.0, v40
	global_store_dwordx4 v[60:61], v[48:51], off offset:1024
	v_mul_f32_e32 v44, 0xbfb8aa3b, v44
	v_mul_f32_e32 v45, 0xbfb8aa3b, v45
	v_rcp_f32_e32 v48, v40
	v_add_f32_e32 v40, 1.0, v41
	v_mul_f32_e32 v41, 0xbfb8aa3b, v42
	v_mul_f32_e32 v46, 0xbfb8aa3b, v46
	v_mul_f32_e32 v47, 0xbfb8aa3b, v47
	v_exp_f32_e32 v41, v41
	v_mul_f32_e32 v42, 0xbfb8aa3b, v43
	v_exp_f32_e32 v44, v44
	v_exp_f32_e32 v45, v45
	v_exp_f32_e32 v46, v46
	v_exp_f32_e32 v47, v47
	v_exp_f32_e32 v42, v42
	v_rcp_f32_e32 v43, v40
	v_add_f32_e32 v40, 1.0, v41
	v_add_f32_e32 v44, 1.0, v44
	v_add_f32_e32 v45, 1.0, v45
	v_add_f32_e32 v46, 1.0, v46
	v_add_f32_e32 v47, 1.0, v47
	v_rcp_f32_e32 v49, v40
	v_add_f32_e32 v40, 1.0, v42
	v_mul_f32_e32 v32, 0xbfb8aa3b, v32
	v_rcp_f32_e32 v44, v44
	v_rcp_f32_e32 v45, v45
	v_rcp_f32_e32 v46, v46
	v_rcp_f32_e32 v47, v47
	v_rcp_f32_e32 v50, v40
	v_exp_f32_e32 v32, v32
	v_mul_f32_e32 v33, 0xbfb8aa3b, v33
	v_exp_f32_e32 v33, v33
	v_cvt_pk_bf16_f32 v40, v44, v45
	v_cvt_pk_bf16_f32 v41, v46, v47
	v_cvt_pk_bf16_f32 v42, v48, v43
	v_cvt_pk_bf16_f32 v43, v49, v50
	v_add_f32_e32 v32, 1.0, v32
	global_store_dwordx4 v[60:61], v[40:43], off offset:2048
	v_mul_f32_e32 v36, 0xbfb8aa3b, v36
	v_mul_f32_e32 v37, 0xbfb8aa3b, v37
	v_rcp_f32_e32 v40, v32
	v_add_f32_e32 v32, 1.0, v33
	v_mul_f32_e32 v33, 0xbfb8aa3b, v34
	v_mul_f32_e32 v38, 0xbfb8aa3b, v38
	v_mul_f32_e32 v39, 0xbfb8aa3b, v39
	v_exp_f32_e32 v33, v33
	v_mul_f32_e32 v34, 0xbfb8aa3b, v35
	v_exp_f32_e32 v36, v36
	v_exp_f32_e32 v37, v37
	v_exp_f32_e32 v38, v38
	v_exp_f32_e32 v39, v39
	v_exp_f32_e32 v34, v34
	v_rcp_f32_e32 v35, v32
	v_add_f32_e32 v32, 1.0, v33
	v_add_f32_e32 v36, 1.0, v36
	v_add_f32_e32 v37, 1.0, v37
	v_add_f32_e32 v38, 1.0, v38
	v_add_f32_e32 v39, 1.0, v39
	v_rcp_f32_e32 v41, v32
	v_add_f32_e32 v32, 1.0, v34
	v_mul_f32_e32 v24, 0xbfb8aa3b, v24
	v_rcp_f32_e32 v36, v36
	v_rcp_f32_e32 v37, v37
	v_rcp_f32_e32 v38, v38
	v_rcp_f32_e32 v39, v39
	v_rcp_f32_e32 v42, v32
	v_exp_f32_e32 v24, v24
	v_mul_f32_e32 v25, 0xbfb8aa3b, v25
	v_exp_f32_e32 v25, v25
	v_cvt_pk_bf16_f32 v32, v36, v37
	v_cvt_pk_bf16_f32 v33, v38, v39
	v_cvt_pk_bf16_f32 v34, v40, v35
	v_cvt_pk_bf16_f32 v35, v41, v42
	v_add_f32_e32 v24, 1.0, v24
	v_mul_f32_e32 v28, 0xbfb8aa3b, v28
	v_mul_f32_e32 v29, 0xbfb8aa3b, v29
	global_store_dwordx4 v[60:61], v[32:35], off offset:3072
	v_exp_f32_e32 v28, v28
	v_exp_f32_e32 v29, v29
	v_rcp_f32_e32 v32, v24
	v_add_f32_e32 v24, 1.0, v25
	v_mul_f32_e32 v25, 0xbfb8aa3b, v26
	v_mul_f32_e32 v30, 0xbfb8aa3b, v30
	v_mul_f32_e32 v31, 0xbfb8aa3b, v31
	v_exp_f32_e32 v25, v25
	v_mul_f32_e32 v26, 0xbfb8aa3b, v27
	v_exp_f32_e32 v30, v30
	v_exp_f32_e32 v31, v31
	v_exp_f32_e32 v26, v26
	v_add_f32_e32 v28, 1.0, v28
	v_add_f32_e32 v29, 1.0, v29
	v_rcp_f32_e32 v27, v24
	v_add_f32_e32 v24, 1.0, v25
	v_rcp_f32_e32 v28, v28
	v_rcp_f32_e32 v29, v29
	v_add_f32_e32 v30, 1.0, v30
	v_add_f32_e32 v31, 1.0, v31
	v_rcp_f32_e32 v33, v24
	v_add_f32_e32 v24, 1.0, v26
	v_mul_f32_e32 v16, 0xbfb8aa3b, v16
	v_rcp_f32_e32 v30, v30
	v_rcp_f32_e32 v31, v31
	v_rcp_f32_e32 v34, v24
	v_exp_f32_e32 v16, v16
	v_mul_f32_e32 v17, 0xbfb8aa3b, v17
	v_exp_f32_e32 v17, v17
	v_cvt_pk_bf16_f32 v24, v28, v29
	v_add_co_u32_e32 v28, vcc, s83, v120
	v_cvt_pk_bf16_f32 v25, v30, v31
	v_cvt_pk_bf16_f32 v26, v32, v27
	v_cvt_pk_bf16_f32 v27, v33, v34
	v_addc_co_u32_e32 v29, vcc, 0, v121, vcc
	v_add_f32_e32 v16, 1.0, v16
	global_store_dwordx4 v[28:29], v[24:27], off
	v_mul_f32_e32 v20, 0xbfb8aa3b, v20
	v_mul_f32_e32 v21, 0xbfb8aa3b, v21
	v_rcp_f32_e32 v24, v16
	v_add_f32_e32 v16, 1.0, v17
	v_mul_f32_e32 v17, 0xbfb8aa3b, v18
	v_mul_f32_e32 v22, 0xbfb8aa3b, v22
	v_mul_f32_e32 v23, 0xbfb8aa3b, v23
	v_exp_f32_e32 v17, v17
	v_mul_f32_e32 v18, 0xbfb8aa3b, v19
	v_exp_f32_e32 v20, v20
	v_exp_f32_e32 v21, v21
	v_exp_f32_e32 v22, v22
	v_exp_f32_e32 v23, v23
	v_exp_f32_e32 v18, v18
	v_rcp_f32_e32 v19, v16
	v_add_f32_e32 v16, 1.0, v17
	v_add_f32_e32 v20, 1.0, v20
	v_add_f32_e32 v21, 1.0, v21
	v_add_f32_e32 v22, 1.0, v22
	v_add_f32_e32 v23, 1.0, v23
	v_rcp_f32_e32 v25, v16
	v_add_f32_e32 v16, 1.0, v18
	v_mul_f32_e32 v8, 0xbfb8aa3b, v8
	v_rcp_f32_e32 v20, v20
	v_rcp_f32_e32 v21, v21
	v_rcp_f32_e32 v22, v22
	v_rcp_f32_e32 v23, v23
	v_rcp_f32_e32 v26, v16
	v_exp_f32_e32 v8, v8
	v_mul_f32_e32 v9, 0xbfb8aa3b, v9
	v_exp_f32_e32 v9, v9
	v_cvt_pk_bf16_f32 v16, v20, v21
	v_cvt_pk_bf16_f32 v17, v22, v23
	v_cvt_pk_bf16_f32 v18, v24, v19
	v_cvt_pk_bf16_f32 v19, v25, v26
	v_add_f32_e32 v8, 1.0, v8
	global_store_dwordx4 v[28:29], v[16:19], off offset:1024
	v_mul_f32_e32 v12, 0xbfb8aa3b, v12
	v_mul_f32_e32 v13, 0xbfb8aa3b, v13
	v_rcp_f32_e32 v16, v8
	v_add_f32_e32 v8, 1.0, v9
	v_mul_f32_e32 v9, 0xbfb8aa3b, v10
	v_mul_f32_e32 v14, 0xbfb8aa3b, v14
	v_mul_f32_e32 v15, 0xbfb8aa3b, v15
	v_exp_f32_e32 v9, v9
	v_mul_f32_e32 v10, 0xbfb8aa3b, v11
	v_exp_f32_e32 v12, v12
	v_exp_f32_e32 v13, v13
	v_exp_f32_e32 v14, v14
	v_exp_f32_e32 v15, v15
	v_exp_f32_e32 v10, v10
	v_rcp_f32_e32 v11, v8
	v_add_f32_e32 v8, 1.0, v9
	v_add_f32_e32 v12, 1.0, v12
	v_add_f32_e32 v13, 1.0, v13
	v_add_f32_e32 v14, 1.0, v14
	v_add_f32_e32 v15, 1.0, v15
	v_rcp_f32_e32 v17, v8
	v_add_f32_e32 v8, 1.0, v10
	v_mul_f32_e32 v0, 0xbfb8aa3b, v0
	v_rcp_f32_e32 v12, v12
	v_rcp_f32_e32 v13, v13
	v_rcp_f32_e32 v14, v14
	v_rcp_f32_e32 v15, v15
	v_rcp_f32_e32 v18, v8
	v_exp_f32_e32 v0, v0
	v_mul_f32_e32 v1, 0xbfb8aa3b, v1
	v_exp_f32_e32 v1, v1
	v_cvt_pk_bf16_f32 v8, v12, v13
	v_cvt_pk_bf16_f32 v9, v14, v15
	v_cvt_pk_bf16_f32 v10, v16, v11
	v_cvt_pk_bf16_f32 v11, v17, v18
	v_add_f32_e32 v0, 1.0, v0
	v_mul_f32_e32 v4, 0xbfb8aa3b, v4
	v_mul_f32_e32 v5, 0xbfb8aa3b, v5
	global_store_dwordx4 v[28:29], v[8:11], off offset:2048
	v_exp_f32_e32 v4, v4
	v_exp_f32_e32 v5, v5
	v_rcp_f32_e32 v8, v0
	v_add_f32_e32 v0, 1.0, v1
	v_mul_f32_e32 v1, 0xbfb8aa3b, v2
	v_mul_f32_e32 v6, 0xbfb8aa3b, v6
	v_mul_f32_e32 v7, 0xbfb8aa3b, v7
	v_exp_f32_e32 v1, v1
	v_mul_f32_e32 v2, 0xbfb8aa3b, v3
	v_exp_f32_e32 v6, v6
	v_exp_f32_e32 v7, v7
	v_exp_f32_e32 v2, v2
	v_add_f32_e32 v4, 1.0, v4
	v_add_f32_e32 v5, 1.0, v5
	v_rcp_f32_e32 v3, v0
	v_add_f32_e32 v0, 1.0, v1
	v_rcp_f32_e32 v4, v4
	v_rcp_f32_e32 v5, v5
	v_add_f32_e32 v6, 1.0, v6
	v_add_f32_e32 v7, 1.0, v7
	v_rcp_f32_e32 v9, v0
	v_add_f32_e32 v0, 1.0, v2
	v_rcp_f32_e32 v6, v6
	v_rcp_f32_e32 v7, v7
	v_rcp_f32_e32 v10, v0
	v_cvt_pk_bf16_f32 v0, v4, v5
	v_cndmask_b32_e64 v4, 0, 1, s[14:15]
	v_cvt_pk_bf16_f32 v1, v6, v7
	v_cvt_pk_bf16_f32 v2, v8, v3
	v_cvt_pk_bf16_f32 v3, v9, v10
	v_cmp_ne_u32_e64 s[0:1], 1, v4
	s_andn2_b64 vcc, exec, s[14:15]
	global_store_dwordx4 v[28:29], v[0:3], off offset:3072
	s_cbranch_vccnz .LBB0_760
	s_barrier

.LBB0_764:
	v_mul_f32_e32 v124, 0xbfb8aa3b, v124
	v_mul_f32_e32 v125, 0xbfb8aa3b, v125
	v_mul_f32_e32 v120, 0xbfb8aa3b, v120
	v_mul_f32_e32 v121, 0xbfb8aa3b, v121
	v_mul_f32_e32 v122, 0xbfb8aa3b, v122
	v_exp_f32_e32 v124, v124
	v_exp_f32_e32 v125, v125
	v_mul_f32_e32 v126, 0xbfb8aa3b, v126
	v_mul_f32_e32 v127, 0xbfb8aa3b, v127
	v_exp_f32_e32 v120, v120
	v_exp_f32_e32 v121, v121
	v_exp_f32_e32 v122, v122
	v_mul_f32_e32 v123, 0xbfb8aa3b, v123
	v_exp_f32_e32 v126, v126
	v_exp_f32_e32 v127, v127
	v_exp_f32_e32 v123, v123
	v_mov_b32_e32 v128, v182
	v_add_f32_e32 v124, 1.0, v124
	v_add_f32_e32 v125, 1.0, v125
	v_add_f32_e32 v120, 1.0, v120
	v_add_f32_e32 v121, 1.0, v121
	v_add_f32_e32 v122, 1.0, v122
	v_rcp_f32_e32 v124, v124
	v_rcp_f32_e32 v125, v125
	v_add_f32_e32 v126, 1.0, v126
	v_add_f32_e32 v127, 1.0, v127
	v_rcp_f32_e32 v120, v120
	v_rcp_f32_e32 v121, v121
	v_rcp_f32_e32 v130, v122
	v_add_f32_e32 v122, 1.0, v123
	v_mul_f32_e32 v112, 0xbfb8aa3b, v112
	v_and_b32_e32 v128, 63, v128
	v_rcp_f32_e32 v126, v126
	v_rcp_f32_e32 v127, v127
	v_rcp_f32_e32 v131, v122
	v_exp_f32_e32 v112, v112
	v_mul_f32_e32 v113, 0xbfb8aa3b, v113
	s_mov_b64 s[2:3], s[16:17]
	s_add_i32 s10, s36, 8
	s_mov_b32 s11, s13
	v_ashrrev_i32_e32 v129, 31, v128
	v_exp_f32_e32 v113, v113
	s_lshl_b64 s[30:31], s[10:11], 17
	v_lshl_add_u64 v[128:129], v[128:129], 4, s[2:3]
	v_cvt_pk_bf16_f32 v122, v124, v125
	v_cvt_pk_bf16_f32 v124, v120, v121
	v_lshl_add_u64 v[120:121], v[128:129], 0, s[30:31]
	v_cvt_pk_bf16_f32 v123, v126, v127
	v_cvt_pk_bf16_f32 v125, v130, v131
	v_lshl_add_u64 v[120:121], v[120:121], 0, s[22:23]
	v_add_f32_e32 v112, 1.0, v112
	global_store_dwordx4 v[120:121], v[122:125], off
	v_mul_f32_e32 v116, 0xbfb8aa3b, v116
	v_mul_f32_e32 v117, 0xbfb8aa3b, v117
	v_rcp_f32_e32 v122, v112
	v_add_f32_e32 v112, 1.0, v113
	v_mul_f32_e32 v113, 0xbfb8aa3b, v114
	v_mul_f32_e32 v118, 0xbfb8aa3b, v118
	v_mul_f32_e32 v119, 0xbfb8aa3b, v119
	v_exp_f32_e32 v113, v113
	v_mul_f32_e32 v114, 0xbfb8aa3b, v115
	v_exp_f32_e32 v116, v116
	v_exp_f32_e32 v117, v117
	v_exp_f32_e32 v118, v118
	v_exp_f32_e32 v119, v119
	v_exp_f32_e32 v114, v114
	v_rcp_f32_e32 v115, v112
	v_add_f32_e32 v112, 1.0, v113
	v_add_f32_e32 v116, 1.0, v116
	v_add_f32_e32 v117, 1.0, v117
	v_add_f32_e32 v118, 1.0, v118
	v_add_f32_e32 v119, 1.0, v119
	v_rcp_f32_e32 v123, v112
	v_add_f32_e32 v112, 1.0, v114
	v_mul_f32_e32 v104, 0xbfb8aa3b, v104
	v_rcp_f32_e32 v116, v116
	v_rcp_f32_e32 v117, v117
	v_rcp_f32_e32 v118, v118
	v_rcp_f32_e32 v119, v119
	v_rcp_f32_e32 v124, v112
	v_exp_f32_e32 v104, v104
	v_mul_f32_e32 v105, 0xbfb8aa3b, v105
	v_exp_f32_e32 v105, v105
	v_cvt_pk_bf16_f32 v112, v116, v117
	v_cvt_pk_bf16_f32 v113, v118, v119
	v_cvt_pk_bf16_f32 v114, v122, v115
	v_cvt_pk_bf16_f32 v115, v123, v124
	v_add_f32_e32 v104, 1.0, v104
	global_store_dwordx4 v[120:121], v[112:115], off offset:1024
	v_mul_f32_e32 v108, 0xbfb8aa3b, v108
	v_mul_f32_e32 v109, 0xbfb8aa3b, v109
	v_rcp_f32_e32 v112, v104
	v_add_f32_e32 v104, 1.0, v105
	v_mul_f32_e32 v105, 0xbfb8aa3b, v106
	v_mul_f32_e32 v110, 0xbfb8aa3b, v110
	v_mul_f32_e32 v111, 0xbfb8aa3b, v111
	v_exp_f32_e32 v105, v105
	v_mul_f32_e32 v106, 0xbfb8aa3b, v107
	v_exp_f32_e32 v108, v108
	v_exp_f32_e32 v109, v109
	v_exp_f32_e32 v110, v110
	v_exp_f32_e32 v111, v111
	v_exp_f32_e32 v106, v106
	v_rcp_f32_e32 v107, v104
	v_add_f32_e32 v104, 1.0, v105
	v_add_f32_e32 v108, 1.0, v108
	v_add_f32_e32 v109, 1.0, v109
	v_add_f32_e32 v110, 1.0, v110
	v_add_f32_e32 v111, 1.0, v111
	v_rcp_f32_e32 v113, v104
	v_add_f32_e32 v104, 1.0, v106
	v_mul_f32_e32 v96, 0xbfb8aa3b, v96
	v_rcp_f32_e32 v108, v108
	v_rcp_f32_e32 v109, v109
	v_rcp_f32_e32 v110, v110
	v_rcp_f32_e32 v111, v111
	v_rcp_f32_e32 v114, v104
	v_exp_f32_e32 v96, v96
	v_mul_f32_e32 v97, 0xbfb8aa3b, v97
	v_exp_f32_e32 v97, v97
	v_cvt_pk_bf16_f32 v104, v108, v109
	v_cvt_pk_bf16_f32 v105, v110, v111
	v_cvt_pk_bf16_f32 v106, v112, v107
	v_cvt_pk_bf16_f32 v107, v113, v114
	v_add_f32_e32 v96, 1.0, v96
	global_store_dwordx4 v[120:121], v[104:107], off offset:2048
	v_mul_f32_e32 v100, 0xbfb8aa3b, v100
	v_mul_f32_e32 v101, 0xbfb8aa3b, v101
	v_rcp_f32_e32 v104, v96
	v_add_f32_e32 v96, 1.0, v97
	v_mul_f32_e32 v97, 0xbfb8aa3b, v98
	v_mul_f32_e32 v102, 0xbfb8aa3b, v102
	v_mul_f32_e32 v103, 0xbfb8aa3b, v103
	v_exp_f32_e32 v97, v97
	v_mul_f32_e32 v98, 0xbfb8aa3b, v99
	v_exp_f32_e32 v100, v100
	v_exp_f32_e32 v101, v101
	v_exp_f32_e32 v102, v102
	v_exp_f32_e32 v103, v103
	v_exp_f32_e32 v98, v98
	v_rcp_f32_e32 v99, v96
	v_add_f32_e32 v96, 1.0, v97
	v_add_f32_e32 v100, 1.0, v100
	v_add_f32_e32 v101, 1.0, v101
	v_add_f32_e32 v102, 1.0, v102
	v_add_f32_e32 v103, 1.0, v103
	v_rcp_f32_e32 v105, v96
	v_add_f32_e32 v96, 1.0, v98
	v_mul_f32_e32 v88, 0xbfb8aa3b, v88
	v_rcp_f32_e32 v100, v100
	v_rcp_f32_e32 v101, v101
	v_rcp_f32_e32 v102, v102
	v_rcp_f32_e32 v103, v103
	v_rcp_f32_e32 v106, v96
	v_exp_f32_e32 v88, v88
	v_mul_f32_e32 v89, 0xbfb8aa3b, v89
	v_exp_f32_e32 v89, v89
	v_cvt_pk_bf16_f32 v96, v100, v101
	v_cvt_pk_bf16_f32 v97, v102, v103
	v_cvt_pk_bf16_f32 v98, v104, v99
	v_cvt_pk_bf16_f32 v99, v105, v106
	v_add_f32_e32 v88, 1.0, v88
	v_mul_f32_e32 v92, 0xbfb8aa3b, v92
	v_mul_f32_e32 v93, 0xbfb8aa3b, v93
	global_store_dwordx4 v[120:121], v[96:99], off offset:3072
	v_exp_f32_e32 v92, v92
	v_exp_f32_e32 v93, v93
	v_rcp_f32_e32 v96, v88
	v_add_f32_e32 v88, 1.0, v89
	v_mul_f32_e32 v89, 0xbfb8aa3b, v90
	v_mul_f32_e32 v94, 0xbfb8aa3b, v94
	v_mul_f32_e32 v95, 0xbfb8aa3b, v95
	v_exp_f32_e32 v89, v89
	v_mul_f32_e32 v90, 0xbfb8aa3b, v91
	v_exp_f32_e32 v94, v94
	v_exp_f32_e32 v95, v95
	v_exp_f32_e32 v90, v90
	v_add_f32_e32 v92, 1.0, v92
	v_add_f32_e32 v93, 1.0, v93
	v_rcp_f32_e32 v91, v88
	v_add_f32_e32 v88, 1.0, v89
	v_rcp_f32_e32 v92, v92
	v_rcp_f32_e32 v93, v93
	v_add_f32_e32 v94, 1.0, v94
	v_add_f32_e32 v95, 1.0, v95
	v_rcp_f32_e32 v97, v88
	v_add_f32_e32 v88, 1.0, v90
	v_mul_f32_e32 v80, 0xbfb8aa3b, v80
	v_rcp_f32_e32 v94, v94
	v_rcp_f32_e32 v95, v95
	v_rcp_f32_e32 v98, v88
	v_exp_f32_e32 v80, v80
	v_mul_f32_e32 v81, 0xbfb8aa3b, v81
	v_exp_f32_e32 v81, v81
	v_cvt_pk_bf16_f32 v88, v92, v93
	v_add_co_u32_e32 v92, vcc, s82, v120
	v_cvt_pk_bf16_f32 v89, v94, v95
	v_cvt_pk_bf16_f32 v90, v96, v91
	v_cvt_pk_bf16_f32 v91, v97, v98
	v_addc_co_u32_e32 v93, vcc, 0, v121, vcc
	v_add_f32_e32 v80, 1.0, v80
	global_store_dwordx4 v[92:93], v[88:91], off
	v_mul_f32_e32 v84, 0xbfb8aa3b, v84
	v_mul_f32_e32 v85, 0xbfb8aa3b, v85
	v_rcp_f32_e32 v88, v80
	v_add_f32_e32 v80, 1.0, v81
	v_mul_f32_e32 v81, 0xbfb8aa3b, v82
	v_mul_f32_e32 v86, 0xbfb8aa3b, v86
	v_mul_f32_e32 v87, 0xbfb8aa3b, v87
	v_exp_f32_e32 v81, v81
	v_mul_f32_e32 v82, 0xbfb8aa3b, v83
	v_exp_f32_e32 v84, v84
	v_exp_f32_e32 v85, v85
	v_exp_f32_e32 v86, v86
	v_exp_f32_e32 v87, v87
	v_exp_f32_e32 v82, v82
	v_rcp_f32_e32 v83, v80
	v_add_f32_e32 v80, 1.0, v81
	v_add_f32_e32 v84, 1.0, v84
	v_add_f32_e32 v85, 1.0, v85
	v_add_f32_e32 v86, 1.0, v86
	v_add_f32_e32 v87, 1.0, v87
	v_rcp_f32_e32 v89, v80
	v_add_f32_e32 v80, 1.0, v82
	v_mul_f32_e32 v72, 0xbfb8aa3b, v72
	v_rcp_f32_e32 v84, v84
	v_rcp_f32_e32 v85, v85
	v_rcp_f32_e32 v86, v86
	v_rcp_f32_e32 v87, v87
	v_rcp_f32_e32 v90, v80
	v_exp_f32_e32 v72, v72
	v_mul_f32_e32 v73, 0xbfb8aa3b, v73
	v_exp_f32_e32 v73, v73
	v_cvt_pk_bf16_f32 v80, v84, v85
	v_cvt_pk_bf16_f32 v81, v86, v87
	v_cvt_pk_bf16_f32 v82, v88, v83
	v_cvt_pk_bf16_f32 v83, v89, v90
	v_add_f32_e32 v72, 1.0, v72
	global_store_dwordx4 v[92:93], v[80:83], off offset:1024
	v_mul_f32_e32 v76, 0xbfb8aa3b, v76
	v_mul_f32_e32 v77, 0xbfb8aa3b, v77
	v_rcp_f32_e32 v80, v72
	v_add_f32_e32 v72, 1.0, v73
	v_mul_f32_e32 v73, 0xbfb8aa3b, v74
	v_mul_f32_e32 v78, 0xbfb8aa3b, v78
	v_mul_f32_e32 v79, 0xbfb8aa3b, v79
	v_exp_f32_e32 v73, v73
	v_mul_f32_e32 v74, 0xbfb8aa3b, v75
	v_exp_f32_e32 v76, v76
	v_exp_f32_e32 v77, v77
	v_exp_f32_e32 v78, v78
	v_exp_f32_e32 v79, v79
	v_exp_f32_e32 v74, v74
	v_rcp_f32_e32 v75, v72
	v_add_f32_e32 v72, 1.0, v73
	v_add_f32_e32 v76, 1.0, v76
	v_add_f32_e32 v77, 1.0, v77
	v_add_f32_e32 v78, 1.0, v78
	v_add_f32_e32 v79, 1.0, v79
	v_rcp_f32_e32 v81, v72
	v_add_f32_e32 v72, 1.0, v74
	v_mul_f32_e32 v64, 0xbfb8aa3b, v64
	v_rcp_f32_e32 v76, v76
	v_rcp_f32_e32 v77, v77
	v_rcp_f32_e32 v78, v78
	v_rcp_f32_e32 v79, v79
	v_rcp_f32_e32 v82, v72
	v_exp_f32_e32 v64, v64
	v_mul_f32_e32 v65, 0xbfb8aa3b, v65
	v_exp_f32_e32 v65, v65
	v_cvt_pk_bf16_f32 v72, v76, v77
	v_cvt_pk_bf16_f32 v73, v78, v79
	v_cvt_pk_bf16_f32 v74, v80, v75
	v_cvt_pk_bf16_f32 v75, v81, v82
	v_add_f32_e32 v64, 1.0, v64
	global_store_dwordx4 v[92:93], v[72:75], off offset:2048
	v_mul_f32_e32 v68, 0xbfb8aa3b, v68
	v_mul_f32_e32 v69, 0xbfb8aa3b, v69
	v_rcp_f32_e32 v72, v64
	v_add_f32_e32 v64, 1.0, v65
	v_mul_f32_e32 v65, 0xbfb8aa3b, v66
	v_mul_f32_e32 v70, 0xbfb8aa3b, v70
	v_mul_f32_e32 v71, 0xbfb8aa3b, v71
	v_exp_f32_e32 v65, v65
	v_mul_f32_e32 v66, 0xbfb8aa3b, v67
	v_exp_f32_e32 v68, v68
	v_exp_f32_e32 v69, v69
	v_exp_f32_e32 v70, v70
	v_exp_f32_e32 v71, v71
	v_exp_f32_e32 v66, v66
	v_rcp_f32_e32 v67, v64
	v_add_f32_e32 v64, 1.0, v65
	v_add_f32_e32 v68, 1.0, v68
	v_add_f32_e32 v69, 1.0, v69
	v_add_f32_e32 v70, 1.0, v70
	v_add_f32_e32 v71, 1.0, v71
	v_rcp_f32_e32 v73, v64
	v_add_f32_e32 v64, 1.0, v66
	v_mul_f32_e32 v56, 0xbfb8aa3b, v56
	v_rcp_f32_e32 v68, v68
	v_rcp_f32_e32 v69, v69
	v_rcp_f32_e32 v70, v70
	v_rcp_f32_e32 v71, v71
	v_rcp_f32_e32 v74, v64
	v_exp_f32_e32 v56, v56
	v_mul_f32_e32 v57, 0xbfb8aa3b, v57
	v_exp_f32_e32 v57, v57
	v_cvt_pk_bf16_f32 v64, v68, v69
	v_cvt_pk_bf16_f32 v65, v70, v71
	v_cvt_pk_bf16_f32 v66, v72, v67
	v_cvt_pk_bf16_f32 v67, v73, v74
	v_add_f32_e32 v56, 1.0, v56
	v_mul_f32_e32 v60, 0xbfb8aa3b, v60
	v_mul_f32_e32 v61, 0xbfb8aa3b, v61
	global_store_dwordx4 v[92:93], v[64:67], off offset:3072
	v_exp_f32_e32 v60, v60
	v_exp_f32_e32 v61, v61
	v_rcp_f32_e32 v64, v56
	v_add_f32_e32 v56, 1.0, v57
	v_mul_f32_e32 v57, 0xbfb8aa3b, v58
	v_mul_f32_e32 v62, 0xbfb8aa3b, v62
	v_mul_f32_e32 v63, 0xbfb8aa3b, v63
	v_exp_f32_e32 v57, v57
	v_mul_f32_e32 v58, 0xbfb8aa3b, v59
	v_exp_f32_e32 v62, v62
	v_exp_f32_e32 v63, v63
	v_exp_f32_e32 v58, v58
	v_add_f32_e32 v60, 1.0, v60
	v_add_f32_e32 v61, 1.0, v61
	v_rcp_f32_e32 v59, v56
	v_add_f32_e32 v56, 1.0, v57
	v_rcp_f32_e32 v60, v60
	v_rcp_f32_e32 v61, v61
	v_add_f32_e32 v62, 1.0, v62
	v_add_f32_e32 v63, 1.0, v63
	v_rcp_f32_e32 v65, v56
	v_add_f32_e32 v56, 1.0, v58
	v_mul_f32_e32 v48, 0xbfb8aa3b, v48
	v_rcp_f32_e32 v62, v62
	v_rcp_f32_e32 v63, v63
	v_rcp_f32_e32 v66, v56
	v_exp_f32_e32 v48, v48
	v_mul_f32_e32 v49, 0xbfb8aa3b, v49
	v_exp_f32_e32 v49, v49
	v_cvt_pk_bf16_f32 v56, v60, v61
	v_add_co_u32_e32 v60, vcc, s51, v120
	v_cvt_pk_bf16_f32 v57, v62, v63
	v_cvt_pk_bf16_f32 v58, v64, v59
	v_cvt_pk_bf16_f32 v59, v65, v66
	v_addc_co_u32_e32 v61, vcc, 0, v121, vcc
	v_add_f32_e32 v48, 1.0, v48
	global_store_dwordx4 v[60:61], v[56:59], off
	v_mul_f32_e32 v52, 0xbfb8aa3b, v52
	v_mul_f32_e32 v53, 0xbfb8aa3b, v53
	v_rcp_f32_e32 v56, v48
	v_add_f32_e32 v48, 1.0, v49
	v_mul_f32_e32 v49, 0xbfb8aa3b, v50
	v_mul_f32_e32 v54, 0xbfb8aa3b, v54
	v_mul_f32_e32 v55, 0xbfb8aa3b, v55
	v_exp_f32_e32 v49, v49
	v_mul_f32_e32 v50, 0xbfb8aa3b, v51
	v_exp_f32_e32 v52, v52
	v_exp_f32_e32 v53, v53
	v_exp_f32_e32 v54, v54
	v_exp_f32_e32 v55, v55
	v_exp_f32_e32 v50, v50
	v_rcp_f32_e32 v51, v48
	v_add_f32_e32 v48, 1.0, v49
	v_add_f32_e32 v52, 1.0, v52
	v_add_f32_e32 v53, 1.0, v53
	v_add_f32_e32 v54, 1.0, v54
	v_add_f32_e32 v55, 1.0, v55
	v_rcp_f32_e32 v57, v48
	v_add_f32_e32 v48, 1.0, v50
	v_mul_f32_e32 v40, 0xbfb8aa3b, v40
	v_rcp_f32_e32 v52, v52
	v_rcp_f32_e32 v53, v53
	v_rcp_f32_e32 v54, v54
	v_rcp_f32_e32 v55, v55
	v_rcp_f32_e32 v58, v48
	v_exp_f32_e32 v40, v40
	v_mul_f32_e32 v41, 0xbfb8aa3b, v41
	v_exp_f32_e32 v41, v41
	v_cvt_pk_bf16_f32 v48, v52, v53
	v_cvt_pk_bf16_f32 v49, v54, v55
	v_cvt_pk_bf16_f32 v50, v56, v51
	v_cvt_pk_bf16_f32 v51, v57, v58
	v_add_f32_e32 v40, 1.0, v40
	global_store_dwordx4 v[60:61], v[48:51], off offset:1024
	v_mul_f32_e32 v44, 0xbfb8aa3b, v44
	v_mul_f32_e32 v45, 0xbfb8aa3b, v45
	v_rcp_f32_e32 v48, v40
	v_add_f32_e32 v40, 1.0, v41
	v_mul_f32_e32 v41, 0xbfb8aa3b, v42
	v_mul_f32_e32 v46, 0xbfb8aa3b, v46
	v_mul_f32_e32 v47, 0xbfb8aa3b, v47
	v_exp_f32_e32 v41, v41
	v_mul_f32_e32 v42, 0xbfb8aa3b, v43
	v_exp_f32_e32 v44, v44
	v_exp_f32_e32 v45, v45
	v_exp_f32_e32 v46, v46
	v_exp_f32_e32 v47, v47
	v_exp_f32_e32 v42, v42
	v_rcp_f32_e32 v43, v40
	v_add_f32_e32 v40, 1.0, v41
	v_add_f32_e32 v44, 1.0, v44
	v_add_f32_e32 v45, 1.0, v45
	v_add_f32_e32 v46, 1.0, v46
	v_add_f32_e32 v47, 1.0, v47
	v_rcp_f32_e32 v49, v40
	v_add_f32_e32 v40, 1.0, v42
	v_mul_f32_e32 v32, 0xbfb8aa3b, v32
	v_rcp_f32_e32 v44, v44
	v_rcp_f32_e32 v45, v45
	v_rcp_f32_e32 v46, v46
	v_rcp_f32_e32 v47, v47
	v_rcp_f32_e32 v50, v40
	v_exp_f32_e32 v32, v32
	v_mul_f32_e32 v33, 0xbfb8aa3b, v33
	v_exp_f32_e32 v33, v33
	v_cvt_pk_bf16_f32 v40, v44, v45
	v_cvt_pk_bf16_f32 v41, v46, v47
	v_cvt_pk_bf16_f32 v42, v48, v43
	v_cvt_pk_bf16_f32 v43, v49, v50
	v_add_f32_e32 v32, 1.0, v32
	global_store_dwordx4 v[60:61], v[40:43], off offset:2048
	v_mul_f32_e32 v36, 0xbfb8aa3b, v36
	v_mul_f32_e32 v37, 0xbfb8aa3b, v37
	v_rcp_f32_e32 v40, v32
	v_add_f32_e32 v32, 1.0, v33
	v_mul_f32_e32 v33, 0xbfb8aa3b, v34
	v_mul_f32_e32 v38, 0xbfb8aa3b, v38
	v_mul_f32_e32 v39, 0xbfb8aa3b, v39
	v_exp_f32_e32 v33, v33
	v_mul_f32_e32 v34, 0xbfb8aa3b, v35
	v_exp_f32_e32 v36, v36
	v_exp_f32_e32 v37, v37
	v_exp_f32_e32 v38, v38
	v_exp_f32_e32 v39, v39
	v_exp_f32_e32 v34, v34
	v_rcp_f32_e32 v35, v32
	v_add_f32_e32 v32, 1.0, v33
	v_add_f32_e32 v36, 1.0, v36
	v_add_f32_e32 v37, 1.0, v37
	v_add_f32_e32 v38, 1.0, v38
	v_add_f32_e32 v39, 1.0, v39
	v_rcp_f32_e32 v41, v32
	v_add_f32_e32 v32, 1.0, v34
	v_mul_f32_e32 v24, 0xbfb8aa3b, v24
	v_rcp_f32_e32 v36, v36
	v_rcp_f32_e32 v37, v37
	v_rcp_f32_e32 v38, v38
	v_rcp_f32_e32 v39, v39
	v_rcp_f32_e32 v42, v32
	v_exp_f32_e32 v24, v24
	v_mul_f32_e32 v25, 0xbfb8aa3b, v25
	v_exp_f32_e32 v25, v25
	v_cvt_pk_bf16_f32 v32, v36, v37
	v_cvt_pk_bf16_f32 v33, v38, v39
	v_cvt_pk_bf16_f32 v34, v40, v35
	v_cvt_pk_bf16_f32 v35, v41, v42
	v_add_f32_e32 v24, 1.0, v24
	v_mul_f32_e32 v28, 0xbfb8aa3b, v28
	v_mul_f32_e32 v29, 0xbfb8aa3b, v29
	global_store_dwordx4 v[60:61], v[32:35], off offset:3072
	v_exp_f32_e32 v28, v28
	v_exp_f32_e32 v29, v29
	v_rcp_f32_e32 v32, v24
	v_add_f32_e32 v24, 1.0, v25
	v_mul_f32_e32 v25, 0xbfb8aa3b, v26
	v_mul_f32_e32 v30, 0xbfb8aa3b, v30
	v_mul_f32_e32 v31, 0xbfb8aa3b, v31
	v_exp_f32_e32 v25, v25
	v_mul_f32_e32 v26, 0xbfb8aa3b, v27
	v_exp_f32_e32 v30, v30
	v_exp_f32_e32 v31, v31
	v_exp_f32_e32 v26, v26
	v_add_f32_e32 v28, 1.0, v28
	v_add_f32_e32 v29, 1.0, v29
	v_rcp_f32_e32 v27, v24
	v_add_f32_e32 v24, 1.0, v25
	v_rcp_f32_e32 v28, v28
	v_rcp_f32_e32 v29, v29
	v_add_f32_e32 v30, 1.0, v30
	v_add_f32_e32 v31, 1.0, v31
	v_rcp_f32_e32 v33, v24
	v_add_f32_e32 v24, 1.0, v26
	v_mul_f32_e32 v16, 0xbfb8aa3b, v16
	v_rcp_f32_e32 v30, v30
	v_rcp_f32_e32 v31, v31
	v_rcp_f32_e32 v34, v24
	v_exp_f32_e32 v16, v16
	v_mul_f32_e32 v17, 0xbfb8aa3b, v17
	v_exp_f32_e32 v17, v17
	v_cvt_pk_bf16_f32 v24, v28, v29
	v_add_co_u32_e32 v28, vcc, s83, v120
	v_cvt_pk_bf16_f32 v25, v30, v31
	v_cvt_pk_bf16_f32 v26, v32, v27
	v_cvt_pk_bf16_f32 v27, v33, v34
	v_addc_co_u32_e32 v29, vcc, 0, v121, vcc
	v_add_f32_e32 v16, 1.0, v16
	global_store_dwordx4 v[28:29], v[24:27], off
	v_mul_f32_e32 v20, 0xbfb8aa3b, v20
	v_mul_f32_e32 v21, 0xbfb8aa3b, v21
	v_rcp_f32_e32 v24, v16
	v_add_f32_e32 v16, 1.0, v17
	v_mul_f32_e32 v17, 0xbfb8aa3b, v18
	v_mul_f32_e32 v22, 0xbfb8aa3b, v22
	v_mul_f32_e32 v23, 0xbfb8aa3b, v23
	v_exp_f32_e32 v17, v17
	v_mul_f32_e32 v18, 0xbfb8aa3b, v19
	v_exp_f32_e32 v20, v20
	v_exp_f32_e32 v21, v21
	v_exp_f32_e32 v22, v22
	v_exp_f32_e32 v23, v23
	v_exp_f32_e32 v18, v18
	v_rcp_f32_e32 v19, v16
	v_add_f32_e32 v16, 1.0, v17
	v_add_f32_e32 v20, 1.0, v20
	v_add_f32_e32 v21, 1.0, v21
	v_add_f32_e32 v22, 1.0, v22
	v_add_f32_e32 v23, 1.0, v23
	v_rcp_f32_e32 v25, v16
	v_add_f32_e32 v16, 1.0, v18
	v_mul_f32_e32 v8, 0xbfb8aa3b, v8
	v_rcp_f32_e32 v20, v20
	v_rcp_f32_e32 v21, v21
	v_rcp_f32_e32 v22, v22
	v_rcp_f32_e32 v23, v23
	v_rcp_f32_e32 v26, v16
	v_exp_f32_e32 v8, v8
	v_mul_f32_e32 v9, 0xbfb8aa3b, v9
	v_exp_f32_e32 v9, v9
	v_cvt_pk_bf16_f32 v16, v20, v21
	v_cvt_pk_bf16_f32 v17, v22, v23
	v_cvt_pk_bf16_f32 v18, v24, v19
	v_cvt_pk_bf16_f32 v19, v25, v26
	v_add_f32_e32 v8, 1.0, v8
	global_store_dwordx4 v[28:29], v[16:19], off offset:1024
	v_mul_f32_e32 v12, 0xbfb8aa3b, v12
	v_mul_f32_e32 v13, 0xbfb8aa3b, v13
	v_rcp_f32_e32 v16, v8
	v_add_f32_e32 v8, 1.0, v9
	v_mul_f32_e32 v9, 0xbfb8aa3b, v10
	v_mul_f32_e32 v14, 0xbfb8aa3b, v14
	v_mul_f32_e32 v15, 0xbfb8aa3b, v15
	v_exp_f32_e32 v9, v9
	v_mul_f32_e32 v10, 0xbfb8aa3b, v11
	v_exp_f32_e32 v12, v12
	v_exp_f32_e32 v13, v13
	v_exp_f32_e32 v14, v14
	v_exp_f32_e32 v15, v15
	v_exp_f32_e32 v10, v10
	v_rcp_f32_e32 v11, v8
	v_add_f32_e32 v8, 1.0, v9
	v_add_f32_e32 v12, 1.0, v12
	v_add_f32_e32 v13, 1.0, v13
	v_add_f32_e32 v14, 1.0, v14
	v_add_f32_e32 v15, 1.0, v15
	v_rcp_f32_e32 v17, v8
	v_add_f32_e32 v8, 1.0, v10
	v_mul_f32_e32 v0, 0xbfb8aa3b, v0
	v_rcp_f32_e32 v12, v12
	v_rcp_f32_e32 v13, v13
	v_rcp_f32_e32 v14, v14
	v_rcp_f32_e32 v15, v15
	v_rcp_f32_e32 v18, v8
	v_exp_f32_e32 v0, v0
	v_mul_f32_e32 v1, 0xbfb8aa3b, v1
	v_exp_f32_e32 v1, v1
	v_cvt_pk_bf16_f32 v8, v12, v13
	v_cvt_pk_bf16_f32 v9, v14, v15
	v_cvt_pk_bf16_f32 v10, v16, v11
	v_cvt_pk_bf16_f32 v11, v17, v18
	v_add_f32_e32 v0, 1.0, v0
	global_store_dwordx4 v[28:29], v[8:11], off offset:2048
	v_mul_f32_e32 v4, 0xbfb8aa3b, v4
	v_mul_f32_e32 v5, 0xbfb8aa3b, v5
	v_rcp_f32_e32 v8, v0
	v_add_f32_e32 v0, 1.0, v1
	v_mul_f32_e32 v1, 0xbfb8aa3b, v2
	v_mul_f32_e32 v6, 0xbfb8aa3b, v6
	v_mul_f32_e32 v7, 0xbfb8aa3b, v7
	v_exp_f32_e32 v1, v1
	v_mul_f32_e32 v2, 0xbfb8aa3b, v3
	v_exp_f32_e32 v4, v4
	v_exp_f32_e32 v5, v5
	v_exp_f32_e32 v6, v6
	v_exp_f32_e32 v7, v7
	v_exp_f32_e32 v2, v2
	v_rcp_f32_e32 v3, v0
	v_add_f32_e32 v0, 1.0, v1
	v_add_f32_e32 v4, 1.0, v4
	v_add_f32_e32 v5, 1.0, v5
	v_add_f32_e32 v6, 1.0, v6
	v_add_f32_e32 v7, 1.0, v7
	v_rcp_f32_e32 v9, v0
	v_add_f32_e32 v0, 1.0, v2
	v_rcp_f32_e32 v4, v4
	v_rcp_f32_e32 v5, v5
	v_rcp_f32_e32 v6, v6
	v_rcp_f32_e32 v7, v7
	v_rcp_f32_e32 v10, v0
	v_cvt_pk_bf16_f32 v0, v4, v5
	v_cvt_pk_bf16_f32 v2, v8, v3
	v_cvt_pk_bf16_f32 v1, v6, v7
	v_cvt_pk_bf16_f32 v3, v9, v10
	s_and_b64 vcc, exec, s[0:1]
	global_store_dwordx4 v[28:29], v[0:3], off offset:3072
	s_cbranch_vccnz .LBB0_766
	s_barrier

.LBB0_770:
	v_mov_b32_e32 v128, v182
	s_mov_b64 s[2:3], s[16:17]
	v_and_b32_e32 v128, 63, v128
	s_add_u32 s30, s30, s22
	v_ashrrev_i32_e32 v129, 31, v128
	s_addc_u32 s31, s31, s23
	v_lshl_add_u64 v[156:157], v[128:129], 4, s[2:3]
	v_lshl_add_u64 v[158:159], v[156:157], 0, s[4:5]
	v_lshl_add_u64 v[156:157], v[156:157], 0, s[30:31]
	global_load_dwordx4 v[128:131], v[158:159], off nt
	global_load_dwordx4 v[160:163], v[156:157], off
	s_waitcnt vmcnt(0) lgkmcnt(0)
	v_lshlrev_b32_e32 v172, 16, v128
	v_lshlrev_b32_e32 v136, 16, v160
	v_and_b32_e32 v173, 0xffff0000, v128
	v_lshlrev_b32_e32 v128, 16, v161
	v_rcp_f32_e32 v170, v136
	v_and_b32_e32 v136, 0xffff0000, v160
	v_rcp_f32_e32 v160, v128
	v_and_b32_e32 v128, 0xffff0000, v161
	v_rcp_f32_e32 v161, v128
	v_lshlrev_b32_e32 v128, 16, v129
	v_and_b32_e32 v129, 0xffff0000, v129
	v_rcp_f32_e32 v171, v136
	v_pk_mul_f32 v[128:129], v[160:161], v[128:129]
	v_lshlrev_b32_e32 v160, 16, v130
	v_pk_mul_f32 v[10:11], v[10:11], v[128:129]
	v_lshlrev_b32_e32 v128, 16, v162
	v_and_b32_e32 v129, 0xffff0000, v162
	v_rcp_f32_e32 v128, v128
	v_rcp_f32_e32 v129, v129
	v_and_b32_e32 v161, 0xffff0000, v130
	v_lshlrev_b32_e32 v130, 16, v131
	v_and_b32_e32 v131, 0xffff0000, v131
	v_pk_mul_f32 v[128:129], v[128:129], v[160:161]
	v_pk_mul_f32 v[170:171], v[170:171], v[172:173]
	v_pk_mul_f32 v[12:13], v[12:13], v[128:129]
	v_lshlrev_b32_e32 v128, 16, v163
	v_and_b32_e32 v129, 0xffff0000, v163
	v_rcp_f32_e32 v128, v128
	v_rcp_f32_e32 v129, v129
	v_pk_mul_f32 v[8:9], v[8:9], v[170:171]
	v_pk_mul_f32 v[128:129], v[128:129], v[130:131]
	s_nop 0
	v_pk_mul_f32 v[14:15], v[14:15], v[128:129]
	global_load_dwordx4 v[128:131], v[158:159], off offset:1024 nt
	global_load_dwordx4 v[160:163], v[156:157], off offset:1024
	s_waitcnt vmcnt(0) lgkmcnt(0)
	v_lshlrev_b32_e32 v172, 16, v128
	v_lshlrev_b32_e32 v136, 16, v160
	v_and_b32_e32 v173, 0xffff0000, v128
	v_lshlrev_b32_e32 v128, 16, v161
	v_rcp_f32_e32 v170, v136
	v_and_b32_e32 v136, 0xffff0000, v160
	v_rcp_f32_e32 v160, v128
	v_and_b32_e32 v128, 0xffff0000, v161
	v_rcp_f32_e32 v161, v128
	v_lshlrev_b32_e32 v128, 16, v129
	v_and_b32_e32 v129, 0xffff0000, v129
	v_rcp_f32_e32 v171, v136
	v_pk_mul_f32 v[128:129], v[160:161], v[128:129]
	v_lshlrev_b32_e32 v160, 16, v130
	v_pk_mul_f32 v[30:31], v[30:31], v[128:129]
	v_lshlrev_b32_e32 v128, 16, v162
	v_and_b32_e32 v129, 0xffff0000, v162
	v_rcp_f32_e32 v128, v128
	v_rcp_f32_e32 v129, v129
	v_and_b32_e32 v161, 0xffff0000, v130
	v_lshlrev_b32_e32 v130, 16, v131
	v_and_b32_e32 v131, 0xffff0000, v131
	v_pk_mul_f32 v[128:129], v[128:129], v[160:161]
	v_pk_mul_f32 v[170:171], v[170:171], v[172:173]
	v_pk_mul_f32 v[32:33], v[32:33], v[128:129]
	v_lshlrev_b32_e32 v128, 16, v163
	v_and_b32_e32 v129, 0xffff0000, v163
	v_rcp_f32_e32 v128, v128
	v_rcp_f32_e32 v129, v129
	v_pk_mul_f32 v[28:29], v[28:29], v[170:171]
	v_pk_mul_f32 v[128:129], v[128:129], v[130:131]
	s_nop 0
	v_pk_mul_f32 v[34:35], v[34:35], v[128:129]
	s_nop 0
	global_load_dwordx4 v[128:131], v[158:159], off offset:2048 nt
	global_load_dwordx4 v[160:163], v[156:157], off offset:2048
	s_waitcnt vmcnt(0) lgkmcnt(0)
	v_lshlrev_b32_e32 v172, 16, v128
	v_lshlrev_b32_e32 v136, 16, v160
	v_and_b32_e32 v173, 0xffff0000, v128
	v_lshlrev_b32_e32 v128, 16, v161
	v_rcp_f32_e32 v170, v136
	v_and_b32_e32 v136, 0xffff0000, v160
	v_rcp_f32_e32 v160, v128
	v_and_b32_e32 v128, 0xffff0000, v161
	v_rcp_f32_e32 v161, v128
	v_lshlrev_b32_e32 v128, 16, v129
	v_and_b32_e32 v129, 0xffff0000, v129
	v_rcp_f32_e32 v171, v136
	v_pk_mul_f32 v[128:129], v[160:161], v[128:129]
	v_lshlrev_b32_e32 v160, 16, v130
	v_pk_mul_f32 v[42:43], v[42:43], v[128:129]
	v_lshlrev_b32_e32 v128, 16, v162
	v_and_b32_e32 v129, 0xffff0000, v162
	v_rcp_f32_e32 v128, v128
	v_rcp_f32_e32 v129, v129
	v_and_b32_e32 v161, 0xffff0000, v130
	v_lshlrev_b32_e32 v130, 16, v131
	v_and_b32_e32 v131, 0xffff0000, v131
	v_pk_mul_f32 v[128:129], v[128:129], v[160:161]
	v_pk_mul_f32 v[170:171], v[170:171], v[172:173]
	v_pk_mul_f32 v[44:45], v[44:45], v[128:129]
	v_lshlrev_b32_e32 v128, 16, v163
	v_and_b32_e32 v129, 0xffff0000, v163
	v_rcp_f32_e32 v128, v128
	v_rcp_f32_e32 v129, v129
	v_pk_mul_f32 v[40:41], v[40:41], v[170:171]
	v_pk_mul_f32 v[128:129], v[128:129], v[130:131]
	s_nop 0
	v_pk_mul_f32 v[46:47], v[46:47], v[128:129]
	global_load_dwordx4 v[128:131], v[158:159], off offset:3072 nt
	global_load_dwordx4 v[160:163], v[156:157], off offset:3072
	s_waitcnt vmcnt(0) lgkmcnt(0)
	v_lshlrev_b32_e32 v172, 16, v128
	v_lshlrev_b32_e32 v136, 16, v160
	v_and_b32_e32 v173, 0xffff0000, v128
	v_lshlrev_b32_e32 v128, 16, v161
	v_rcp_f32_e32 v170, v136
	v_and_b32_e32 v136, 0xffff0000, v160
	v_rcp_f32_e32 v160, v128
	v_and_b32_e32 v128, 0xffff0000, v161
	v_rcp_f32_e32 v161, v128
	v_lshlrev_b32_e32 v128, 16, v129
	v_and_b32_e32 v129, 0xffff0000, v129
	v_rcp_f32_e32 v171, v136
	v_pk_mul_f32 v[128:129], v[160:161], v[128:129]
	v_lshlrev_b32_e32 v160, 16, v130
	v_pk_mul_f32 v[50:51], v[50:51], v[128:129]
	v_lshlrev_b32_e32 v128, 16, v162
	v_and_b32_e32 v129, 0xffff0000, v162
	v_rcp_f32_e32 v128, v128
	v_rcp_f32_e32 v129, v129
	v_and_b32_e32 v161, 0xffff0000, v130
	v_lshlrev_b32_e32 v130, 16, v131
	v_and_b32_e32 v131, 0xffff0000, v131
	v_pk_mul_f32 v[128:129], v[128:129], v[160:161]
	v_add_co_u32_e32 v160, vcc, s82, v158
	v_pk_mul_f32 v[52:53], v[52:53], v[128:129]
	v_lshlrev_b32_e32 v128, 16, v163
	v_and_b32_e32 v129, 0xffff0000, v163
	v_rcp_f32_e32 v128, v128
	v_rcp_f32_e32 v129, v129
	v_pk_mul_f32 v[170:171], v[170:171], v[172:173]
	v_addc_co_u32_e32 v161, vcc, 0, v159, vcc
	v_pk_mul_f32 v[128:129], v[128:129], v[130:131]
	v_pk_mul_f32 v[48:49], v[48:49], v[170:171]
	v_pk_mul_f32 v[54:55], v[54:55], v[128:129]
	v_add_co_u32_e32 v162, vcc, s82, v156
	global_load_dwordx4 v[128:131], v[160:161], off nt
	s_nop 0
	v_addc_co_u32_e32 v163, vcc, 0, v157, vcc
	global_load_dwordx4 v[170:173], v[162:163], off
	s_waitcnt vmcnt(0) lgkmcnt(0)
	v_lshlrev_b32_e32 v176, 16, v128
	v_and_b32_e32 v177, 0xffff0000, v128
	v_lshlrev_b32_e32 v136, 16, v170
	v_lshlrev_b32_e32 v128, 16, v171
	v_rcp_f32_e32 v174, v136
	v_and_b32_e32 v136, 0xffff0000, v170
	v_rcp_f32_e32 v170, v128
	v_and_b32_e32 v128, 0xffff0000, v171
	v_rcp_f32_e32 v171, v128
	v_lshlrev_b32_e32 v128, 16, v129
	v_and_b32_e32 v129, 0xffff0000, v129
	v_rcp_f32_e32 v175, v136
	v_pk_mul_f32 v[128:129], v[170:171], v[128:129]
	v_lshlrev_b32_e32 v170, 16, v130
	v_pk_mul_f32 v[66:67], v[66:67], v[128:129]
	v_lshlrev_b32_e32 v128, 16, v172
	v_and_b32_e32 v129, 0xffff0000, v172
	v_rcp_f32_e32 v128, v128
	v_rcp_f32_e32 v129, v129
	v_and_b32_e32 v171, 0xffff0000, v130
	v_lshlrev_b32_e32 v130, 16, v131
	v_and_b32_e32 v131, 0xffff0000, v131
	v_pk_mul_f32 v[128:129], v[128:129], v[170:171]
	v_pk_mul_f32 v[174:175], v[174:175], v[176:177]
	v_pk_mul_f32 v[68:69], v[68:69], v[128:129]
	v_lshlrev_b32_e32 v128, 16, v173
	v_and_b32_e32 v129, 0xffff0000, v173
	v_rcp_f32_e32 v128, v128
	v_rcp_f32_e32 v129, v129
	v_pk_mul_f32 v[64:65], v[64:65], v[174:175]
	v_pk_mul_f32 v[128:129], v[128:129], v[130:131]
	s_nop 0
	v_pk_mul_f32 v[70:71], v[70:71], v[128:129]
	global_load_dwordx4 v[128:131], v[160:161], off offset:1024 nt
	global_load_dwordx4 v[170:173], v[162:163], off offset:1024
	s_waitcnt vmcnt(0) lgkmcnt(0)
	v_lshlrev_b32_e32 v176, 16, v128
	v_lshlrev_b32_e32 v136, 16, v170
	v_and_b32_e32 v177, 0xffff0000, v128
	v_lshlrev_b32_e32 v128, 16, v171
	v_rcp_f32_e32 v174, v136
	v_and_b32_e32 v136, 0xffff0000, v170
	v_rcp_f32_e32 v170, v128
	v_and_b32_e32 v128, 0xffff0000, v171
	v_rcp_f32_e32 v171, v128
	v_lshlrev_b32_e32 v128, 16, v129
	v_and_b32_e32 v129, 0xffff0000, v129
	v_rcp_f32_e32 v175, v136
	v_pk_mul_f32 v[128:129], v[170:171], v[128:129]
	v_lshlrev_b32_e32 v170, 16, v130
	v_pk_mul_f32 v[82:83], v[82:83], v[128:129]
	v_lshlrev_b32_e32 v128, 16, v172
	v_and_b32_e32 v129, 0xffff0000, v172
	v_rcp_f32_e32 v128, v128
	v_rcp_f32_e32 v129, v129
	v_and_b32_e32 v171, 0xffff0000, v130
	v_lshlrev_b32_e32 v130, 16, v131
	v_and_b32_e32 v131, 0xffff0000, v131
	v_pk_mul_f32 v[128:129], v[128:129], v[170:171]
	v_pk_mul_f32 v[174:175], v[174:175], v[176:177]
	v_pk_mul_f32 v[84:85], v[84:85], v[128:129]
	v_lshlrev_b32_e32 v128, 16, v173
	v_and_b32_e32 v129, 0xffff0000, v173
	v_rcp_f32_e32 v128, v128
	v_rcp_f32_e32 v129, v129
	v_pk_mul_f32 v[80:81], v[80:81], v[174:175]
	v_pk_mul_f32 v[128:129], v[128:129], v[130:131]
	s_nop 0
	v_pk_mul_f32 v[86:87], v[86:87], v[128:129]
	s_nop 0
	global_load_dwordx4 v[128:131], v[160:161], off offset:2048 nt
	global_load_dwordx4 v[170:173], v[162:163], off offset:2048
	s_waitcnt vmcnt(0) lgkmcnt(0)
	v_lshlrev_b32_e32 v176, 16, v128
	v_lshlrev_b32_e32 v136, 16, v170
	v_and_b32_e32 v177, 0xffff0000, v128
	v_lshlrev_b32_e32 v128, 16, v171
	v_rcp_f32_e32 v174, v136
	v_and_b32_e32 v136, 0xffff0000, v170
	v_rcp_f32_e32 v170, v128
	v_and_b32_e32 v128, 0xffff0000, v171
	v_rcp_f32_e32 v171, v128
	v_lshlrev_b32_e32 v128, 16, v129
	v_and_b32_e32 v129, 0xffff0000, v129
	v_rcp_f32_e32 v175, v136
	v_pk_mul_f32 v[128:129], v[170:171], v[128:129]
	v_lshlrev_b32_e32 v170, 16, v130
	v_pk_mul_f32 v[102:103], v[102:103], v[128:129]
	v_lshlrev_b32_e32 v128, 16, v172
	v_and_b32_e32 v129, 0xffff0000, v172
	v_rcp_f32_e32 v128, v128
	v_rcp_f32_e32 v129, v129
	v_and_b32_e32 v171, 0xffff0000, v130
	v_lshlrev_b32_e32 v130, 16, v131
	v_and_b32_e32 v131, 0xffff0000, v131
	v_pk_mul_f32 v[128:129], v[128:129], v[170:171]
	v_pk_mul_f32 v[174:175], v[174:175], v[176:177]
	v_pk_mul_f32 v[104:105], v[104:105], v[128:129]
	v_lshlrev_b32_e32 v128, 16, v173
	v_and_b32_e32 v129, 0xffff0000, v173
	v_rcp_f32_e32 v128, v128
	v_rcp_f32_e32 v129, v129
	v_pk_mul_f32 v[100:101], v[100:101], v[174:175]
	v_pk_mul_f32 v[128:129], v[128:129], v[130:131]
	s_nop 0
	v_pk_mul_f32 v[106:107], v[106:107], v[128:129]
	global_load_dwordx4 v[128:131], v[160:161], off offset:3072 nt
	s_nop 0
	global_load_dwordx4 v[160:163], v[162:163], off offset:3072
	s_waitcnt vmcnt(0) lgkmcnt(0)
	v_lshlrev_b32_e32 v172, 16, v128
	v_lshlrev_b32_e32 v136, 16, v160
	v_and_b32_e32 v173, 0xffff0000, v128
	v_lshlrev_b32_e32 v128, 16, v161
	v_rcp_f32_e32 v170, v136
	v_and_b32_e32 v136, 0xffff0000, v160
	v_rcp_f32_e32 v160, v128
	v_and_b32_e32 v128, 0xffff0000, v161
	v_rcp_f32_e32 v161, v128
	v_lshlrev_b32_e32 v128, 16, v129
	v_and_b32_e32 v129, 0xffff0000, v129
	v_rcp_f32_e32 v171, v136
	v_pk_mul_f32 v[128:129], v[160:161], v[128:129]
	v_lshlrev_b32_e32 v160, 16, v130
	v_pk_mul_f32 v[110:111], v[110:111], v[128:129]
	v_lshlrev_b32_e32 v128, 16, v162
	v_and_b32_e32 v129, 0xffff0000, v162
	v_rcp_f32_e32 v128, v128
	v_rcp_f32_e32 v129, v129
	v_and_b32_e32 v161, 0xffff0000, v130
	v_lshlrev_b32_e32 v130, 16, v131
	v_and_b32_e32 v131, 0xffff0000, v131
	v_pk_mul_f32 v[128:129], v[128:129], v[160:161]
	v_add_co_u32_e32 v160, vcc, s51, v158
	v_pk_mul_f32 v[112:113], v[112:113], v[128:129]
	v_lshlrev_b32_e32 v128, 16, v163
	v_and_b32_e32 v129, 0xffff0000, v163
	v_rcp_f32_e32 v128, v128
	v_rcp_f32_e32 v129, v129
	v_pk_mul_f32 v[170:171], v[170:171], v[172:173]
	v_addc_co_u32_e32 v161, vcc, 0, v159, vcc
	v_pk_mul_f32 v[128:129], v[128:129], v[130:131]
	v_pk_mul_f32 v[108:109], v[108:109], v[170:171]
	v_pk_mul_f32 v[114:115], v[114:115], v[128:129]
	v_add_co_u32_e32 v162, vcc, s51, v156
	global_load_dwordx4 v[128:131], v[160:161], off nt
	s_nop 0
	v_addc_co_u32_e32 v163, vcc, 0, v157, vcc
	global_load_dwordx4 v[170:173], v[162:163], off
	v_add_co_u32_e32 v158, vcc, s83, v158
	s_waitcnt vmcnt(0) lgkmcnt(0)
	v_lshlrev_b32_e32 v176, 16, v128
	v_and_b32_e32 v177, 0xffff0000, v128
	v_addc_co_u32_e32 v159, vcc, 0, v159, vcc
	v_lshlrev_b32_e32 v136, 16, v170
	v_lshlrev_b32_e32 v128, 16, v171
	v_rcp_f32_e32 v174, v136
	v_and_b32_e32 v136, 0xffff0000, v170
	v_rcp_f32_e32 v170, v128
	v_and_b32_e32 v128, 0xffff0000, v171
	v_rcp_f32_e32 v171, v128
	v_lshlrev_b32_e32 v128, 16, v129
	v_and_b32_e32 v129, 0xffff0000, v129
	v_rcp_f32_e32 v175, v136
	v_pk_mul_f32 v[128:129], v[170:171], v[128:129]
	v_lshlrev_b32_e32 v170, 16, v130
	v_pk_mul_f32 v[126:127], v[126:127], v[128:129]
	v_lshlrev_b32_e32 v128, 16, v172
	v_and_b32_e32 v129, 0xffff0000, v172
	v_rcp_f32_e32 v128, v128
	v_rcp_f32_e32 v129, v129
	v_and_b32_e32 v171, 0xffff0000, v130
	v_lshlrev_b32_e32 v130, 16, v131
	v_and_b32_e32 v131, 0xffff0000, v131
	v_pk_mul_f32 v[128:129], v[128:129], v[170:171]
	v_pk_mul_f32 v[174:175], v[174:175], v[176:177]
	v_pk_mul_f32 v[120:121], v[120:121], v[128:129]
	v_lshlrev_b32_e32 v128, 16, v173
	v_and_b32_e32 v129, 0xffff0000, v173
	v_rcp_f32_e32 v128, v128
	v_rcp_f32_e32 v129, v129
	v_pk_mul_f32 v[124:125], v[124:125], v[174:175]
	v_add_co_u32_e32 v156, vcc, s83, v156
	v_pk_mul_f32 v[128:129], v[128:129], v[130:131]
	s_nop 0
	v_addc_co_u32_e32 v157, vcc, 0, v157, vcc
	v_pk_mul_f32 v[122:123], v[122:123], v[128:129]
	global_load_dwordx4 v[128:131], v[160:161], off offset:1024 nt
	global_load_dwordx4 v[170:173], v[162:163], off offset:1024
	s_and_b64 vcc, exec, s[0:1]
	s_waitcnt vmcnt(0) lgkmcnt(0)
	v_lshlrev_b32_e32 v176, 16, v128
	v_lshlrev_b32_e32 v136, 16, v170
	v_and_b32_e32 v177, 0xffff0000, v128
	v_lshlrev_b32_e32 v128, 16, v171
	v_rcp_f32_e32 v174, v136
	v_and_b32_e32 v136, 0xffff0000, v170
	v_rcp_f32_e32 v170, v128
	v_and_b32_e32 v128, 0xffff0000, v171
	v_rcp_f32_e32 v171, v128
	v_lshlrev_b32_e32 v128, 16, v129
	v_and_b32_e32 v129, 0xffff0000, v129
	v_rcp_f32_e32 v175, v136
	v_pk_mul_f32 v[128:129], v[170:171], v[128:129]
	v_lshlrev_b32_e32 v170, 16, v130
	v_pk_mul_f32 v[118:119], v[118:119], v[128:129]
	v_lshlrev_b32_e32 v128, 16, v172
	v_and_b32_e32 v129, 0xffff0000, v172
	v_rcp_f32_e32 v128, v128
	v_rcp_f32_e32 v129, v129
	v_and_b32_e32 v171, 0xffff0000, v130
	v_lshlrev_b32_e32 v130, 16, v131
	v_and_b32_e32 v131, 0xffff0000, v131
	v_pk_mul_f32 v[128:129], v[128:129], v[170:171]
	v_pk_mul_f32 v[174:175], v[174:175], v[176:177]
	v_pk_mul_f32 v[96:97], v[96:97], v[128:129]
	v_lshlrev_b32_e32 v128, 16, v173
	v_and_b32_e32 v129, 0xffff0000, v173
	v_rcp_f32_e32 v128, v128
	v_rcp_f32_e32 v129, v129
	v_pk_mul_f32 v[116:117], v[116:117], v[174:175]
	v_pk_mul_f32 v[128:129], v[128:129], v[130:131]
	s_nop 0
	v_pk_mul_f32 v[98:99], v[98:99], v[128:129]
	s_nop 0
	global_load_dwordx4 v[128:131], v[160:161], off offset:2048 nt
	global_load_dwordx4 v[170:173], v[162:163], off offset:2048
	s_waitcnt vmcnt(0) lgkmcnt(0)
	v_lshlrev_b32_e32 v176, 16, v128
	v_lshlrev_b32_e32 v136, 16, v170
	v_and_b32_e32 v177, 0xffff0000, v128
	v_lshlrev_b32_e32 v128, 16, v171
	v_rcp_f32_e32 v174, v136
	v_and_b32_e32 v136, 0xffff0000, v170
	v_rcp_f32_e32 v170, v128
	v_and_b32_e32 v128, 0xffff0000, v171
	v_rcp_f32_e32 v171, v128
	v_lshlrev_b32_e32 v128, 16, v129
	v_and_b32_e32 v129, 0xffff0000, v129
	v_rcp_f32_e32 v175, v136
	v_pk_mul_f32 v[128:129], v[170:171], v[128:129]
	v_lshlrev_b32_e32 v170, 16, v130
	v_pk_mul_f32 v[94:95], v[94:95], v[128:129]
	v_lshlrev_b32_e32 v128, 16, v172
	v_and_b32_e32 v129, 0xffff0000, v172
	v_rcp_f32_e32 v128, v128
	v_rcp_f32_e32 v129, v129
	v_and_b32_e32 v171, 0xffff0000, v130
	v_lshlrev_b32_e32 v130, 16, v131
	v_and_b32_e32 v131, 0xffff0000, v131
	v_pk_mul_f32 v[128:129], v[128:129], v[170:171]
	v_pk_mul_f32 v[174:175], v[174:175], v[176:177]
	v_pk_mul_f32 v[88:89], v[88:89], v[128:129]
	v_lshlrev_b32_e32 v128, 16, v173
	v_and_b32_e32 v129, 0xffff0000, v173
	v_rcp_f32_e32 v128, v128
	v_rcp_f32_e32 v129, v129
	v_pk_mul_f32 v[92:93], v[92:93], v[174:175]
	v_pk_mul_f32 v[128:129], v[128:129], v[130:131]
	s_nop 0
	v_pk_mul_f32 v[90:91], v[90:91], v[128:129]
	global_load_dwordx4 v[128:131], v[160:161], off offset:3072 nt
	s_nop 0
	global_load_dwordx4 v[160:163], v[162:163], off offset:3072
	s_waitcnt vmcnt(0) lgkmcnt(0)
	v_lshlrev_b32_e32 v172, 16, v128
	v_lshlrev_b32_e32 v136, 16, v160
	v_and_b32_e32 v173, 0xffff0000, v128
	v_lshlrev_b32_e32 v128, 16, v161
	v_rcp_f32_e32 v170, v136
	v_and_b32_e32 v136, 0xffff0000, v160
	v_rcp_f32_e32 v160, v128
	v_and_b32_e32 v128, 0xffff0000, v161
	v_rcp_f32_e32 v161, v128
	v_lshlrev_b32_e32 v128, 16, v129
	v_and_b32_e32 v129, 0xffff0000, v129
	v_rcp_f32_e32 v171, v136
	v_pk_mul_f32 v[128:129], v[160:161], v[128:129]
	v_lshlrev_b32_e32 v160, 16, v130
	v_pk_mul_f32 v[78:79], v[78:79], v[128:129]
	v_lshlrev_b32_e32 v128, 16, v162
	v_and_b32_e32 v129, 0xffff0000, v162
	v_rcp_f32_e32 v128, v128
	v_rcp_f32_e32 v129, v129
	v_and_b32_e32 v161, 0xffff0000, v130
	v_lshlrev_b32_e32 v130, 16, v131
	v_and_b32_e32 v131, 0xffff0000, v131
	v_pk_mul_f32 v[128:129], v[128:129], v[160:161]
	v_pk_mul_f32 v[170:171], v[170:171], v[172:173]
	v_pk_mul_f32 v[72:73], v[72:73], v[128:129]
	v_lshlrev_b32_e32 v128, 16, v163
	v_and_b32_e32 v129, 0xffff0000, v163
	v_rcp_f32_e32 v128, v128
	v_rcp_f32_e32 v129, v129
	v_pk_mul_f32 v[76:77], v[76:77], v[170:171]
	v_pk_mul_f32 v[128:129], v[128:129], v[130:131]
	s_nop 0
	v_pk_mul_f32 v[74:75], v[74:75], v[128:129]
	s_nop 0
	global_load_dwordx4 v[128:131], v[158:159], off nt
	global_load_dwordx4 v[160:163], v[156:157], off
	s_waitcnt vmcnt(0) lgkmcnt(0)
	v_lshlrev_b32_e32 v172, 16, v128
	v_lshlrev_b32_e32 v136, 16, v160
	v_and_b32_e32 v173, 0xffff0000, v128
	v_lshlrev_b32_e32 v128, 16, v161
	v_rcp_f32_e32 v170, v136
	v_and_b32_e32 v136, 0xffff0000, v160
	v_rcp_f32_e32 v160, v128
	v_and_b32_e32 v128, 0xffff0000, v161
	v_rcp_f32_e32 v161, v128
	v_lshlrev_b32_e32 v128, 16, v129
	v_and_b32_e32 v129, 0xffff0000, v129
	v_rcp_f32_e32 v171, v136
	v_pk_mul_f32 v[128:129], v[160:161], v[128:129]
	v_lshlrev_b32_e32 v160, 16, v130
	v_pk_mul_f32 v[62:63], v[62:63], v[128:129]
	v_lshlrev_b32_e32 v128, 16, v162
	v_and_b32_e32 v129, 0xffff0000, v162
	v_rcp_f32_e32 v128, v128
	v_rcp_f32_e32 v129, v129
	v_and_b32_e32 v161, 0xffff0000, v130
	v_lshlrev_b32_e32 v130, 16, v131
	v_and_b32_e32 v131, 0xffff0000, v131
	v_pk_mul_f32 v[128:129], v[128:129], v[160:161]
	v_pk_mul_f32 v[170:171], v[170:171], v[172:173]
	v_pk_mul_f32 v[56:57], v[56:57], v[128:129]
	v_lshlrev_b32_e32 v128, 16, v163
	v_and_b32_e32 v129, 0xffff0000, v163
	v_rcp_f32_e32 v128, v128
	v_rcp_f32_e32 v129, v129
	v_pk_mul_f32 v[60:61], v[60:61], v[170:171]
	v_pk_mul_f32 v[128:129], v[128:129], v[130:131]
	s_nop 0
	v_pk_mul_f32 v[58:59], v[58:59], v[128:129]
	global_load_dwordx4 v[128:131], v[158:159], off offset:1024 nt
	global_load_dwordx4 v[160:163], v[156:157], off offset:1024
	s_waitcnt vmcnt(0) lgkmcnt(0)
	v_lshlrev_b32_e32 v172, 16, v128
	v_lshlrev_b32_e32 v136, 16, v160
	v_and_b32_e32 v173, 0xffff0000, v128
	v_lshlrev_b32_e32 v128, 16, v161
	v_rcp_f32_e32 v170, v136
	v_and_b32_e32 v136, 0xffff0000, v160
	v_rcp_f32_e32 v160, v128
	v_and_b32_e32 v128, 0xffff0000, v161
	v_rcp_f32_e32 v161, v128
	v_lshlrev_b32_e32 v128, 16, v129
	v_and_b32_e32 v129, 0xffff0000, v129
	v_rcp_f32_e32 v171, v136
	v_pk_mul_f32 v[128:129], v[160:161], v[128:129]
	v_lshlrev_b32_e32 v160, 16, v130
	v_pk_mul_f32 v[38:39], v[38:39], v[128:129]
	v_lshlrev_b32_e32 v128, 16, v162
	v_and_b32_e32 v129, 0xffff0000, v162
	v_rcp_f32_e32 v128, v128
	v_rcp_f32_e32 v129, v129
	v_and_b32_e32 v161, 0xffff0000, v130
	v_lshlrev_b32_e32 v130, 16, v131
	v_and_b32_e32 v131, 0xffff0000, v131
	v_pk_mul_f32 v[128:129], v[128:129], v[160:161]
	v_pk_mul_f32 v[170:171], v[170:171], v[172:173]
	v_pk_mul_f32 v[24:25], v[24:25], v[128:129]
	v_lshlrev_b32_e32 v128, 16, v163
	v_and_b32_e32 v129, 0xffff0000, v163
	v_rcp_f32_e32 v128, v128
	v_rcp_f32_e32 v129, v129
	v_pk_mul_f32 v[36:37], v[36:37], v[170:171]
	v_pk_mul_f32 v[128:129], v[128:129], v[130:131]
	s_nop 0
	v_pk_mul_f32 v[26:27], v[26:27], v[128:129]
	s_nop 0
	global_load_dwordx4 v[128:131], v[158:159], off offset:2048 nt
	global_load_dwordx4 v[160:163], v[156:157], off offset:2048
	s_waitcnt vmcnt(0) lgkmcnt(0)
	v_lshlrev_b32_e32 v172, 16, v128
	v_lshlrev_b32_e32 v136, 16, v160
	v_and_b32_e32 v173, 0xffff0000, v128
	v_lshlrev_b32_e32 v128, 16, v161
	v_rcp_f32_e32 v170, v136
	v_and_b32_e32 v136, 0xffff0000, v160
	v_rcp_f32_e32 v160, v128
	v_and_b32_e32 v128, 0xffff0000, v161
	v_rcp_f32_e32 v161, v128
	v_lshlrev_b32_e32 v128, 16, v129
	v_and_b32_e32 v129, 0xffff0000, v129
	v_rcp_f32_e32 v171, v136
	v_pk_mul_f32 v[128:129], v[160:161], v[128:129]
	v_lshlrev_b32_e32 v160, 16, v130
	v_pk_mul_f32 v[22:23], v[22:23], v[128:129]
	v_lshlrev_b32_e32 v128, 16, v162
	v_and_b32_e32 v129, 0xffff0000, v162
	v_rcp_f32_e32 v128, v128
	v_rcp_f32_e32 v129, v129
	v_and_b32_e32 v161, 0xffff0000, v130
	v_lshlrev_b32_e32 v130, 16, v131
	v_and_b32_e32 v131, 0xffff0000, v131
	v_pk_mul_f32 v[128:129], v[128:129], v[160:161]
	v_pk_mul_f32 v[170:171], v[170:171], v[172:173]
	v_pk_mul_f32 v[16:17], v[16:17], v[128:129]
	v_lshlrev_b32_e32 v128, 16, v163
	v_and_b32_e32 v129, 0xffff0000, v163
	v_rcp_f32_e32 v128, v128
	v_rcp_f32_e32 v129, v129
	v_pk_mul_f32 v[20:21], v[20:21], v[170:171]
	v_pk_mul_f32 v[128:129], v[128:129], v[130:131]
	s_nop 0
	v_pk_mul_f32 v[18:19], v[18:19], v[128:129]
	global_load_dwordx4 v[128:131], v[158:159], off offset:3072 nt
	s_nop 0
	global_load_dwordx4 v[156:159], v[156:157], off offset:3072
	s_waitcnt vmcnt(0) lgkmcnt(0)
	v_lshlrev_b32_e32 v162, 16, v128
	v_lshlrev_b32_e32 v136, 16, v156
	v_and_b32_e32 v163, 0xffff0000, v128
	v_lshlrev_b32_e32 v128, 16, v157
	v_rcp_f32_e32 v160, v136
	v_and_b32_e32 v136, 0xffff0000, v156
	v_rcp_f32_e32 v156, v128
	v_and_b32_e32 v128, 0xffff0000, v157
	v_rcp_f32_e32 v157, v128
	v_lshlrev_b32_e32 v128, 16, v129
	v_and_b32_e32 v129, 0xffff0000, v129
	v_rcp_f32_e32 v161, v136
	v_pk_mul_f32 v[128:129], v[156:157], v[128:129]
	v_lshlrev_b32_e32 v156, 16, v130
	v_pk_mul_f32 v[6:7], v[6:7], v[128:129]
	v_lshlrev_b32_e32 v128, 16, v158
	v_and_b32_e32 v129, 0xffff0000, v158
	v_rcp_f32_e32 v128, v128
	v_rcp_f32_e32 v129, v129
	v_and_b32_e32 v157, 0xffff0000, v130
	v_lshlrev_b32_e32 v130, 16, v131
	v_and_b32_e32 v131, 0xffff0000, v131
	v_pk_mul_f32 v[128:129], v[128:129], v[156:157]
	v_pk_mul_f32 v[160:161], v[160:161], v[162:163]
	v_pk_mul_f32 v[0:1], v[0:1], v[128:129]
	v_lshlrev_b32_e32 v128, 16, v159
	v_and_b32_e32 v129, 0xffff0000, v159
	v_rcp_f32_e32 v128, v128
	v_rcp_f32_e32 v129, v129
	v_pk_mul_f32 v[4:5], v[4:5], v[160:161]
	v_pk_mul_f32 v[128:129], v[128:129], v[130:131]
	s_nop 0
	v_pk_mul_f32 v[2:3], v[2:3], v[128:129]
	s_nop 0
	s_cbranch_vccnz .LBB0_772
	s_barrier

.LBB0_776:
	v_mov_b32_e32 v128, v182
	s_mov_b64 s[10:11], s[16:17]
	v_and_b32_e32 v128, 63, v128
	v_readlane_b32 s96, v252, 26
	v_ashrrev_i32_e32 v129, 31, v128
	v_lshl_add_u64 v[130:131], v[128:129], 4, s[10:11]
	v_lshl_add_u64 v[130:131], v[130:131], 0, s[30:31]
	global_load_dwordx4 v[160:163], v[130:131], off nt
	s_lshl_b32 s10, s12, 8
	s_add_i32 s10, s10, s52
	v_and_or_b32 v158, v128, 15, s10
	v_ashrrev_i32_e32 v128, 1, v128
	v_and_b32_e32 v128, -8, v128
	v_ashrrev_i32_e32 v159, 31, v158
	s_lshl_b32 s12, s24, 8
	v_add_u32_e32 v128, s53, v128
	v_lshlrev_b64 v[156:157], 12, v[158:159]
	s_lshl_b64 s[24:25], s[12:13], 1
	v_lshl_add_u64 v[156:157], s[8:9], 0, v[156:157]
	v_ashrrev_i32_e32 v129, 31, v128
	v_lshl_add_u64 v[168:169], v[156:157], 0, s[24:25]
	v_lshlrev_b64 v[156:157], 1, v[128:129]
	v_lshl_add_u64 v[128:129], v[168:169], 0, v[156:157]
	s_mov_b32 s10, 0x80000
	s_waitcnt vmcnt(0) lgkmcnt(0)
	v_lshlrev_b32_e32 v168, 16, v160
	v_and_b32_e32 v169, 0xffff0000, v160
	v_lshlrev_b32_e32 v160, 16, v161
	v_and_b32_e32 v161, 0xffff0000, v161
	v_lshlrev_b32_e32 v170, 16, v162
	v_and_b32_e32 v171, 0xffff0000, v162
	v_lshlrev_b32_e32 v162, 16, v163
	v_and_b32_e32 v163, 0xffff0000, v163
	v_pk_mul_f32 v[8:9], v[8:9], v[168:169]
	v_pk_mul_f32 v[10:11], v[10:11], v[160:161]
	v_pk_mul_f32 v[12:13], v[12:13], v[170:171]
	v_pk_mul_f32 v[14:15], v[14:15], v[162:163]
	v_cvt_pk_bf16_f32 v8, v8, v9
	v_cvt_pk_bf16_f32 v9, v10, v11
	v_cvt_pk_bf16_f32 v10, v12, v13
	v_cvt_pk_bf16_f32 v11, v14, v15
	global_store_dwordx4 v[128:129], v[8:11], off
	global_load_dwordx4 v[8:11], v[130:131], off offset:1024 nt
	s_waitcnt vmcnt(0) lgkmcnt(0)
	v_lshlrev_b32_e32 v12, 16, v8
	v_and_b32_e32 v13, 0xffff0000, v8
	v_lshlrev_b32_e32 v8, 16, v9
	v_and_b32_e32 v9, 0xffff0000, v9
	v_lshlrev_b32_e32 v14, 16, v10
	v_and_b32_e32 v15, 0xffff0000, v10
	v_lshlrev_b32_e32 v10, 16, v11
	v_and_b32_e32 v11, 0xffff0000, v11
	v_pk_mul_f32 v[12:13], v[28:29], v[12:13]
	v_pk_mul_f32 v[28:29], v[30:31], v[8:9]
	v_pk_mul_f32 v[14:15], v[32:33], v[14:15]
	v_pk_mul_f32 v[30:31], v[34:35], v[10:11]
	v_cvt_pk_bf16_f32 v8, v12, v13
	v_cvt_pk_bf16_f32 v9, v28, v29
	v_cvt_pk_bf16_f32 v10, v14, v15
	v_cvt_pk_bf16_f32 v11, v30, v31
	global_store_dwordx4 v[128:129], v[8:11], off offset:256
	global_load_dwordx4 v[8:11], v[130:131], off offset:2048 nt
	v_or_b32_e32 v12, 16, v158
	v_ashrrev_i32_e32 v13, 31, v12
	v_lshlrev_b64 v[12:13], 12, v[12:13]
	v_lshl_add_u64 v[12:13], s[8:9], 0, v[12:13]
	v_lshl_add_u64 v[12:13], v[12:13], 0, s[24:25]
	v_lshl_add_u64 v[12:13], v[12:13], 0, v[156:157]
	s_waitcnt vmcnt(0) lgkmcnt(0)
	v_lshlrev_b32_e32 v14, 16, v8
	v_and_b32_e32 v15, 0xffff0000, v8
	v_lshlrev_b32_e32 v8, 16, v9
	v_and_b32_e32 v9, 0xffff0000, v9
	v_lshlrev_b32_e32 v28, 16, v10
	v_and_b32_e32 v29, 0xffff0000, v10
	v_lshlrev_b32_e32 v10, 16, v11
	v_and_b32_e32 v11, 0xffff0000, v11
	v_pk_mul_f32 v[14:15], v[40:41], v[14:15]
	v_pk_mul_f32 v[30:31], v[42:43], v[8:9]
	v_pk_mul_f32 v[28:29], v[44:45], v[28:29]
	v_pk_mul_f32 v[32:33], v[46:47], v[10:11]
	v_cvt_pk_bf16_f32 v8, v14, v15
	v_cvt_pk_bf16_f32 v9, v30, v31
	v_cvt_pk_bf16_f32 v10, v28, v29
	v_cvt_pk_bf16_f32 v11, v32, v33
	global_store_dwordx4 v[12:13], v[8:11], off
	global_load_dwordx4 v[8:11], v[130:131], off offset:3072 nt
	v_add_co_u32_e32 v14, vcc, s82, v130
	s_waitcnt vmcnt(0) lgkmcnt(0)
	v_lshlrev_b32_e32 v28, 16, v8
	v_and_b32_e32 v29, 0xffff0000, v8
	v_lshlrev_b32_e32 v8, 16, v9
	v_and_b32_e32 v9, 0xffff0000, v9
	v_lshlrev_b32_e32 v30, 16, v10
	v_and_b32_e32 v31, 0xffff0000, v10
	v_lshlrev_b32_e32 v10, 16, v11
	v_and_b32_e32 v11, 0xffff0000, v11
	v_pk_mul_f32 v[28:29], v[48:49], v[28:29]
	v_pk_mul_f32 v[32:33], v[50:51], v[8:9]
	v_pk_mul_f32 v[30:31], v[52:53], v[30:31]
	v_pk_mul_f32 v[34:35], v[54:55], v[10:11]
	v_cvt_pk_bf16_f32 v8, v28, v29
	v_cvt_pk_bf16_f32 v9, v32, v33
	v_cvt_pk_bf16_f32 v10, v30, v31
	v_cvt_pk_bf16_f32 v11, v34, v35
	global_store_dwordx4 v[12:13], v[8:11], off offset:256
	v_addc_co_u32_e32 v15, vcc, 0, v131, vcc
	global_load_dwordx4 v[8:11], v[14:15], off nt
	v_or_b32_e32 v12, 32, v158
	v_ashrrev_i32_e32 v13, 31, v12
	v_lshlrev_b64 v[12:13], 12, v[12:13]
	v_lshl_add_u64 v[12:13], s[8:9], 0, v[12:13]
	v_lshl_add_u64 v[12:13], v[12:13], 0, s[24:25]
	v_lshl_add_u64 v[12:13], v[12:13], 0, v[156:157]
	s_waitcnt vmcnt(0) lgkmcnt(0)
	v_lshlrev_b32_e32 v28, 16, v8
	v_and_b32_e32 v29, 0xffff0000, v8
	v_lshlrev_b32_e32 v8, 16, v9
	v_and_b32_e32 v9, 0xffff0000, v9
	v_lshlrev_b32_e32 v30, 16, v10
	v_and_b32_e32 v31, 0xffff0000, v10
	v_lshlrev_b32_e32 v10, 16, v11
	v_and_b32_e32 v11, 0xffff0000, v11
	v_pk_mul_f32 v[28:29], v[64:65], v[28:29]
	v_pk_mul_f32 v[32:33], v[66:67], v[8:9]
	v_pk_mul_f32 v[30:31], v[68:69], v[30:31]
	v_pk_mul_f32 v[34:35], v[70:71], v[10:11]
	v_cvt_pk_bf16_f32 v8, v28, v29
	v_cvt_pk_bf16_f32 v9, v32, v33
	v_cvt_pk_bf16_f32 v10, v30, v31
	v_cvt_pk_bf16_f32 v11, v34, v35
	global_store_dwordx4 v[12:13], v[8:11], off
	global_load_dwordx4 v[8:11], v[14:15], off offset:1024 nt
	s_waitcnt vmcnt(0) lgkmcnt(0)
	v_lshlrev_b32_e32 v28, 16, v8
	v_and_b32_e32 v29, 0xffff0000, v8
	v_lshlrev_b32_e32 v8, 16, v9
	v_and_b32_e32 v9, 0xffff0000, v9
	v_lshlrev_b32_e32 v30, 16, v10
	v_and_b32_e32 v31, 0xffff0000, v10
	v_lshlrev_b32_e32 v10, 16, v11
	v_and_b32_e32 v11, 0xffff0000, v11
	v_pk_mul_f32 v[28:29], v[80:81], v[28:29]
	v_pk_mul_f32 v[32:33], v[82:83], v[8:9]
	v_pk_mul_f32 v[30:31], v[84:85], v[30:31]
	v_pk_mul_f32 v[34:35], v[86:87], v[10:11]
	v_cvt_pk_bf16_f32 v8, v28, v29
	v_cvt_pk_bf16_f32 v9, v32, v33
	v_cvt_pk_bf16_f32 v10, v30, v31
	v_cvt_pk_bf16_f32 v11, v34, v35
	global_store_dwordx4 v[12:13], v[8:11], off offset:256
	global_load_dwordx4 v[8:11], v[14:15], off offset:2048 nt
	v_or_b32_e32 v12, 48, v158
	v_ashrrev_i32_e32 v13, 31, v12
	v_lshlrev_b64 v[12:13], 12, v[12:13]
	v_lshl_add_u64 v[12:13], s[8:9], 0, v[12:13]
	v_lshl_add_u64 v[12:13], v[12:13], 0, s[24:25]
	v_lshl_add_u64 v[12:13], v[12:13], 0, v[156:157]
	s_waitcnt vmcnt(0) lgkmcnt(0)
	v_lshlrev_b32_e32 v28, 16, v8
	v_and_b32_e32 v29, 0xffff0000, v8
	v_lshlrev_b32_e32 v8, 16, v9
	v_and_b32_e32 v9, 0xffff0000, v9
	v_lshlrev_b32_e32 v30, 16, v10
	v_and_b32_e32 v31, 0xffff0000, v10
	v_lshlrev_b32_e32 v10, 16, v11
	v_and_b32_e32 v11, 0xffff0000, v11
	v_pk_mul_f32 v[28:29], v[100:101], v[28:29]
	v_pk_mul_f32 v[32:33], v[102:103], v[8:9]
	v_pk_mul_f32 v[30:31], v[104:105], v[30:31]
	v_pk_mul_f32 v[34:35], v[106:107], v[10:11]
	v_cvt_pk_bf16_f32 v8, v28, v29
	v_cvt_pk_bf16_f32 v9, v32, v33
	v_cvt_pk_bf16_f32 v10, v30, v31
	v_cvt_pk_bf16_f32 v11, v34, v35
	global_store_dwordx4 v[12:13], v[8:11], off
	global_load_dwordx4 v[8:11], v[14:15], off offset:3072 nt
	v_add_co_u32_e32 v14, vcc, s51, v130
	s_waitcnt vmcnt(0) lgkmcnt(0)
	v_lshlrev_b32_e32 v28, 16, v8
	v_and_b32_e32 v29, 0xffff0000, v8
	v_lshlrev_b32_e32 v8, 16, v9
	v_and_b32_e32 v9, 0xffff0000, v9
	v_lshlrev_b32_e32 v30, 16, v10
	v_and_b32_e32 v31, 0xffff0000, v10
	v_lshlrev_b32_e32 v10, 16, v11
	v_and_b32_e32 v11, 0xffff0000, v11
	v_pk_mul_f32 v[28:29], v[108:109], v[28:29]
	v_pk_mul_f32 v[32:33], v[110:111], v[8:9]
	v_pk_mul_f32 v[30:31], v[112:113], v[30:31]
	v_pk_mul_f32 v[34:35], v[114:115], v[10:11]
	v_cvt_pk_bf16_f32 v8, v28, v29
	v_cvt_pk_bf16_f32 v9, v32, v33
	v_cvt_pk_bf16_f32 v10, v30, v31
	v_cvt_pk_bf16_f32 v11, v34, v35
	global_store_dwordx4 v[12:13], v[8:11], off offset:256
	v_addc_co_u32_e32 v15, vcc, 0, v131, vcc
	global_load_dwordx4 v[8:11], v[14:15], off nt
	v_add_co_u32_e32 v12, vcc, s10, v128
	s_mov_b64 s[10:11], 0x80000
	s_nop 0
	v_addc_co_u32_e32 v13, vcc, 0, v129, vcc
	s_waitcnt vmcnt(0) lgkmcnt(0)
	v_lshlrev_b32_e32 v28, 16, v8
	v_and_b32_e32 v29, 0xffff0000, v8
	v_lshlrev_b32_e32 v8, 16, v9
	v_and_b32_e32 v9, 0xffff0000, v9
	v_lshlrev_b32_e32 v30, 16, v10
	v_and_b32_e32 v31, 0xffff0000, v10
	v_lshlrev_b32_e32 v10, 16, v11
	v_and_b32_e32 v11, 0xffff0000, v11
	v_pk_mul_f32 v[28:29], v[124:125], v[28:29]
	v_pk_mul_f32 v[32:33], v[126:127], v[8:9]
	v_pk_mul_f32 v[30:31], v[120:121], v[30:31]
	v_pk_mul_f32 v[34:35], v[122:123], v[10:11]
	v_cvt_pk_bf16_f32 v8, v28, v29
	v_cvt_pk_bf16_f32 v9, v32, v33
	v_cvt_pk_bf16_f32 v10, v30, v31
	v_cvt_pk_bf16_f32 v11, v34, v35
	global_store_dwordx4 v[12:13], v[8:11], off
	global_load_dwordx4 v[8:11], v[14:15], off offset:1024 nt
	v_lshl_add_u64 v[12:13], v[128:129], 0, s[10:11]
	s_mov_b32 s10, 0x90000
	s_waitcnt vmcnt(0) lgkmcnt(0)
	v_lshlrev_b32_e32 v28, 16, v8
	v_and_b32_e32 v29, 0xffff0000, v8
	v_lshlrev_b32_e32 v8, 16, v9
	v_and_b32_e32 v9, 0xffff0000, v9
	v_lshlrev_b32_e32 v30, 16, v10
	v_and_b32_e32 v31, 0xffff0000, v10
	v_lshlrev_b32_e32 v10, 16, v11
	v_and_b32_e32 v11, 0xffff0000, v11
	v_pk_mul_f32 v[28:29], v[116:117], v[28:29]
	v_pk_mul_f32 v[32:33], v[118:119], v[8:9]
	v_pk_mul_f32 v[30:31], v[96:97], v[30:31]
	v_pk_mul_f32 v[34:35], v[98:99], v[10:11]
	v_cvt_pk_bf16_f32 v8, v28, v29
	v_cvt_pk_bf16_f32 v9, v32, v33
	v_cvt_pk_bf16_f32 v10, v30, v31
	v_cvt_pk_bf16_f32 v11, v34, v35
	global_store_dwordx4 v[12:13], v[8:11], off offset:256
	global_load_dwordx4 v[8:11], v[14:15], off offset:2048 nt
	v_add_co_u32_e32 v12, vcc, s10, v128
	s_mov_b64 s[10:11], 0x90000
	s_nop 0
	v_addc_co_u32_e32 v13, vcc, 0, v129, vcc
	s_waitcnt vmcnt(0) lgkmcnt(0)
	v_lshlrev_b32_e32 v28, 16, v8
	v_and_b32_e32 v29, 0xffff0000, v8
	v_lshlrev_b32_e32 v8, 16, v9
	v_and_b32_e32 v9, 0xffff0000, v9
	v_lshlrev_b32_e32 v30, 16, v10
	v_and_b32_e32 v31, 0xffff0000, v10
	v_lshlrev_b32_e32 v10, 16, v11
	v_and_b32_e32 v11, 0xffff0000, v11
	v_pk_mul_f32 v[28:29], v[92:93], v[28:29]
	v_pk_mul_f32 v[32:33], v[94:95], v[8:9]
	v_pk_mul_f32 v[30:31], v[88:89], v[30:31]
	v_pk_mul_f32 v[34:35], v[90:91], v[10:11]
	v_cvt_pk_bf16_f32 v8, v28, v29
	v_cvt_pk_bf16_f32 v9, v32, v33
	v_cvt_pk_bf16_f32 v10, v30, v31
	v_cvt_pk_bf16_f32 v11, v34, v35
	global_store_dwordx4 v[12:13], v[8:11], off
	global_load_dwordx4 v[8:11], v[14:15], off offset:3072 nt
	v_lshl_add_u64 v[14:15], v[128:129], 0, s[10:11]
	v_add_co_u32_e32 v12, vcc, s83, v130
	s_mov_b32 s10, 0xa0000
	s_nop 0
	v_addc_co_u32_e32 v13, vcc, 0, v131, vcc
	s_waitcnt vmcnt(0) lgkmcnt(0)
	v_lshlrev_b32_e32 v28, 16, v8
	v_and_b32_e32 v29, 0xffff0000, v8
	v_lshlrev_b32_e32 v8, 16, v9
	v_and_b32_e32 v9, 0xffff0000, v9
	v_lshlrev_b32_e32 v30, 16, v10
	v_and_b32_e32 v31, 0xffff0000, v10
	v_lshlrev_b32_e32 v10, 16, v11
	v_and_b32_e32 v11, 0xffff0000, v11
	v_pk_mul_f32 v[28:29], v[76:77], v[28:29]
	v_pk_mul_f32 v[32:33], v[78:79], v[8:9]
	v_pk_mul_f32 v[30:31], v[72:73], v[30:31]
	v_pk_mul_f32 v[34:35], v[74:75], v[10:11]
	v_cvt_pk_bf16_f32 v8, v28, v29
	v_cvt_pk_bf16_f32 v9, v32, v33
	v_cvt_pk_bf16_f32 v10, v30, v31
	v_cvt_pk_bf16_f32 v11, v34, v35
	global_store_dwordx4 v[14:15], v[8:11], off offset:256
	global_load_dwordx4 v[8:11], v[12:13], off nt
	v_add_co_u32_e32 v14, vcc, s10, v128
	s_mov_b64 s[10:11], 0xa0000
	s_nop 0
	v_addc_co_u32_e32 v15, vcc, 0, v129, vcc
	s_waitcnt vmcnt(0) lgkmcnt(0)
	v_lshlrev_b32_e32 v28, 16, v8
	v_and_b32_e32 v29, 0xffff0000, v8
	v_lshlrev_b32_e32 v8, 16, v9
	v_and_b32_e32 v9, 0xffff0000, v9
	v_lshlrev_b32_e32 v30, 16, v10
	v_and_b32_e32 v31, 0xffff0000, v10
	v_lshlrev_b32_e32 v10, 16, v11
	v_and_b32_e32 v11, 0xffff0000, v11
	v_pk_mul_f32 v[28:29], v[60:61], v[28:29]
	v_pk_mul_f32 v[32:33], v[62:63], v[8:9]
	v_pk_mul_f32 v[30:31], v[56:57], v[30:31]
	v_pk_mul_f32 v[34:35], v[58:59], v[10:11]
	v_cvt_pk_bf16_f32 v8, v28, v29
	v_cvt_pk_bf16_f32 v9, v32, v33
	v_cvt_pk_bf16_f32 v10, v30, v31
	v_cvt_pk_bf16_f32 v11, v34, v35
	global_store_dwordx4 v[14:15], v[8:11], off
	global_load_dwordx4 v[8:11], v[12:13], off offset:1024 nt
	v_lshl_add_u64 v[14:15], v[128:129], 0, s[10:11]
	s_mov_b32 s10, 0xb0000
	s_waitcnt vmcnt(0) lgkmcnt(0)
	v_lshlrev_b32_e32 v28, 16, v8
	v_and_b32_e32 v29, 0xffff0000, v8
	v_lshlrev_b32_e32 v8, 16, v9
	v_and_b32_e32 v9, 0xffff0000, v9
	v_lshlrev_b32_e32 v30, 16, v10
	v_and_b32_e32 v31, 0xffff0000, v10
	v_lshlrev_b32_e32 v10, 16, v11
	v_and_b32_e32 v11, 0xffff0000, v11
	v_pk_mul_f32 v[28:29], v[36:37], v[28:29]
	v_pk_mul_f32 v[32:33], v[38:39], v[8:9]
	v_pk_mul_f32 v[24:25], v[24:25], v[30:31]
	v_pk_mul_f32 v[26:27], v[26:27], v[10:11]
	v_cvt_pk_bf16_f32 v8, v28, v29
	v_cvt_pk_bf16_f32 v9, v32, v33
	v_cvt_pk_bf16_f32 v10, v24, v25
	v_cvt_pk_bf16_f32 v11, v26, v27
	global_store_dwordx4 v[14:15], v[8:11], off offset:256
	global_load_dwordx4 v[8:11], v[12:13], off offset:2048 nt
	v_add_co_u32_e32 v14, vcc, s10, v128
	s_mov_b64 s[10:11], 0xb0000
	s_nop 0
	v_addc_co_u32_e32 v15, vcc, 0, v129, vcc
	s_andn2_b64 vcc, exec, s[4:5]
	s_mov_b64 s[4:5], -1
	s_waitcnt vmcnt(0) lgkmcnt(0)
	v_lshlrev_b32_e32 v24, 16, v8
	v_and_b32_e32 v25, 0xffff0000, v8
	v_lshlrev_b32_e32 v8, 16, v9
	v_and_b32_e32 v9, 0xffff0000, v9
	v_lshlrev_b32_e32 v26, 16, v10
	v_and_b32_e32 v27, 0xffff0000, v10
	v_lshlrev_b32_e32 v10, 16, v11
	v_and_b32_e32 v11, 0xffff0000, v11
	v_pk_mul_f32 v[20:21], v[20:21], v[24:25]
	v_pk_mul_f32 v[22:23], v[22:23], v[8:9]
	v_pk_mul_f32 v[16:17], v[16:17], v[26:27]
	v_pk_mul_f32 v[18:19], v[18:19], v[10:11]
	v_cvt_pk_bf16_f32 v8, v20, v21
	v_cvt_pk_bf16_f32 v9, v22, v23
	v_cvt_pk_bf16_f32 v10, v16, v17
	v_cvt_pk_bf16_f32 v11, v18, v19
	global_store_dwordx4 v[14:15], v[8:11], off
	global_load_dwordx4 v[8:11], v[12:13], off offset:3072 nt
	v_lshl_add_u64 v[12:13], v[128:129], 0, s[10:11]
	s_waitcnt vmcnt(0) lgkmcnt(0)
	v_lshlrev_b32_e32 v14, 16, v8
	v_and_b32_e32 v15, 0xffff0000, v8
	v_lshlrev_b32_e32 v8, 16, v9
	v_and_b32_e32 v9, 0xffff0000, v9
	v_lshlrev_b32_e32 v16, 16, v10
	v_and_b32_e32 v17, 0xffff0000, v10
	v_lshlrev_b32_e32 v10, 16, v11
	v_and_b32_e32 v11, 0xffff0000, v11
	v_pk_mul_f32 v[4:5], v[4:5], v[14:15]
	v_pk_mul_f32 v[6:7], v[6:7], v[8:9]
	v_pk_mul_f32 v[8:9], v[0:1], v[16:17]
	v_pk_mul_f32 v[10:11], v[2:3], v[10:11]
	v_cvt_pk_bf16_f32 v0, v4, v5
	v_cvt_pk_bf16_f32 v1, v6, v7
	v_cvt_pk_bf16_f32 v2, v8, v9
	v_cvt_pk_bf16_f32 v3, v10, v11
	global_store_dwordx4 v[12:13], v[0:3], off offset:256
	s_cbranch_vccnz .LBB0_753
	s_and_b64 vcc, exec, s[0:1]
	s_cbranch_vccnz .LBB0_752
	s_barrier
	s_branch .LBB0_752
